# v30 + residual GEMM phases: pre-epilogue alignment barrier of waves 0-3 moved below the issue of the epilogue's first 14 global loads
# baseline (speedup 1.0000x reference)
; #define PG8_STAGE(bufoff, gbase, voff) do { _Pragma("unroll") for (int _i = 0; _i < 2; ++_i) \
;         __builtin_amdgcn_global_load_lds((const unsigned*)((const char*)(gbase) + (voff)[_i]), (LAS unsigned*)(lds + (bufoff) + ldsw + _i * 8192), 16, 0, 0); } while (0)
; #define PG8_LDA(dst, b, h) do { _Pragma("unroll") for (int m = 0; m < 4; ++m) _Pragma("unroll") for (int k = 0; k < 2; ++k) dst[m][k] = *(const LAS bf16x8*)(lds + PG8_SA(b, h) + aoff + m * 2048 + k * 1024); } while (0)
; #define PG8_LDB(dst, b, h) do { _Pragma("unroll") for (int n = 0; n < 2; ++n) _Pragma("unroll") for (int k = 0; k < 2; ++k) dst[n][k] = *(const LAS bf16x8*)(lds + PG8_SB(b, h) + boff + n * 2048 + k * 1024); } while (0)
; #define PG8_MMA(ai, bj, At, Bt) do { __builtin_amdgcn_s_setprio(1); _Pragma("unroll") for (int m = 0; m < 4; ++m) _Pragma("unroll") for (int n = 0; n < 2; ++n) _Pragma("unroll") for (int k = 0; k < 2; ++k) \
;         acc[ai][bj][m][n] = __builtin_amdgcn_mfma_f32_16x16x32_bf16(Bt[n][k], At[m][k], acc[ai][bj][m][n], 0, 0, 0); __builtin_amdgcn_s_setprio(0); } while (0)
; #define PG8_WAIT_V(n) asm volatile("s_waitcnt vmcnt(" #n ")" ::: "memory")
; #define PG8_WAIT_L(n) asm volatile("s_waitcnt lgkmcnt(" #n ")" ::: "memory")
; template <class Epi, class Sched, bool ALIGN_EPI = false, bool SP2 = false>
; __device__ __forceinline__ void gemm_phase(LAS unsigned char* lds, const Gemm g, const Sched& S, const Epi& E) {
;     ...
;         for (int t = 0; t < nt; t += 2) {
;             const bool last = (t == nt - 2);
;             const char* a1 = cA + (size_t)(t + 1) * kstep;
;             const char* a2 = last ? nA : cA + (size_t)(t + 2) * kstep; const char* b2 = last ? nB : cB + (size_t)(t + 2) * kstep;
;             const char* a3 = a2 + kstep; const char* b3 = b2 + kstep;
;             if (last && has_next) S.a_ready(nxt);
;             if constexpr (SP2) {
;             PG8_LDB(B0, 0, 0); PG8_LDB(B1, 0, 1); PG8_SCHED; PG8_LDA(At, 0, 0); PG8_STAGE(PG8_SA(1, 1), a1 + hstep, voffA);
;             PG8_WAIT_V(8); PG8_WAIT_L(0); PG8_BAR; PG8_MMA(0, 0, At, B0); PG8_MMA(0, 1, At, B1); PG8_BAR; PG8_SCHED;
;             PG8_LDA(At, 0, 1); PG8_STAGE(PG8_SB(0, 0), b2, voffB); PG8_STAGE(PG8_SB(0, 1), b2 + hstepB, voffB); PG8_STAGE(PG8_SA(0, 0), a2, voffA);
;             PG8_WAIT_V(8); PG8_WAIT_L(0); PG8_BAR; PG8_MMA(1, 0, At, B0); PG8_MMA(1, 1, At, B1); PG8_BAR; PG8_SCHED;
.LBB0_317:
	ds_read_b128 v[130:133], v196
	ds_read_b128 v[134:137], v196 offset:1024
	ds_read_b128 v[138:141], v196 offset:2048
	ds_read_b128 v[142:145], v196 offset:3072
	ds_read_b128 v[166:169], v197
	ds_read_b128 v[170:173], v197 offset:1024
	ds_read_b128 v[174:177], v197 offset:2048
	ds_read_b128 v[178:181], v197 offset:3072
	s_add_u32 s54, s16, 0x100
	s_addc_u32 s55, s17, 0
	s_cmpk_eq_i32 s13, 0x54
	s_cselect_b32 s59, s3, s55
	s_cselect_b32 s58, s2, s54
	s_cselect_b32 s57, s53, s12
	s_cselect_b32 s56, s52, s5
	v_lshl_add_u64 v[190:191], s[16:17], 0, v[158:159]
	s_add_i32 m0, s29, 0xc000
	ds_read_b128 v[182:185], v198
	ds_read_b128 v[186:189], v198 offset:1024
	ds_read_b128 v[202:205], v198 offset:2048
	ds_read_b128 v[206:209], v198 offset:3072
	ds_read_b128 v[210:213], v198 offset:4096
	ds_read_b128 v[214:217], v198 offset:5120
	ds_read_b128 v[218:221], v198 offset:6144
	ds_read_b128 v[222:225], v198 offset:7168
	global_load_lds_dwordx4 v[190:191], off
	v_lshl_add_u64 v[190:191], s[16:17], 0, v[160:161]
	s_add_i32 m0, s29, 0xe000
	s_nop 0
	global_load_lds_dwordx4 v[190:191], off
	s_waitcnt vmcnt(8)
	s_waitcnt lgkmcnt(0)
	s_barrier
	s_waitcnt lgkmcnt(0)
	v_mfma_f32_16x16x32_bf16 v[126:129], v[130:133], v[182:185], v[126:129]
	v_mfma_f32_16x16x32_bf16 v[122:125], v[138:141], v[182:185], v[122:125]
	v_mfma_f32_16x16x32_bf16 v[110:113], v[130:133], v[202:205], v[110:113]
	v_mfma_f32_16x16x32_bf16 v[106:109], v[138:141], v[202:205], v[106:109]
	v_mfma_f32_16x16x32_bf16 v[94:97], v[130:133], v[210:213], v[94:97]
	v_mfma_f32_16x16x32_bf16 v[90:93], v[138:141], v[210:213], v[90:93]
	v_mfma_f32_16x16x32_bf16 v[78:81], v[130:133], v[218:221], v[78:81]
	v_mfma_f32_16x16x32_bf16 v[74:77], v[138:141], v[218:221], v[74:77]
	v_mfma_f32_16x16x32_bf16 v[126:129], v[134:137], v[186:189], v[126:129]
	v_mfma_f32_16x16x32_bf16 v[122:125], v[142:145], v[186:189], v[122:125]
	v_mfma_f32_16x16x32_bf16 v[110:113], v[134:137], v[206:209], v[110:113]
	v_mfma_f32_16x16x32_bf16 v[106:109], v[142:145], v[206:209], v[106:109]
	v_mfma_f32_16x16x32_bf16 v[94:97], v[134:137], v[214:217], v[94:97]
	v_mfma_f32_16x16x32_bf16 v[90:93], v[142:145], v[214:217], v[90:93]
	v_mfma_f32_16x16x32_bf16 v[78:81], v[134:137], v[222:225], v[78:81]
	v_mfma_f32_16x16x32_bf16 v[74:77], v[142:145], v[222:225], v[74:77]
	v_mfma_f32_16x16x32_bf16 v[118:121], v[166:169], v[182:185], v[118:121]
	v_mfma_f32_16x16x32_bf16 v[114:117], v[174:177], v[182:185], v[114:117]
	v_mfma_f32_16x16x32_bf16 v[102:105], v[166:169], v[202:205], v[102:105]
	v_mfma_f32_16x16x32_bf16 v[98:101], v[174:177], v[202:205], v[98:101]
	v_mfma_f32_16x16x32_bf16 v[86:89], v[166:169], v[210:213], v[86:89]
	v_mfma_f32_16x16x32_bf16 v[82:85], v[174:177], v[210:213], v[82:85]
	v_mfma_f32_16x16x32_bf16 v[70:73], v[166:169], v[218:221], v[70:73]
	v_mfma_f32_16x16x32_bf16 v[66:69], v[174:177], v[218:221], v[66:69]
	v_mfma_f32_16x16x32_bf16 v[118:121], v[170:173], v[186:189], v[118:121]
	v_mfma_f32_16x16x32_bf16 v[114:117], v[178:181], v[186:189], v[114:117]
	v_mfma_f32_16x16x32_bf16 v[102:105], v[170:173], v[206:209], v[102:105]
	v_mfma_f32_16x16x32_bf16 v[98:101], v[178:181], v[206:209], v[98:101]
	v_mfma_f32_16x16x32_bf16 v[86:89], v[170:173], v[214:217], v[86:89]
	v_mfma_f32_16x16x32_bf16 v[82:85], v[178:181], v[214:217], v[82:85]
	v_mfma_f32_16x16x32_bf16 v[70:73], v[170:173], v[222:225], v[70:73]
	v_mfma_f32_16x16x32_bf16 v[66:69], v[178:181], v[222:225], v[66:69]
	s_barrier
	s_add_i32 s14, s64, s28
	s_mov_b32 m0, s14
	ds_read_b128 v[182:185], v198 offset:16384
	ds_read_b128 v[186:189], v198 offset:17408
	ds_read_b128 v[202:205], v198 offset:18432
	ds_read_b128 v[206:209], v198 offset:19456
	ds_read_b128 v[210:213], v198 offset:20480
	ds_read_b128 v[214:217], v198 offset:21504
	ds_read_b128 v[218:221], v198 offset:22528
	ds_read_b128 v[222:225], v198 offset:23552
	global_load_lds_dwordx4 v148, s[56:57]
	s_add_i32 m0, s14, 0x2000
	s_add_u32 s14, s56, 0x58000
	s_addc_u32 s15, s57, 0
	s_add_i32 s16, s65, s28
	global_load_lds_dwordx4 v152, s[56:57]
	s_mov_b32 m0, s16
	s_nop 0
	global_load_lds_dwordx4 v148, s[14:15]
	s_add_i32 m0, s16, 0x2000
	s_nop 0
	global_load_lds_dwordx4 v152, s[14:15]
	s_mov_b32 m0, s29
	s_nop 0
	global_load_lds_dwordx4 v146, s[58:59]
	s_mov_b32 m0, s30
	s_nop 0
	global_load_lds_dwordx4 v150, s[58:59]
	s_waitcnt vmcnt(8)
	s_waitcnt lgkmcnt(0)
	s_barrier
	s_waitcnt lgkmcnt(0)
	v_mfma_f32_16x16x32_bf16 v[62:65], v[130:133], v[182:185], v[62:65]
	v_mfma_f32_16x16x32_bf16 v[58:61], v[138:141], v[182:185], v[58:61]
	v_mfma_f32_16x16x32_bf16 v[46:49], v[130:133], v[202:205], v[46:49]
	v_mfma_f32_16x16x32_bf16 v[42:45], v[138:141], v[202:205], v[42:45]
	v_mfma_f32_16x16x32_bf16 v[30:33], v[130:133], v[210:213], v[30:33]
	v_mfma_f32_16x16x32_bf16 v[26:29], v[138:141], v[210:213], v[26:29]
	v_mfma_f32_16x16x32_bf16 v[14:17], v[130:133], v[218:221], v[14:17]
	v_mfma_f32_16x16x32_bf16 v[10:13], v[138:141], v[218:221], v[10:13]
	v_mfma_f32_16x16x32_bf16 v[62:65], v[134:137], v[186:189], v[62:65]
	v_mfma_f32_16x16x32_bf16 v[58:61], v[142:145], v[186:189], v[58:61]
	v_mfma_f32_16x16x32_bf16 v[46:49], v[134:137], v[206:209], v[46:49]
	v_mfma_f32_16x16x32_bf16 v[42:45], v[142:145], v[206:209], v[42:45]
	v_mfma_f32_16x16x32_bf16 v[30:33], v[134:137], v[214:217], v[30:33]
	v_mfma_f32_16x16x32_bf16 v[26:29], v[142:145], v[214:217], v[26:29]
	v_mfma_f32_16x16x32_bf16 v[14:17], v[134:137], v[222:225], v[14:17]
	v_mfma_f32_16x16x32_bf16 v[10:13], v[142:145], v[222:225], v[10:13]
	v_mfma_f32_16x16x32_bf16 v[54:57], v[166:169], v[182:185], v[54:57]
	v_mfma_f32_16x16x32_bf16 v[50:53], v[174:177], v[182:185], v[50:53]
	v_mfma_f32_16x16x32_bf16 v[38:41], v[166:169], v[202:205], v[38:41]
	v_mfma_f32_16x16x32_bf16 v[34:37], v[174:177], v[202:205], v[34:37]
	v_mfma_f32_16x16x32_bf16 v[22:25], v[166:169], v[210:213], v[22:25]
	v_mfma_f32_16x16x32_bf16 v[18:21], v[174:177], v[210:213], v[18:21]
	v_mfma_f32_16x16x32_bf16 v[6:9], v[166:169], v[218:221], v[6:9]
	v_mfma_f32_16x16x32_bf16 v[2:5], v[174:177], v[218:221], v[2:5]
	v_mfma_f32_16x16x32_bf16 v[54:57], v[170:173], v[186:189], v[54:57]
	v_mfma_f32_16x16x32_bf16 v[50:53], v[178:181], v[186:189], v[50:53]
	v_mfma_f32_16x16x32_bf16 v[38:41], v[170:173], v[206:209], v[38:41]
	v_mfma_f32_16x16x32_bf16 v[34:37], v[178:181], v[206:209], v[34:37]
	v_mfma_f32_16x16x32_bf16 v[22:25], v[170:173], v[214:217], v[22:25]
	v_mfma_f32_16x16x32_bf16 v[18:21], v[178:181], v[214:217], v[18:21]
	v_mfma_f32_16x16x32_bf16 v[6:9], v[170:173], v[222:225], v[6:9]
	v_mfma_f32_16x16x32_bf16 v[2:5], v[178:181], v[222:225], v[2:5]
	s_barrier
; #define PG8_STAGE(bufoff, gbase, voff) do { _Pragma("unroll") for (int _i = 0; _i < 2; ++_i) \
;         __builtin_amdgcn_global_load_lds((const unsigned*)((const char*)(gbase) + (voff)[_i]), (LAS unsigned*)(lds + (bufoff) + ldsw + _i * 8192), 16, 0, 0); } while (0)
; #define PG8_LDA(dst, b, h) do { _Pragma("unroll") for (int m = 0; m < 4; ++m) _Pragma("unroll") for (int k = 0; k < 2; ++k) dst[m][k] = *(const LAS bf16x8*)(lds + PG8_SA(b, h) + aoff + m * 2048 + k * 1024); } while (0)
; #define PG8_LDB(dst, b, h) do { _Pragma("unroll") for (int n = 0; n < 2; ++n) _Pragma("unroll") for (int k = 0; k < 2; ++k) dst[n][k] = *(const LAS bf16x8*)(lds + PG8_SB(b, h) + boff + n * 2048 + k * 1024); } while (0)
; #define PG8_MMA(ai, bj, At, Bt) do { __builtin_amdgcn_s_setprio(1); _Pragma("unroll") for (int m = 0; m < 4; ++m) _Pragma("unroll") for (int n = 0; n < 2; ++n) _Pragma("unroll") for (int k = 0; k < 2; ++k) \
;         acc[ai][bj][m][n] = __builtin_amdgcn_mfma_f32_16x16x32_bf16(Bt[n][k], At[m][k], acc[ai][bj][m][n], 0, 0, 0); __builtin_amdgcn_s_setprio(0); } while (0)
; #define PG8_WAIT_V(n) asm volatile("s_waitcnt vmcnt(" #n ")" ::: "memory")
; #define PG8_WAIT_L(n) asm volatile("s_waitcnt lgkmcnt(" #n ")" ::: "memory")
; #define PG8_BAR __builtin_amdgcn_s_barrier()
; #define PG8_SCHED __builtin_amdgcn_sched_barrier(0)
; template <class Epi, class Sched, bool ALIGN_EPI = false, bool SP2 = false>
; __device__ __forceinline__ void gemm_phase(LAS unsigned char* lds, const Gemm g, const Sched& S, const Epi& E) {
;     ...
;             PG8_LDB(B0, 1, 0); PG8_LDB(B1, 1, 1); PG8_SCHED; PG8_LDA(At, 1, 0); PG8_STAGE(PG8_SA(0, 1), a2 + hstep, voffA);
;             PG8_WAIT_V(8); PG8_WAIT_L(0); PG8_BAR; PG8_MMA(0, 0, At, B0); PG8_MMA(0, 1, At, B1); PG8_BAR; PG8_SCHED;
;             PG8_LDA(At, 1, 1); PG8_STAGE(PG8_SB(1, 0), b3, voffB); PG8_STAGE(PG8_SB(1, 1), b3 + hstepB, voffB); PG8_STAGE(PG8_SA(1, 0), a3, voffA);
;             PG8_WAIT_V(8); PG8_WAIT_L(0); PG8_BAR; PG8_MMA(1, 0, At, B0); PG8_MMA(1, 1, At, B1); PG8_BAR; PG8_SCHED;
	s_add_i32 s16, 0, 0x18000
	s_add_i32 s17, 0, 0x1c000
	v_add_u32_e32 v142, s16, v1
	v_add_u32_e32 v154, s17, v1
	ds_read_b128 v[130:133], v142
	ds_read_b128 v[134:137], v142 offset:1024
	ds_read_b128 v[138:141], v142 offset:2048
	ds_read_b128 v[142:145], v142 offset:3072
	ds_read_b128 v[166:169], v154
	ds_read_b128 v[170:173], v154 offset:1024
	ds_read_b128 v[174:177], v154 offset:2048
	ds_read_b128 v[178:181], v154 offset:3072
	s_add_u32 s14, s58, 0x160000
	s_addc_u32 s15, s59, 0
	s_mov_b32 m0, s31
	ds_read_b128 v[182:185], v198 offset:32768
	ds_read_b128 v[186:189], v198 offset:33792
	ds_read_b128 v[202:205], v198 offset:34816
	ds_read_b128 v[206:209], v198 offset:35840
	ds_read_b128 v[210:213], v198 offset:36864
	ds_read_b128 v[214:217], v198 offset:37888
	ds_read_b128 v[218:221], v198 offset:38912
	ds_read_b128 v[222:225], v198 offset:39936
	global_load_lds_dwordx4 v146, s[14:15]
	s_mov_b32 m0, s33
	s_nop 0
	global_load_lds_dwordx4 v150, s[14:15]
	s_waitcnt vmcnt(8)
	s_waitcnt lgkmcnt(0)
	s_barrier
	s_waitcnt lgkmcnt(0)
	v_mfma_f32_16x16x32_bf16 v[126:129], v[130:133], v[182:185], v[126:129]
	v_mfma_f32_16x16x32_bf16 v[122:125], v[138:141], v[182:185], v[122:125]
	v_mfma_f32_16x16x32_bf16 v[110:113], v[130:133], v[202:205], v[110:113]
	v_mfma_f32_16x16x32_bf16 v[106:109], v[138:141], v[202:205], v[106:109]
	v_mfma_f32_16x16x32_bf16 v[94:97], v[130:133], v[210:213], v[94:97]
	v_mfma_f32_16x16x32_bf16 v[90:93], v[138:141], v[210:213], v[90:93]
	v_mfma_f32_16x16x32_bf16 v[78:81], v[130:133], v[218:221], v[78:81]
	v_mfma_f32_16x16x32_bf16 v[74:77], v[138:141], v[218:221], v[74:77]
	v_mfma_f32_16x16x32_bf16 v[126:129], v[134:137], v[186:189], v[126:129]
	v_mfma_f32_16x16x32_bf16 v[122:125], v[142:145], v[186:189], v[122:125]
	v_mfma_f32_16x16x32_bf16 v[110:113], v[134:137], v[206:209], v[110:113]
	v_mfma_f32_16x16x32_bf16 v[106:109], v[142:145], v[206:209], v[106:109]
	v_mfma_f32_16x16x32_bf16 v[94:97], v[134:137], v[214:217], v[94:97]
	v_mfma_f32_16x16x32_bf16 v[90:93], v[142:145], v[214:217], v[90:93]
	v_mfma_f32_16x16x32_bf16 v[78:81], v[134:137], v[222:225], v[78:81]
	v_mfma_f32_16x16x32_bf16 v[74:77], v[142:145], v[222:225], v[74:77]
	v_mfma_f32_16x16x32_bf16 v[118:121], v[166:169], v[182:185], v[118:121]
	v_mfma_f32_16x16x32_bf16 v[114:117], v[174:177], v[182:185], v[114:117]
	v_mfma_f32_16x16x32_bf16 v[102:105], v[166:169], v[202:205], v[102:105]
	v_mfma_f32_16x16x32_bf16 v[98:101], v[174:177], v[202:205], v[98:101]
	v_mfma_f32_16x16x32_bf16 v[86:89], v[166:169], v[210:213], v[86:89]
	v_mfma_f32_16x16x32_bf16 v[82:85], v[174:177], v[210:213], v[82:85]
	v_mfma_f32_16x16x32_bf16 v[70:73], v[166:169], v[218:221], v[70:73]
	v_mfma_f32_16x16x32_bf16 v[66:69], v[174:177], v[218:221], v[66:69]
	v_mfma_f32_16x16x32_bf16 v[118:121], v[170:173], v[186:189], v[118:121]
	v_mfma_f32_16x16x32_bf16 v[114:117], v[178:181], v[186:189], v[114:117]
	v_mfma_f32_16x16x32_bf16 v[102:105], v[170:173], v[206:209], v[102:105]
	v_mfma_f32_16x16x32_bf16 v[98:101], v[178:181], v[206:209], v[98:101]
	v_mfma_f32_16x16x32_bf16 v[86:89], v[170:173], v[214:217], v[86:89]
	v_mfma_f32_16x16x32_bf16 v[82:85], v[178:181], v[214:217], v[82:85]
	v_mfma_f32_16x16x32_bf16 v[70:73], v[170:173], v[222:225], v[70:73]
	v_mfma_f32_16x16x32_bf16 v[66:69], v[178:181], v[222:225], v[66:69]
	s_barrier
	s_add_u32 s98, s56, 0x80
	s_addc_u32 s99, s57, 0
	s_add_u32 s100, s58, 0x80
	s_addc_u32 s101, s59, 0
	s_add_i32 s14, s16, s28
	s_mov_b32 m0, s14
	ds_read_b128 v[182:185], v198 offset:49152
	ds_read_b128 v[186:189], v198 offset:50176
	ds_read_b128 v[202:205], v198 offset:51200
	ds_read_b128 v[206:209], v198 offset:52224
	ds_read_b128 v[210:213], v198 offset:53248
	ds_read_b128 v[214:217], v198 offset:54272
	ds_read_b128 v[218:221], v198 offset:55296
	ds_read_b128 v[222:225], v198 offset:56320
	global_load_lds_dwordx4 v148, s[98:99]
	s_add_i32 m0, s14, 0x2000
	s_add_u32 s14, s56, 0x58080
	s_addc_u32 s15, s57, 0
	s_add_i32 s16, s17, s28
	global_load_lds_dwordx4 v152, s[98:99]
	s_mov_b32 m0, s16
	s_nop 0
	global_load_lds_dwordx4 v148, s[14:15]
	s_add_i32 m0, s16, 0x2000
	s_nop 0
	global_load_lds_dwordx4 v152, s[14:15]
	s_mov_b32 m0, s61
	s_nop 0
	global_load_lds_dwordx4 v146, s[100:101]
	s_mov_b32 m0, s62
	s_nop 0
	global_load_lds_dwordx4 v150, s[100:101]
	s_waitcnt vmcnt(8)
	s_waitcnt lgkmcnt(0)
	s_barrier
	s_waitcnt lgkmcnt(0)
	v_mfma_f32_16x16x32_bf16 v[62:65], v[130:133], v[182:185], v[62:65]
	v_mfma_f32_16x16x32_bf16 v[58:61], v[138:141], v[182:185], v[58:61]
	v_mfma_f32_16x16x32_bf16 v[46:49], v[130:133], v[202:205], v[46:49]
	v_mfma_f32_16x16x32_bf16 v[42:45], v[138:141], v[202:205], v[42:45]
	v_mfma_f32_16x16x32_bf16 v[30:33], v[130:133], v[210:213], v[30:33]
	v_mfma_f32_16x16x32_bf16 v[26:29], v[138:141], v[210:213], v[26:29]
	v_mfma_f32_16x16x32_bf16 v[14:17], v[130:133], v[218:221], v[14:17]
	v_mfma_f32_16x16x32_bf16 v[10:13], v[138:141], v[218:221], v[10:13]
	v_mfma_f32_16x16x32_bf16 v[62:65], v[134:137], v[186:189], v[62:65]
	v_mfma_f32_16x16x32_bf16 v[58:61], v[142:145], v[186:189], v[58:61]
	v_mfma_f32_16x16x32_bf16 v[46:49], v[134:137], v[206:209], v[46:49]
	v_mfma_f32_16x16x32_bf16 v[42:45], v[142:145], v[206:209], v[42:45]
	v_mfma_f32_16x16x32_bf16 v[30:33], v[134:137], v[214:217], v[30:33]
	v_mfma_f32_16x16x32_bf16 v[26:29], v[142:145], v[214:217], v[26:29]
	v_mfma_f32_16x16x32_bf16 v[14:17], v[134:137], v[222:225], v[14:17]
	v_mfma_f32_16x16x32_bf16 v[10:13], v[142:145], v[222:225], v[10:13]
	v_mfma_f32_16x16x32_bf16 v[54:57], v[166:169], v[182:185], v[54:57]
	v_mfma_f32_16x16x32_bf16 v[50:53], v[174:177], v[182:185], v[50:53]
	v_mfma_f32_16x16x32_bf16 v[38:41], v[166:169], v[202:205], v[38:41]
	v_mfma_f32_16x16x32_bf16 v[34:37], v[174:177], v[202:205], v[34:37]
	v_mfma_f32_16x16x32_bf16 v[22:25], v[166:169], v[210:213], v[22:25]
	v_mfma_f32_16x16x32_bf16 v[18:21], v[174:177], v[210:213], v[18:21]
	v_mfma_f32_16x16x32_bf16 v[6:9], v[166:169], v[218:221], v[6:9]
	v_mfma_f32_16x16x32_bf16 v[2:5], v[174:177], v[218:221], v[2:5]
	v_mfma_f32_16x16x32_bf16 v[54:57], v[170:173], v[186:189], v[54:57]
	v_mfma_f32_16x16x32_bf16 v[50:53], v[178:181], v[186:189], v[50:53]
	v_mfma_f32_16x16x32_bf16 v[38:41], v[170:173], v[206:209], v[38:41]
	v_mfma_f32_16x16x32_bf16 v[34:37], v[178:181], v[206:209], v[34:37]
	v_mfma_f32_16x16x32_bf16 v[22:25], v[170:173], v[214:217], v[22:25]
	v_mfma_f32_16x16x32_bf16 v[18:21], v[178:181], v[214:217], v[18:21]
	v_mfma_f32_16x16x32_bf16 v[6:9], v[170:173], v[222:225], v[6:9]
	v_mfma_f32_16x16x32_bf16 v[2:5], v[178:181], v[222:225], v[2:5]
	s_barrier
; #define LAS __attribute__((address_space(3)))
; #define ERN_LOADX(q) do { _Pragma("unroll") for (int m = 0; m < 4; ++m) xb[(q) & 1][m] = *(const f32x4*)((const char*)xi + 4u * ERN_EOFF(q, m)); } while (0)
; #define ERN_LOADX(g) do { _Pragma("unroll") for (int bj_ = 0; bj_ < 2; ++bj_) _Pragma("unroll") for (int rh_ = 0; rh_ < 2; ++rh_) xb[(g) & 1][bj_][rh_] = *(const f32x4*)((const char*)xi + 4u * ERN_EOFF(g, bj_, rh_)); } while (0)
; #define PG8_BAR __builtin_amdgcn_s_barrier()
;     __device__ __forceinline__ void operator()(const f32x4 (&acc)[2][2][4][2], const Unit& u, int wr, int wc, int fr, int fq) const {
;         const int s = u.pm >> 5, lane = fq * 16 + fr, rr = lane >> 3, pc = lane & 7;
;         const float* __restrict__ xi = xin + (size_t)u.pm * BM * DM; float* __restrict__ xo = xout + (size_t)u.pm * BM * DM; bf16_t* __restrict__ ho = Hn + (size_t)u.pm * BM * DM;
;         LAS unsigned char* st = lds_epi + (wr * 4 + wc) * 2304;
;         LAS float* sst = (LAS float*)(lds_epi + 18432 + (wr * 4 + wc) * 512);
;         const int colr = u.pn * BM + wc * 64 + 4 * pc;
;         const unsigned eb = (unsigned)((wr * 64 + rr) * DM + colr);
;         f32x4 gv[2], gsn[2];
; #pragma unroll
;         for (int bj = 0; bj < 2; ++bj) { gv[bj] = *(const f32x4*)(gate + (size_t)s * MODW + colr + bj * 32) * (0.5f * GS2);
;             if (!PLAIN) gsn[bj] = *(const f32x4*)(gnext + colr + bj * 32) * (*(const f32x4*)(scnext + (size_t)s * MODW + colr + bj * 32) + 1.0f); else gsn[bj] = gv[bj]; }
;         const unsigned wr_off = (unsigned)(fr * 144 + 16 * fq), rd_off = (unsigned)(rr * 144 + pc * 16);
;         const bool odd = (rr & 1) != 0;
;         f32x4 xb[2][2][2];
;     ...
;         ERN_LOADX(0);
; template <class Epi, class Sched, bool ALIGN_EPI = false, bool SP2 = false>
; __device__ __forceinline__ void gemm_phase(LAS unsigned char* lds, const Gemm g, const Sched& S, const Epi& E) {
;     ...
;         if constexpr (ALIGN_EPI) { if (wr == 0) PG8_BAR; }
;         if constexpr (!Epi::AFTER_DRAIN) { E(acc, cur, wr, wc, fr, fq); S.done(cur); }
	s_add_i32 s13, s13, 2
	s_add_u32 s5, s5, 0x100
	s_addc_u32 s12, s12, 0
	s_cmpk_gt_u32 s13, 0x55
	s_mov_b64 s[16:17], s[54:55]
	s_cbranch_scc0 .LBB0_317
	s_setprio 0
	s_ashr_i32 s12, s4, 5
	s_ashr_i32 s5, s4, 31
	v_lshl_or_b32 v130, s0, 8, v192
	s_mul_i32 s14, s12, 0x12000
	s_mul_hi_i32 s0, s12, 0x12000
	s_add_u32 s12, s35, s14
	v_ashrrev_i32_e32 v131, 31, v130
	s_addc_u32 s13, s36, s0
	v_lshlrev_b64 v[132:133], 2, v[130:131]
	v_lshl_add_u64 v[134:135], s[12:13], 0, v[132:133]
	s_add_u32 s12, s37, s14
	s_addc_u32 s13, s60, s0
	v_lshl_add_u64 v[136:137], s[46:47], 0, v[132:133]
	v_lshl_add_u64 v[132:133], s[12:13], 0, v[132:133]
	s_lshl_b64 s[54:55], s[4:5], 21
	v_readlane_b32 s12, v253, 2
	v_readlane_b32 s13, v253, 3
	s_add_u32 s58, s12, s54
	v_add_u32_e32 v202, v130, v193
	s_addc_u32 s59, s13, s55
	v_lshlrev_b32_e32 v207, 2, v202
	global_load_dwordx4 v[170:173], v[136:137], off
	global_load_dwordx4 v[166:169], v[134:135], off
	global_load_dwordx4 v[174:177], v[134:135], off offset:128
	global_load_dwordx4 v[186:189], v[132:133], off
	global_load_dwordx4 v[208:211], v[132:133], off offset:128
	global_load_dwordx4 v[212:215], v207, s[58:59]
	v_add_u32_e32 v130, 0x10000, v207
	global_load_dwordx4 v[216:219], v130, s[58:59]
	global_load_dwordx4 v[220:223], v[136:137], off offset:128
	global_load_dwordx4 v[224:227], v207, s[58:59] offset:128
	v_add_u32_e32 v206, 0x10080, v207
	v_add_u32_e32 v130, 0x20000, v207
	global_load_dwordx4 v[228:231], v206, s[58:59]
	v_add_u32_e32 v154, 0x30000, v207
	v_add_u32_e32 v184, 0x20080, v207
	v_add_u32_e32 v182, 0x30080, v207
	global_load_dwordx4 v[142:145], v130, s[58:59]
	global_load_dwordx4 v[138:141], v154, s[58:59]
	global_load_dwordx4 v[134:137], v184, s[58:59]
	s_nop 0
	global_load_dwordx4 v[130:133], v182, s[58:59]
	s_and_b64 vcc, exec, s[50:51]
	s_cbranch_vccz .Lalign_320
	s_barrier
; #define LAS __attribute__((address_space(3)))
; __device__ __forceinline__ unsigned cvt_pk_bf16(float lo, float hi) { unsigned r; asm volatile("v_cvt_pk_bf16_f32 %0, %1, %2" : "=v"(r) : "v"(lo), "v"(hi)); return r; }
; #define ERN_EOFF(q, m) (eb + (unsigned)((((q) & 1) * HALF + (m) * 16) * DM + ERN_COL((q) >> 1)))
;     __device__ __forceinline__ void operator()(const f32x4 (&acc)[2][2][4][2], const Unit& u, int wr, int wc, int fr, int fq) const {
;     ...
;             float sq0 = 0.f, sq1 = 0.f; u32x2 hw[2][2];
; #pragma unroll
;             for (int bj = 0; bj < 2; ++bj) {
;                 *(LAS f32x4*)(st + wr_off) = acc[ai][bj][m][0]; *(LAS f32x4*)(st + wr_off + 64) = acc[ai][bj][m][1];
;                 const f32x4 a0 = *(const LAS f32x4*)(st + rd_off), a1 = *(const LAS f32x4*)(st + rd_off + 8 * 144);
;                 { const f32x4 xv = xb[g & 1][bj][0] + gv[bj] * a0; __builtin_nontemporal_store(xv, (f32x4*)((char*)xo + 4u * ERN_EOFF(g, bj, 0)));
;                   sq0 += (xv.x * xv.x + xv.y * xv.y) + (xv.z * xv.z + xv.w * xv.w);
;                   const f32x4 hv = xv * gsn[bj]; hw[bj][0].x = cvt_pk_bf16(hv.x, hv.y); hw[bj][0].y = cvt_pk_bf16(hv.z, hv.w); }
;                 { const f32x4 xv = xb[g & 1][bj][1] + gv[bj] * a1; __builtin_nontemporal_store(xv, (f32x4*)((char*)xo + 4u * ERN_EOFF(g, bj, 1)));
;                   sq1 += (xv.x * xv.x + xv.y * xv.y) + (xv.z * xv.z + xv.w * xv.w);
;                   const f32x4 hv = xv * gsn[bj]; hw[bj][1].x = cvt_pk_bf16(hv.x, hv.y); hw[bj][1].y = cvt_pk_bf16(hv.z, hv.w); }
;             }
;             if (!NOH && !PLAIN) {
; #pragma unroll
;                 for (int rh = 0; rh < 2; ++rh) { u32x2 rv; rv.x = __shfl_xor(hw[1][rh].x, 8); rv.y = __shfl_xor(hw[1][rh].y, 8);
;                     const unsigned e0 = ERN_EOFF(g, 0, rh);
;                     const unsigned ee = odd ? (e0 - DM + 32) : e0, eo2 = odd ? e0 : (e0 + DM + 32);
;                     *(u32x2*)((char*)ho + 2u * ee) = odd ? rv : hw[0][rh];
;                     *(u32x2*)((char*)ho + 2u * eo2) = odd ? hw[0][rh] : rv; }
;             }
;             if (!PLAIN) { sq0 += __shfl_xor(sq0, 1); sq0 += __shfl_xor(sq0, 2); sq0 += __shfl_xor(sq0, 4);
;             sq1 += __shfl_xor(sq1, 1); sq1 += __shfl_xor(sq1, 2); sq1 += __shfl_xor(sq1, 4); }
;             if (!PLAIN && pc == 0) { sst[g * 16 + rr] = sq0; sst[g * 16 + 8 + rr] = sq1; }
.Lalign_320:
	ds_write_b128 v200, v[126:129]
	ds_write_b128 v200, v[122:125] offset:64
	v_and_b32_e32 v127, 64, v199
	ds_read_b128 v[122:125], v201
	ds_read_b128 v[232:235], v201 offset:1152
	v_xor_b32_e32 v126, 8, v199
	v_add_u32_e32 v183, 64, v127
	v_cmp_lt_i32_e32 vcc, v126, v183
	v_add_u32_e32 v185, 0x4000, v202
	s_add_u32 s56, s90, s54
	v_cndmask_b32_e32 v126, v199, v126, vcc
	v_lshlrev_b32_e32 v203, 2, v126
	v_lshlrev_b32_e32 v236, 2, v185
	s_addc_u32 s57, s91, s55
	s_lshl_b64 s[12:13], s[4:5], 20
	s_add_u32 s54, s93, s12
	v_readlane_b32 s16, v253, 6
	v_readlane_b32 s17, v253, 7
	s_addc_u32 s55, s92, s13
	v_readlane_b32 s14, v253, 4
	v_readlane_b32 s15, v253, 5
	v_readlane_b32 s18, v253, 8
	v_readlane_b32 s19, v253, 9
	v_readlane_b32 s20, v253, 10
	v_readlane_b32 s21, v253, 11
	v_readlane_b32 s22, v253, 12
	v_readlane_b32 s23, v253, 13
	v_readlane_b32 s24, v253, 14
	v_readlane_b32 s25, v253, 15
	v_readlane_b32 s26, v253, 16
	v_readlane_b32 s27, v253, 17
	s_waitcnt vmcnt(0)
	v_pk_mul_f32 v[180:181], v[166:167], 0.5 op_sel_hi:[1,0]
	v_pk_mul_f32 v[178:179], v[168:169], 0.5 op_sel_hi:[1,0]
	v_pk_add_f32 v[126:127], v[188:189], 1.0 op_sel_hi:[1,0]
	v_pk_add_f32 v[128:129], v[186:187], 1.0 op_sel_hi:[1,0]
	v_pk_mul_f32 v[166:167], v[176:177], 0.5 op_sel_hi:[1,0]
	v_pk_mul_f32 v[168:169], v[174:175], 0.5 op_sel_hi:[1,0]
	v_pk_mul_f32 v[174:175], v[172:173], v[126:127]
	v_pk_mul_f32 v[176:177], v[170:171], v[128:129]
	s_waitcnt lgkmcnt(1)
	v_pk_fma_f32 v[126:127], v[180:181], v[122:123], v[212:213]
	s_waitcnt lgkmcnt(0)
	v_pk_fma_f32 v[122:123], v[180:181], v[232:233], v[216:217]
	v_pk_fma_f32 v[128:129], v[178:179], v[124:125], v[214:215]
	v_pk_fma_f32 v[124:125], v[178:179], v[234:235], v[218:219]
	v_pk_mul_f32 v[186:187], v[176:177], v[122:123]
	global_store_dwordx4 v207, v[126:129], s[56:57] nt
	v_pk_mul_f32 v[170:171], v[174:175], v[128:129]
	v_pk_mul_f32 v[172:173], v[176:177], v[126:127]
	v_pk_mul_f32 v[204:205], v[174:175], v[124:125]
	v_cvt_pk_bf16_f32 v188, v172, v173
	v_cvt_pk_bf16_f32 v189, v170, v171
	global_store_dwordx4 v236, v[122:125], s[56:57] nt
	v_cvt_pk_bf16_f32 v186, v186, v187
	v_cvt_pk_bf16_f32 v187, v204, v205
	ds_write_b128 v200, v[118:121]
	ds_write_b128 v200, v[114:117] offset:64
	ds_read_b128 v[114:117], v201
	v_pk_add_f32 v[190:191], v[210:211], 1.0 op_sel_hi:[1,0]
	v_pk_add_f32 v[118:119], v[208:209], 1.0 op_sel_hi:[1,0]
	ds_read_b128 v[208:211], v201 offset:1152
	v_pk_mul_f32 v[170:171], v[222:223], v[190:191]
	v_pk_mul_f32 v[172:173], v[220:221], v[118:119]
	s_waitcnt lgkmcnt(1)
	v_pk_fma_f32 v[120:121], v[166:167], v[116:117], v[226:227]
	v_pk_fma_f32 v[118:119], v[168:169], v[114:115], v[224:225]
	v_pk_mul_f32 v[190:191], v[170:171], v[120:121]
	v_pk_mul_f32 v[204:205], v[172:173], v[118:119]
	global_store_dwordx4 v207, v[118:121], s[56:57] offset:128 nt
	v_cvt_pk_bf16_f32 v204, v204, v205
	v_cvt_pk_bf16_f32 v191, v190, v191
	ds_bpermute_b32 v190, v203, v204
	ds_bpermute_b32 v191, v203, v191
	s_waitcnt lgkmcnt(2)
	v_pk_fma_f32 v[116:117], v[166:167], v[210:211], v[230:231]
	v_pk_fma_f32 v[114:115], v[168:169], v[208:209], v[228:229]
	global_store_dwordx4 v206, v[114:117], s[56:57] nt
	v_pk_mul_f32 v[204:205], v[172:173], v[114:115]
	v_lshlrev_b32_e32 v206, 1, v202
	v_pk_mul_f32 v[208:209], v[170:171], v[116:117]
	v_cvt_pk_bf16_f32 v204, v204, v205
	s_nop 0
	v_cvt_pk_bf16_f32 v205, v208, v209
	s_waitcnt lgkmcnt(0)
	v_add_u32_e32 v250, 0xfffff040, v206
	v_cndmask_b32_e64 v250, v206, v250, s[40:41]
	v_cndmask_b32_e64 v248, v188, v190, s[40:41]
	v_cndmask_b32_e64 v249, v189, v191, s[40:41]
	global_store_dwordx2 v250, v[248:249], s[54:55]
	v_cndmask_b32_e64 v246, v190, v188, s[40:41]
	v_cndmask_b32_e64 v247, v191, v189, s[40:41]
	s_waitcnt lgkmcnt(1)
	v_add_u32_e32 v190, 0x1040, v206
	v_cndmask_b32_e64 v190, v206, v190, s[38:39]
	global_store_dwordx2 v190, v[246:247], s[54:55]
	ds_bpermute_b32 v188, v203, v204
	ds_bpermute_b32 v189, v203, v205
	v_lshlrev_b32_e32 v190, 1, v185
	s_waitcnt lgkmcnt(0)
	v_add_u32_e32 v250, 0xfffff040, v190
	v_cndmask_b32_e64 v250, v190, v250, s[40:41]
	v_cndmask_b32_e64 v248, v186, v188, s[40:41]
	v_cndmask_b32_e64 v249, v187, v189, s[40:41]
	global_store_dwordx2 v250, v[248:249], s[54:55]
	v_cndmask_b32_e64 v246, v188, v186, s[40:41]
	v_cndmask_b32_e64 v247, v189, v187, s[40:41]
	v_mul_f32_e32 v119, v119, v119
	v_mul_f32_e32 v127, v127, v127
	v_mul_f32_e32 v129, v129, v129
	v_fmac_f32_e32 v119, v118, v118
	v_mul_f32_e32 v118, v121, v121
	v_fmac_f32_e32 v129, v128, v128
	v_fmac_f32_e32 v118, v120, v120
	v_mul_f32_e32 v115, v115, v115
	v_fmac_f32_e32 v127, v126, v126
	v_add_f32_e32 v118, v119, v118
	v_fmac_f32_e32 v115, v114, v114
	v_mul_f32_e32 v114, v117, v117
	v_add_f32_e32 v117, v127, v129
	v_add_f32_e32 v117, v117, v118
	v_xor_b32_e32 v118, 1, v199
	v_cmp_lt_i32_e32 vcc, v118, v183
	v_mul_f32_e32 v123, v123, v123
	v_mul_f32_e32 v125, v125, v125
	v_cndmask_b32_e32 v118, v199, v118, vcc
	v_lshlrev_b32_e32 v204, 2, v118
	ds_bpermute_b32 v118, v204, v117
	v_fmac_f32_e32 v114, v116, v116
	v_fmac_f32_e32 v125, v124, v124
	v_fmac_f32_e32 v123, v122, v122
	v_add_f32_e32 v114, v115, v114
	s_waitcnt lgkmcnt(0)
	v_add_f32_e32 v116, v117, v118
	v_xor_b32_e32 v117, 2, v199
	v_cmp_lt_i32_e32 vcc, v117, v183
	v_add_f32_e32 v115, v123, v125
	v_add_f32_e32 v115, v115, v114
	v_cndmask_b32_e32 v117, v199, v117, vcc
	v_lshlrev_b32_e32 v205, 2, v117
	ds_bpermute_b32 v117, v205, v116
	ds_bpermute_b32 v118, v204, v115
	s_waitcnt lgkmcnt(1)
	v_add_f32_e32 v114, v116, v117
	s_waitcnt lgkmcnt(0)
	v_add_f32_e32 v117, v115, v118
	ds_bpermute_b32 v118, v205, v117
	v_xor_b32_e32 v116, 4, v199
	v_cmp_lt_i32_e32 vcc, v116, v183
	s_nop 1
	v_cndmask_b32_e32 v115, v199, v116, vcc
	v_lshlrev_b32_e32 v206, 2, v115
	s_waitcnt lgkmcnt(0)
	v_add_f32_e32 v116, v117, v118
	ds_bpermute_b32 v115, v206, v114
	ds_bpermute_b32 v117, v206, v116
	v_add_u32_e32 v118, 0x1040, v190
	v_cndmask_b32_e64 v118, v190, v118, s[38:39]
	global_store_dwordx2 v118, v[246:247], s[54:55]
	s_and_saveexec_b64 s[16:17], s[42:43]
	s_cbranch_execz .LBB0_330
	s_waitcnt lgkmcnt(1)
	v_add_f32_e32 v114, v114, v115
	s_waitcnt lgkmcnt(0)
	v_add_f32_e32 v115, v116, v117
	ds_write2_b32 v194, v114, v115 offset1:8

; #define PG8_STAGE(bufoff, gbase, voff) do { _Pragma("unroll") for (int _i = 0; _i < 2; ++_i) \
;         __builtin_amdgcn_global_load_lds((const unsigned*)((const char*)(gbase) + (voff)[_i]), (LAS unsigned*)(lds + (bufoff) + ldsw + _i * 8192), 16, 0, 0); } while (0)
; #define PG8_LDA(dst, b, h) do { _Pragma("unroll") for (int m = 0; m < 4; ++m) _Pragma("unroll") for (int k = 0; k < 2; ++k) dst[m][k] = *(const LAS bf16x8*)(lds + PG8_SA(b, h) + aoff + m * 2048 + k * 1024); } while (0)
; #define PG8_LDB(dst, b, h) do { _Pragma("unroll") for (int n = 0; n < 2; ++n) _Pragma("unroll") for (int k = 0; k < 2; ++k) dst[n][k] = *(const LAS bf16x8*)(lds + PG8_SB(b, h) + boff + n * 2048 + k * 1024); } while (0)
; template <class Epi, class Sched, bool ALIGN_EPI = false, bool SP2 = false>
; __device__ __forceinline__ void gemm_phase(LAS unsigned char* lds, const Gemm g, const Sched& S, const Epi& E) {
;     ...
;         for (int t = 0; t < nt; t += 2) {
;             const bool last = (t == nt - 2);
;             const char* a1 = cA + (size_t)(t + 1) * kstep;
;             const char* a2 = last ? nA : cA + (size_t)(t + 2) * kstep; const char* b2 = last ? nB : cB + (size_t)(t + 2) * kstep;
;             const char* a3 = a2 + kstep; const char* b3 = b2 + kstep;
;             if (last && has_next) S.a_ready(nxt);
;             if constexpr (SP2) {
;             PG8_LDB(B0, 0, 0); PG8_LDB(B1, 0, 1); PG8_SCHED; PG8_LDA(At, 0, 0); PG8_STAGE(PG8_SA(1, 1), a1 + hstep, voffA);
;             PG8_WAIT_V(8); PG8_WAIT_L(0); PG8_BAR; PG8_MMA(0, 0, At, B0); PG8_MMA(0, 1, At, B1); PG8_BAR; PG8_SCHED;
;             PG8_LDA(At, 0, 1); PG8_STAGE(PG8_SB(0, 0), b2, voffB); PG8_STAGE(PG8_SB(0, 1), b2 + hstepB, voffB); PG8_STAGE(PG8_SA(0, 0), a2, voffA);
;             PG8_WAIT_V(8); PG8_WAIT_L(0); PG8_BAR; PG8_MMA(1, 0, At, B0); PG8_MMA(1, 1, At, B1); PG8_BAR; PG8_SCHED;
;             PG8_LDB(B0, 1, 0); PG8_LDB(B1, 1, 1); PG8_SCHED; PG8_LDA(At, 1, 0); PG8_STAGE(PG8_SA(0, 1), a2 + hstep, voffA);
;             PG8_WAIT_V(8); PG8_WAIT_L(0); PG8_BAR; PG8_MMA(0, 0, At, B0); PG8_MMA(0, 1, At, B1); PG8_BAR; PG8_SCHED;
;             PG8_LDA(At, 1, 1); PG8_STAGE(PG8_SB(1, 0), b3, voffB); PG8_STAGE(PG8_SB(1, 1), b3 + hstepB, voffB); PG8_STAGE(PG8_SA(1, 0), a3, voffA);
;             PG8_WAIT_V(8); PG8_WAIT_L(0); PG8_BAR; PG8_MMA(1, 0, At, B0); PG8_MMA(1, 1, At, B1); PG8_BAR; PG8_SCHED;
.LBB0_1250:
	ds_read_b128 v[50:53], v196
	ds_read_b128 v[54:57], v196 offset:1024
	ds_read_b128 v[138:141], v196 offset:2048
	ds_read_b128 v[142:145], v196 offset:3072
	ds_read_b128 v[146:149], v197
	ds_read_b128 v[150:153], v197 offset:1024
	ds_read_b128 v[174:177], v197 offset:2048
	ds_read_b128 v[178:181], v197 offset:3072
	s_add_u32 s48, s16, 0xfff80080
	s_addc_u32 s49, s17, -1
	s_cmp_eq_u32 s47, 28
	s_cselect_b32 s51, s0, s49
	s_cselect_b32 s50, s3, s48
	s_cselect_b32 s49, s15, s25
	s_cselect_b32 s48, s19, s24
	s_add_i32 m0, s29, 0xc000
	ds_read_b128 v[182:185], v198
	ds_read_b128 v[186:189], v198 offset:1024
	ds_read_b128 v[202:205], v198 offset:2048
	ds_read_b128 v[206:209], v198 offset:3072
	ds_read_b128 v[210:213], v198 offset:4096
	ds_read_b128 v[214:217], v198 offset:5120
	ds_read_b128 v[218:221], v198 offset:6144
	ds_read_b128 v[222:225], v198 offset:7168
	global_load_lds_dwordx4 v166, s[16:17]
	s_add_i32 m0, s29, 0xe000
	s_nop 0
	global_load_lds_dwordx4 v168, s[16:17]
	s_waitcnt vmcnt(8)
	s_waitcnt lgkmcnt(0)
	s_barrier
	s_waitcnt lgkmcnt(0)
	v_mfma_f32_16x16x32_bf16 v[134:137], v[50:53], v[182:185], v[134:137]
	v_mfma_f32_16x16x32_bf16 v[130:133], v[138:141], v[182:185], v[130:133]
	v_mfma_f32_16x16x32_bf16 v[118:121], v[50:53], v[202:205], v[118:121]
	v_mfma_f32_16x16x32_bf16 v[114:117], v[138:141], v[202:205], v[114:117]
	v_mfma_f32_16x16x32_bf16 v[102:105], v[50:53], v[210:213], v[102:105]
	v_mfma_f32_16x16x32_bf16 v[98:101], v[138:141], v[210:213], v[98:101]
	v_mfma_f32_16x16x32_bf16 v[86:89], v[50:53], v[218:221], v[86:89]
	v_mfma_f32_16x16x32_bf16 v[82:85], v[138:141], v[218:221], v[82:85]
	v_mfma_f32_16x16x32_bf16 v[134:137], v[54:57], v[186:189], v[134:137]
	v_mfma_f32_16x16x32_bf16 v[130:133], v[142:145], v[186:189], v[130:133]
	v_mfma_f32_16x16x32_bf16 v[118:121], v[54:57], v[206:209], v[118:121]
	v_mfma_f32_16x16x32_bf16 v[114:117], v[142:145], v[206:209], v[114:117]
	v_mfma_f32_16x16x32_bf16 v[102:105], v[54:57], v[214:217], v[102:105]
	v_mfma_f32_16x16x32_bf16 v[98:101], v[142:145], v[214:217], v[98:101]
	v_mfma_f32_16x16x32_bf16 v[86:89], v[54:57], v[222:225], v[86:89]
	v_mfma_f32_16x16x32_bf16 v[82:85], v[142:145], v[222:225], v[82:85]
	v_mfma_f32_16x16x32_bf16 v[126:129], v[146:149], v[182:185], v[126:129]
	v_mfma_f32_16x16x32_bf16 v[122:125], v[174:177], v[182:185], v[122:125]
	v_mfma_f32_16x16x32_bf16 v[110:113], v[146:149], v[202:205], v[110:113]
	v_mfma_f32_16x16x32_bf16 v[106:109], v[174:177], v[202:205], v[106:109]
	v_mfma_f32_16x16x32_bf16 v[94:97], v[146:149], v[210:213], v[94:97]
	v_mfma_f32_16x16x32_bf16 v[90:93], v[174:177], v[210:213], v[90:93]
	v_mfma_f32_16x16x32_bf16 v[78:81], v[146:149], v[218:221], v[78:81]
	v_mfma_f32_16x16x32_bf16 v[74:77], v[174:177], v[218:221], v[74:77]
	v_mfma_f32_16x16x32_bf16 v[126:129], v[150:153], v[186:189], v[126:129]
	v_mfma_f32_16x16x32_bf16 v[122:125], v[178:181], v[186:189], v[122:125]
	v_mfma_f32_16x16x32_bf16 v[110:113], v[150:153], v[206:209], v[110:113]
	v_mfma_f32_16x16x32_bf16 v[106:109], v[178:181], v[206:209], v[106:109]
	v_mfma_f32_16x16x32_bf16 v[94:97], v[150:153], v[214:217], v[94:97]
	v_mfma_f32_16x16x32_bf16 v[90:93], v[178:181], v[214:217], v[90:93]
	v_mfma_f32_16x16x32_bf16 v[78:81], v[150:153], v[222:225], v[78:81]
	v_mfma_f32_16x16x32_bf16 v[74:77], v[178:181], v[222:225], v[74:77]
	s_barrier
	s_add_i32 s58, s56, s28
	s_mov_b32 m0, s58
	ds_read_b128 v[182:185], v198 offset:16384
	ds_read_b128 v[186:189], v198 offset:17408
	ds_read_b128 v[202:205], v198 offset:18432
	ds_read_b128 v[206:209], v198 offset:19456
	ds_read_b128 v[210:213], v198 offset:20480
	ds_read_b128 v[214:217], v198 offset:21504
	ds_read_b128 v[218:221], v198 offset:22528
	ds_read_b128 v[222:225], v198 offset:23552
	global_load_lds_dwordx4 v156, s[48:49]
	s_add_i32 m0, s58, 0x2000
	s_add_u32 s58, s48, 0x20000
	v_lshl_add_u64 v[226:227], s[48:49], 0, v[160:161]
	s_addc_u32 s59, s49, 0
	s_add_i32 s60, s57, s28
	global_load_lds_dwordx4 v160, s[48:49]
	s_mov_b32 m0, s60
	v_lshl_add_u64 v[230:231], s[50:51], 0, v[158:159]
	global_load_lds_dwordx4 v156, s[58:59]
	s_add_i32 m0, s60, 0x2000
	s_nop 0
	global_load_lds_dwordx4 v160, s[58:59]
	v_lshl_add_u64 v[228:229], s[50:51], 0, v[154:155]
	s_mov_b32 m0, s29
	s_nop 0
	global_load_lds_dwordx4 v154, s[50:51]
	s_mov_b32 m0, s30
	s_nop 0
	global_load_lds_dwordx4 v158, s[50:51]
	s_waitcnt vmcnt(8)
	s_waitcnt lgkmcnt(0)
	s_barrier
	s_waitcnt lgkmcnt(0)
	v_mfma_f32_16x16x32_bf16 v[70:73], v[50:53], v[182:185], v[70:73]
	v_mfma_f32_16x16x32_bf16 v[66:69], v[138:141], v[182:185], v[66:69]
	v_mfma_f32_16x16x32_bf16 v[46:49], v[50:53], v[202:205], v[46:49]
	v_mfma_f32_16x16x32_bf16 v[42:45], v[138:141], v[202:205], v[42:45]
	v_mfma_f32_16x16x32_bf16 v[30:33], v[50:53], v[210:213], v[30:33]
	v_mfma_f32_16x16x32_bf16 v[26:29], v[138:141], v[210:213], v[26:29]
	v_mfma_f32_16x16x32_bf16 v[14:17], v[50:53], v[218:221], v[14:17]
	v_mfma_f32_16x16x32_bf16 v[10:13], v[138:141], v[218:221], v[10:13]
	v_mfma_f32_16x16x32_bf16 v[70:73], v[54:57], v[186:189], v[70:73]
	v_mfma_f32_16x16x32_bf16 v[66:69], v[142:145], v[186:189], v[66:69]
	v_mfma_f32_16x16x32_bf16 v[46:49], v[54:57], v[206:209], v[46:49]
	v_mfma_f32_16x16x32_bf16 v[42:45], v[142:145], v[206:209], v[42:45]
	v_mfma_f32_16x16x32_bf16 v[30:33], v[54:57], v[214:217], v[30:33]
	v_mfma_f32_16x16x32_bf16 v[26:29], v[142:145], v[214:217], v[26:29]
	v_mfma_f32_16x16x32_bf16 v[14:17], v[54:57], v[222:225], v[14:17]
	v_mfma_f32_16x16x32_bf16 v[10:13], v[142:145], v[222:225], v[10:13]
	v_mfma_f32_16x16x32_bf16 v[38:41], v[146:149], v[202:205], v[38:41]
	v_mfma_f32_16x16x32_bf16 v[34:37], v[174:177], v[202:205], v[34:37]
	v_mfma_f32_16x16x32_bf16 v[22:25], v[146:149], v[210:213], v[22:25]
	v_mfma_f32_16x16x32_bf16 v[18:21], v[174:177], v[210:213], v[18:21]
	v_mfma_f32_16x16x32_bf16 v[6:9], v[146:149], v[218:221], v[6:9]
	v_mfma_f32_16x16x32_bf16 v[2:5], v[174:177], v[218:221], v[2:5]
	v_mfma_f32_16x16x32_bf16 v[50:53], v[146:149], v[182:185], v[62:65]
	v_mfma_f32_16x16x32_bf16 v[54:57], v[174:177], v[182:185], v[58:61]
	v_mfma_f32_16x16x32_bf16 v[38:41], v[150:153], v[206:209], v[38:41]
	v_mfma_f32_16x16x32_bf16 v[34:37], v[178:181], v[206:209], v[34:37]
	v_mfma_f32_16x16x32_bf16 v[22:25], v[150:153], v[214:217], v[22:25]
	v_mfma_f32_16x16x32_bf16 v[18:21], v[178:181], v[214:217], v[18:21]
	v_mfma_f32_16x16x32_bf16 v[6:9], v[150:153], v[222:225], v[6:9]
	v_mfma_f32_16x16x32_bf16 v[2:5], v[178:181], v[222:225], v[2:5]
	v_mfma_f32_16x16x32_bf16 v[50:53], v[150:153], v[186:189], v[50:53]
	v_mfma_f32_16x16x32_bf16 v[54:57], v[178:181], v[186:189], v[54:57]
	s_barrier
; #define PG8_STAGE(bufoff, gbase, voff) do { _Pragma("unroll") for (int _i = 0; _i < 2; ++_i) \
;         __builtin_amdgcn_global_load_lds((const unsigned*)((const char*)(gbase) + (voff)[_i]), (LAS unsigned*)(lds + (bufoff) + ldsw + _i * 8192), 16, 0, 0); } while (0)
; #define PG8_LDA(dst, b, h) do { _Pragma("unroll") for (int m = 0; m < 4; ++m) _Pragma("unroll") for (int k = 0; k < 2; ++k) dst[m][k] = *(const LAS bf16x8*)(lds + PG8_SA(b, h) + aoff + m * 2048 + k * 1024); } while (0)
; #define PG8_LDB(dst, b, h) do { _Pragma("unroll") for (int n = 0; n < 2; ++n) _Pragma("unroll") for (int k = 0; k < 2; ++k) dst[n][k] = *(const LAS bf16x8*)(lds + PG8_SB(b, h) + boff + n * 2048 + k * 1024); } while (0)
; template <class Epi, class Sched, bool ALIGN_EPI = false, bool SP2 = false>
; __device__ __forceinline__ void gemm_phase(LAS unsigned char* lds, const Gemm g, const Sched& S, const Epi& E) {
;     ...
;         for (int t = 0; t < nt; t += 2) {
;             const bool last = (t == nt - 2);
;             const char* a1 = cA + (size_t)(t + 1) * kstep;
;             const char* a2 = last ? nA : cA + (size_t)(t + 2) * kstep; const char* b2 = last ? nB : cB + (size_t)(t + 2) * kstep;
;             const char* a3 = a2 + kstep; const char* b3 = b2 + kstep;
;             if (last && has_next) S.a_ready(nxt);
;             if constexpr (SP2) {
;             PG8_LDB(B0, 0, 0); PG8_LDB(B1, 0, 1); PG8_SCHED; PG8_LDA(At, 0, 0); PG8_STAGE(PG8_SA(1, 1), a1 + hstep, voffA);
;             PG8_WAIT_V(8); PG8_WAIT_L(0); PG8_BAR; PG8_MMA(0, 0, At, B0); PG8_MMA(0, 1, At, B1); PG8_BAR; PG8_SCHED;
;             PG8_LDA(At, 0, 1); PG8_STAGE(PG8_SB(0, 0), b2, voffB); PG8_STAGE(PG8_SB(0, 1), b2 + hstepB, voffB); PG8_STAGE(PG8_SA(0, 0), a2, voffA);
;             PG8_WAIT_V(8); PG8_WAIT_L(0); PG8_BAR; PG8_MMA(1, 0, At, B0); PG8_MMA(1, 1, At, B1); PG8_BAR; PG8_SCHED;
;             PG8_LDB(B0, 1, 0); PG8_LDB(B1, 1, 1); PG8_SCHED; PG8_LDA(At, 1, 0); PG8_STAGE(PG8_SA(0, 1), a2 + hstep, voffA);
;             PG8_WAIT_V(8); PG8_WAIT_L(0); PG8_BAR; PG8_MMA(0, 0, At, B0); PG8_MMA(0, 1, At, B1); PG8_BAR; PG8_SCHED;
;             PG8_LDA(At, 1, 1); PG8_STAGE(PG8_SB(1, 0), b3, voffB); PG8_STAGE(PG8_SB(1, 1), b3 + hstepB, voffB); PG8_STAGE(PG8_SA(1, 0), a3, voffA);
;             PG8_WAIT_V(8); PG8_WAIT_L(0); PG8_BAR; PG8_MMA(1, 0, At, B0); PG8_MMA(1, 1, At, B1); PG8_BAR; PG8_SCHED;
	s_add_i32 s58, 0, 0x18000
	s_add_i32 s59, 0, 0x1c000
	v_add_u32_e32 v142, s58, v1
	v_add_u32_e32 v162, s59, v1
	ds_read_b128 v[58:61], v142
	ds_read_b128 v[62:65], v142 offset:1024
	ds_read_b128 v[138:141], v142 offset:2048
	ds_read_b128 v[142:145], v142 offset:3072
	ds_read_b128 v[146:149], v162
	ds_read_b128 v[150:153], v162 offset:1024
	ds_read_b128 v[174:177], v162 offset:2048
	ds_read_b128 v[178:181], v162 offset:3072
	s_add_u32 s50, s50, 0x80000
	s_addc_u32 s51, s51, 0
	s_mov_b32 m0, s31
	ds_read_b128 v[182:185], v198 offset:32768
	ds_read_b128 v[186:189], v198 offset:33792
	ds_read_b128 v[202:205], v198 offset:34816
	ds_read_b128 v[206:209], v198 offset:35840
	ds_read_b128 v[210:213], v198 offset:36864
	ds_read_b128 v[214:217], v198 offset:37888
	ds_read_b128 v[218:221], v198 offset:38912
	ds_read_b128 v[222:225], v198 offset:39936
	global_load_lds_dwordx4 v154, s[50:51]
	s_mov_b32 m0, s33
	s_nop 0
	global_load_lds_dwordx4 v158, s[50:51]
	s_waitcnt vmcnt(8)
	s_waitcnt lgkmcnt(0)
	s_barrier
	s_waitcnt lgkmcnt(0)
	v_mfma_f32_16x16x32_bf16 v[134:137], v[58:61], v[182:185], v[134:137]
	v_mfma_f32_16x16x32_bf16 v[130:133], v[138:141], v[182:185], v[130:133]
	v_mfma_f32_16x16x32_bf16 v[118:121], v[58:61], v[202:205], v[118:121]
	v_mfma_f32_16x16x32_bf16 v[114:117], v[138:141], v[202:205], v[114:117]
	v_mfma_f32_16x16x32_bf16 v[102:105], v[58:61], v[210:213], v[102:105]
	v_mfma_f32_16x16x32_bf16 v[98:101], v[138:141], v[210:213], v[98:101]
	v_mfma_f32_16x16x32_bf16 v[86:89], v[58:61], v[218:221], v[86:89]
	v_mfma_f32_16x16x32_bf16 v[82:85], v[138:141], v[218:221], v[82:85]
	v_mfma_f32_16x16x32_bf16 v[134:137], v[62:65], v[186:189], v[134:137]
	v_mfma_f32_16x16x32_bf16 v[130:133], v[142:145], v[186:189], v[130:133]
	v_mfma_f32_16x16x32_bf16 v[118:121], v[62:65], v[206:209], v[118:121]
	v_mfma_f32_16x16x32_bf16 v[114:117], v[142:145], v[206:209], v[114:117]
	v_mfma_f32_16x16x32_bf16 v[102:105], v[62:65], v[214:217], v[102:105]
	v_mfma_f32_16x16x32_bf16 v[98:101], v[142:145], v[214:217], v[98:101]
	v_mfma_f32_16x16x32_bf16 v[86:89], v[62:65], v[222:225], v[86:89]
	v_mfma_f32_16x16x32_bf16 v[82:85], v[142:145], v[222:225], v[82:85]
	v_mfma_f32_16x16x32_bf16 v[126:129], v[146:149], v[182:185], v[126:129]
	v_mfma_f32_16x16x32_bf16 v[122:125], v[174:177], v[182:185], v[122:125]
	v_mfma_f32_16x16x32_bf16 v[110:113], v[146:149], v[202:205], v[110:113]
	v_mfma_f32_16x16x32_bf16 v[106:109], v[174:177], v[202:205], v[106:109]
	v_mfma_f32_16x16x32_bf16 v[94:97], v[146:149], v[210:213], v[94:97]
	v_mfma_f32_16x16x32_bf16 v[90:93], v[174:177], v[210:213], v[90:93]
	v_mfma_f32_16x16x32_bf16 v[78:81], v[146:149], v[218:221], v[78:81]
	v_mfma_f32_16x16x32_bf16 v[74:77], v[174:177], v[218:221], v[74:77]
	v_mfma_f32_16x16x32_bf16 v[126:129], v[150:153], v[186:189], v[126:129]
	v_mfma_f32_16x16x32_bf16 v[122:125], v[178:181], v[186:189], v[122:125]
	v_mfma_f32_16x16x32_bf16 v[110:113], v[150:153], v[206:209], v[110:113]
	v_mfma_f32_16x16x32_bf16 v[106:109], v[178:181], v[206:209], v[106:109]
	v_mfma_f32_16x16x32_bf16 v[94:97], v[150:153], v[214:217], v[94:97]
	v_mfma_f32_16x16x32_bf16 v[90:93], v[178:181], v[214:217], v[90:93]
	v_mfma_f32_16x16x32_bf16 v[78:81], v[150:153], v[222:225], v[78:81]
	v_mfma_f32_16x16x32_bf16 v[74:77], v[178:181], v[222:225], v[74:77]
	s_barrier
	s_add_u32 s98, s48, 0x80
	s_addc_u32 s99, s49, 0
	s_add_i32 s50, s58, s28
	s_mov_b32 m0, s50
	ds_read_b128 v[182:185], v198 offset:49152
	ds_read_b128 v[186:189], v198 offset:50176
	ds_read_b128 v[202:205], v198 offset:51200
	ds_read_b128 v[206:209], v198 offset:52224
	ds_read_b128 v[210:213], v198 offset:53248
	ds_read_b128 v[214:217], v198 offset:54272
	ds_read_b128 v[218:221], v198 offset:55296
	ds_read_b128 v[222:225], v198 offset:56320
	global_load_lds_dwordx4 v156, s[98:99]
	s_add_i32 m0, s50, 0x2000
	s_add_u32 s48, s48, 0x20080
	v_lshl_add_u64 v[190:191], v[226:227], 0, s[10:11]
	s_addc_u32 s49, s49, 0
	s_add_i32 s50, s59, s28
	global_load_lds_dwordx4 v[190:191], off
	s_mov_b32 m0, s50
	s_nop 0
	global_load_lds_dwordx4 v156, s[48:49]
	s_add_i32 m0, s50, 0x2000
	s_nop 0
	global_load_lds_dwordx4 v160, s[48:49]
	v_lshl_add_u64 v[190:191], v[228:229], 0, s[10:11]
	s_mov_b32 m0, s53
	s_nop 0
	global_load_lds_dwordx4 v[190:191], off
	v_lshl_add_u64 v[190:191], v[230:231], 0, s[10:11]
	s_mov_b32 m0, s54
	s_nop 0
	global_load_lds_dwordx4 v[190:191], off
	s_waitcnt vmcnt(8)
	s_waitcnt lgkmcnt(0)
	s_barrier
	s_waitcnt lgkmcnt(0)
	v_mfma_f32_16x16x32_bf16 v[70:73], v[58:61], v[182:185], v[70:73]
	v_mfma_f32_16x16x32_bf16 v[66:69], v[138:141], v[182:185], v[66:69]
	v_mfma_f32_16x16x32_bf16 v[46:49], v[58:61], v[202:205], v[46:49]
	v_mfma_f32_16x16x32_bf16 v[42:45], v[138:141], v[202:205], v[42:45]
	v_mfma_f32_16x16x32_bf16 v[30:33], v[58:61], v[210:213], v[30:33]
	v_mfma_f32_16x16x32_bf16 v[26:29], v[138:141], v[210:213], v[26:29]
	v_mfma_f32_16x16x32_bf16 v[14:17], v[58:61], v[218:221], v[14:17]
	v_mfma_f32_16x16x32_bf16 v[10:13], v[138:141], v[218:221], v[10:13]
	v_mfma_f32_16x16x32_bf16 v[70:73], v[62:65], v[186:189], v[70:73]
	v_mfma_f32_16x16x32_bf16 v[66:69], v[142:145], v[186:189], v[66:69]
	v_mfma_f32_16x16x32_bf16 v[46:49], v[62:65], v[206:209], v[46:49]
	v_mfma_f32_16x16x32_bf16 v[42:45], v[142:145], v[206:209], v[42:45]
	v_mfma_f32_16x16x32_bf16 v[30:33], v[62:65], v[214:217], v[30:33]
	v_mfma_f32_16x16x32_bf16 v[26:29], v[142:145], v[214:217], v[26:29]
	v_mfma_f32_16x16x32_bf16 v[14:17], v[62:65], v[222:225], v[14:17]
	v_mfma_f32_16x16x32_bf16 v[10:13], v[142:145], v[222:225], v[10:13]
	v_mfma_f32_16x16x32_bf16 v[50:53], v[146:149], v[182:185], v[50:53]
	v_mfma_f32_16x16x32_bf16 v[62:65], v[150:153], v[186:189], v[50:53]
	v_mfma_f32_16x16x32_bf16 v[50:53], v[174:177], v[182:185], v[54:57]
	v_mfma_f32_16x16x32_bf16 v[38:41], v[146:149], v[202:205], v[38:41]
	v_mfma_f32_16x16x32_bf16 v[34:37], v[174:177], v[202:205], v[34:37]
	v_mfma_f32_16x16x32_bf16 v[22:25], v[146:149], v[210:213], v[22:25]
	v_mfma_f32_16x16x32_bf16 v[18:21], v[174:177], v[210:213], v[18:21]
	v_mfma_f32_16x16x32_bf16 v[6:9], v[146:149], v[218:221], v[6:9]
	v_mfma_f32_16x16x32_bf16 v[2:5], v[174:177], v[218:221], v[2:5]
	v_mfma_f32_16x16x32_bf16 v[58:61], v[178:181], v[186:189], v[50:53]
	v_mfma_f32_16x16x32_bf16 v[38:41], v[150:153], v[206:209], v[38:41]
	v_mfma_f32_16x16x32_bf16 v[34:37], v[178:181], v[206:209], v[34:37]
	v_mfma_f32_16x16x32_bf16 v[22:25], v[150:153], v[214:217], v[22:25]
	v_mfma_f32_16x16x32_bf16 v[18:21], v[178:181], v[214:217], v[18:21]
	v_mfma_f32_16x16x32_bf16 v[6:9], v[150:153], v[222:225], v[6:9]
	v_mfma_f32_16x16x32_bf16 v[2:5], v[178:181], v[222:225], v[2:5]
	s_barrier
; #define LAS __attribute__((address_space(3)))
;     __device__ __forceinline__ void operator()(const f32x4 (&acc)[2][2][4][2], const Unit& u, int wr, int wc, int fr, int fq) const {
;         const int s = u.pm >> 5, lane = fq * 16 + fr, rr = lane >> 3, pc = lane & 7;
;         const float* __restrict__ xi = xin + (size_t)u.pm * BM * DM; float* __restrict__ xo = xout + (size_t)u.pm * BM * DM; bf16_t* __restrict__ ho = Hn + (size_t)u.pm * BM * DM;
;         LAS unsigned char* st = lds_epi + (wr * 4 + wc) * 2304;
;         LAS float* sst = (LAS float*)(lds_epi + 18432 + (wr * 4 + wc) * 512);
;         const int colr = u.pn * BM + wc * 64 + 4 * pc;
;         const unsigned eb = (unsigned)((wr * 64 + rr) * DM + colr);
;         f32x4 gv[2], gsn[2];
; #pragma unroll
;         for (int bj = 0; bj < 2; ++bj) { gv[bj] = *(const f32x4*)(gate + (size_t)s * MODW + colr + bj * 32) * (0.5f * GS2);
;             if (!PLAIN) gsn[bj] = *(const f32x4*)(gnext + colr + bj * 32) * (*(const f32x4*)(scnext + (size_t)s * MODW + colr + bj * 32) + 1.0f); else gsn[bj] = gv[bj]; }
;         const unsigned wr_off = (unsigned)(fr * 144 + 16 * fq), rd_off = (unsigned)(rr * 144 + pc * 16);
;         const bool odd = (rr & 1) != 0;
;         f32x4 xb[2][2][2];
;     ...
;         ERN_LOADX(0);
; #pragma unroll
;         for (int g = 0; g < 8; ++g) { const int ai = g >> 2, m = g & 3;
;             if (g + 1 < 8) ERN_LOADX(g + 1);
;             float sq0 = 0.f, sq1 = 0.f; u32x2 hw[2][2];
; #pragma unroll
;             for (int bj = 0; bj < 2; ++bj) {
;                 *(LAS f32x4*)(st + wr_off) = acc[ai][bj][m][0]; *(LAS f32x4*)(st + wr_off + 64) = acc[ai][bj][m][1];
;                 const f32x4 a0 = *(const LAS f32x4*)(st + rd_off), a1 = *(const LAS f32x4*)(st + rd_off + 8 * 144);
;                 { const f32x4 xv = xb[g & 1][bj][0] + gv[bj] * a0; __builtin_nontemporal_store(xv, (f32x4*)((char*)xo + 4u * ERN_EOFF(g, bj, 0)));
;                   sq0 += (xv.x * xv.x + xv.y * xv.y) + (xv.z * xv.z + xv.w * xv.w);
;                   const f32x4 hv = xv * gsn[bj]; hw[bj][0].x = cvt_pk_bf16(hv.x, hv.y); hw[bj][0].y = cvt_pk_bf16(hv.z, hv.w); }
;                 { const f32x4 xv = xb[g & 1][bj][1] + gv[bj] * a1; __builtin_nontemporal_store(xv, (f32x4*)((char*)xo + 4u * ERN_EOFF(g, bj, 1)));
;                   sq1 += (xv.x * xv.x + xv.y * xv.y) + (xv.z * xv.z + xv.w * xv.w);
	s_add_i32 s47, s47, 2
	s_add_u32 s16, s16, 0x100
	s_addc_u32 s17, s17, 0
	s_add_u32 s24, s24, 0x100
	s_addc_u32 s25, s25, 0
	s_cmp_gt_u32 s47, 29
	s_cbranch_scc0 .LBB0_1250
	s_setprio 0
	s_ashr_i32 s0, s92, 5
	s_ashr_i32 s93, s92, 31
	v_lshl_or_b32 v50, s46, 8, v192
	s_mul_hi_i32 s15, s0, 0x12000
	s_mul_i32 s0, s0, 0x12000
	s_add_u32 s16, s35, s0
	v_ashrrev_i32_e32 v51, 31, v50
	s_addc_u32 s17, s36, s15
	v_lshlrev_b64 v[52:53], 2, v[50:51]
	v_lshl_add_u64 v[138:139], s[16:17], 0, v[52:53]
	s_add_u32 s16, s37, s0
	s_addc_u32 s17, s52, s15
	v_lshl_add_u64 v[140:141], s[8:9], 0, v[52:53]
	v_lshl_add_u64 v[52:53], s[16:17], 0, v[52:53]
	s_lshl_b64 s[16:17], s[92:93], 21
	s_add_u32 s48, s90, s16
	v_add_u32_e32 v202, v50, v193
	s_addc_u32 s49, s91, s17
	v_lshlrev_b32_e32 v205, 2, v202
	global_load_dwordx4 v[54:57], v[138:139], off
	global_load_dwordx4 v[174:177], v[140:141], off
	global_load_dwordx4 v[178:181], v[52:53], off
	global_load_dwordx4 v[206:209], v[52:53], off offset:128
	global_load_dwordx4 v[186:189], v205, s[48:49]
	v_add_u32_e32 v50, 0x10000, v205
	global_load_dwordx4 v[210:213], v50, s[48:49]
	global_load_dwordx4 v[214:217], v[140:141], off offset:128
	s_nop 0
	global_load_dwordx4 v[50:53], v[138:139], off offset:128
	global_load_dwordx4 v[218:221], v205, s[48:49] offset:128
	v_add_u32_e32 v204, 0x10080, v205
	global_load_dwordx4 v[222:225], v204, s[48:49]
	v_add_u32_e32 v138, 0x20000, v205
	v_add_u32_e32 v162, 0x30000, v205
	v_add_u32_e32 v184, 0x20080, v205
	v_add_u32_e32 v182, 0x30080, v205
	global_load_dwordx4 v[150:153], v138, s[48:49]
	global_load_dwordx4 v[146:149], v162, s[48:49]
	global_load_dwordx4 v[142:145], v184, s[48:49]
	s_nop 0
	global_load_dwordx4 v[138:141], v182, s[48:49]
	s_and_b64 vcc, exec, s[12:13]
	s_cbranch_vccz .Lalign_1253
	s_barrier
.Lalign_1253:
	ds_write_b128 v200, v[134:137]
	ds_write_b128 v200, v[130:133] offset:64
	v_and_b32_e32 v135, 64, v199
	ds_read_b128 v[130:133], v201
	ds_read_b128 v[226:229], v201 offset:1152
	v_xor_b32_e32 v134, 8, v199
	v_add_u32_e32 v183, 64, v135
	v_cmp_lt_i32_e32 vcc, v134, v183
	v_add_u32_e32 v185, 0x4000, v202
	v_lshlrev_b32_e32 v230, 2, v185
	v_cndmask_b32_e32 v134, v199, v134, vcc
	v_lshlrev_b32_e32 v203, 2, v134
	s_lshl_b64 s[16:17], s[92:93], 20
	v_readlane_b32 s0, v252, 41
	s_add_u32 s46, s0, s16
	v_readlane_b32 s0, v252, 42
	s_addc_u32 s47, s0, s17
	s_waitcnt vmcnt(0)
	v_pk_add_f32 v[134:135], v[180:181], 1.0 op_sel_hi:[1,0]
	v_pk_add_f32 v[136:137], v[178:179], 1.0 op_sel_hi:[1,0]
	v_pk_mul_f32 v[178:179], v[176:177], v[134:135]
	v_pk_mul_f32 v[180:181], v[174:175], v[136:137]
	s_waitcnt lgkmcnt(1)
	v_pk_fma_f32 v[134:135], v[54:55], v[130:131], v[186:187]
	s_waitcnt lgkmcnt(0)
	v_pk_fma_f32 v[130:131], v[54:55], v[226:227], v[210:211]
	v_pk_fma_f32 v[136:137], v[56:57], v[132:133], v[188:189]
	v_pk_fma_f32 v[132:133], v[56:57], v[228:229], v[212:213]
	v_pk_mul_f32 v[186:187], v[180:181], v[130:131]
	v_pk_add_f32 v[190:191], v[208:209], 1.0 op_sel_hi:[1,0]
	global_store_dwordx4 v205, v[134:137], s[48:49] nt
	v_pk_mul_f32 v[174:175], v[178:179], v[136:137]
	v_pk_mul_f32 v[176:177], v[180:181], v[134:135]
	v_pk_mul_f32 v[208:209], v[178:179], v[132:133]
	v_cvt_pk_bf16_f32 v188, v176, v177
	v_cvt_pk_bf16_f32 v189, v174, v175
	global_store_dwordx4 v230, v[130:133], s[48:49] nt
	v_cvt_pk_bf16_f32 v186, v186, v187
	v_cvt_pk_bf16_f32 v187, v208, v209
	ds_write_b128 v200, v[126:129]
	ds_write_b128 v200, v[122:125] offset:64
	ds_read_b128 v[122:125], v201
	v_pk_add_f32 v[126:127], v[206:207], 1.0 op_sel_hi:[1,0]
	ds_read_b128 v[206:209], v201 offset:1152
	v_pk_mul_f32 v[174:175], v[216:217], v[190:191]
	v_pk_mul_f32 v[176:177], v[214:215], v[126:127]
	s_waitcnt lgkmcnt(1)
	v_pk_fma_f32 v[128:129], v[52:53], v[124:125], v[220:221]
	v_pk_fma_f32 v[126:127], v[50:51], v[122:123], v[218:219]
	s_waitcnt lgkmcnt(0)
	v_pk_fma_f32 v[122:123], v[50:51], v[206:207], v[222:223]
	v_pk_mul_f32 v[190:191], v[174:175], v[128:129]
	v_pk_mul_f32 v[206:207], v[176:177], v[126:127]
	global_store_dwordx4 v205, v[126:129], s[48:49] offset:128 nt
	v_cvt_pk_bf16_f32 v206, v206, v207
	v_cvt_pk_bf16_f32 v191, v190, v191
	ds_bpermute_b32 v190, v203, v206
	ds_bpermute_b32 v191, v203, v191
	v_pk_fma_f32 v[124:125], v[52:53], v[208:209], v[224:225]
	v_pk_mul_f32 v[206:207], v[176:177], v[122:123]
	global_store_dwordx4 v204, v[122:125], s[48:49] nt
	v_cvt_pk_bf16_f32 v204, v206, v207
	v_lshlrev_b32_e32 v207, 1, v202
	v_pk_mul_f32 v[208:209], v[174:175], v[124:125]
	s_nop 0
	v_cvt_pk_bf16_f32 v206, v208, v209
	s_waitcnt lgkmcnt(0)
	v_add_u32_e32 v250, 0xfffff040, v207
	v_cndmask_b32_e64 v250, v207, v250, s[40:41]
	v_cndmask_b32_e64 v248, v188, v190, s[40:41]
	v_cndmask_b32_e64 v249, v189, v191, s[40:41]
	global_store_dwordx2 v250, v[248:249], s[46:47]
	v_cndmask_b32_e64 v246, v190, v188, s[40:41]
	v_cndmask_b32_e64 v247, v191, v189, s[40:41]
	s_waitcnt lgkmcnt(1)
	v_add_u32_e32 v190, 0x1040, v207
	v_cndmask_b32_e64 v190, v207, v190, s[38:39]
	global_store_dwordx2 v190, v[246:247], s[46:47]
	ds_bpermute_b32 v188, v203, v204
	ds_bpermute_b32 v189, v203, v206
	v_lshlrev_b32_e32 v206, 1, v185
	s_and_saveexec_b64 s[16:17], s[40:41]
	v_readlane_b32 s60, v252, 4
	v_readlane_b32 s58, v252, 10
	s_xor_b64 s[16:17], exec, s[16:17]
	v_readlane_b32 s61, v252, 5
	v_readlane_b32 s59, v252, 11
	s_cbranch_execz .LBB0_1259
	v_lshlrev_b32_e32 v206, 1, v185
	v_add_u32_e32 v185, 0xfffff040, v206
	s_waitcnt lgkmcnt(0)
	global_store_dwordx2 v185, v[188:189], s[46:47]

; #define PG8_STAGE(bufoff, gbase, voff) do { _Pragma("unroll") for (int _i = 0; _i < 2; ++_i) \
;         __builtin_amdgcn_global_load_lds((const unsigned*)((const char*)(gbase) + (voff)[_i]), (LAS unsigned*)(lds + (bufoff) + ldsw + _i * 8192), 16, 0, 0); } while (0)
; #define PG8_LDA(dst, b, h) do { _Pragma("unroll") for (int m = 0; m < 4; ++m) _Pragma("unroll") for (int k = 0; k < 2; ++k) dst[m][k] = *(const LAS bf16x8*)(lds + PG8_SA(b, h) + aoff + m * 2048 + k * 1024); } while (0)
; #define PG8_LDB(dst, b, h) do { _Pragma("unroll") for (int n = 0; n < 2; ++n) _Pragma("unroll") for (int k = 0; k < 2; ++k) dst[n][k] = *(const LAS bf16x8*)(lds + PG8_SB(b, h) + boff + n * 2048 + k * 1024); } while (0)
; template <class Epi, class Sched, bool ALIGN_EPI = false, bool SP2 = false>
; __device__ __forceinline__ void gemm_phase(LAS unsigned char* lds, const Gemm g, const Sched& S, const Epi& E) {
;     ...
;         for (int t = 0; t < nt; t += 2) {
;             const bool last = (t == nt - 2);
;             const char* a1 = cA + (size_t)(t + 1) * kstep;
;             const char* a2 = last ? nA : cA + (size_t)(t + 2) * kstep; const char* b2 = last ? nB : cB + (size_t)(t + 2) * kstep;
;             const char* a3 = a2 + kstep; const char* b3 = b2 + kstep;
;             if (last && has_next) S.a_ready(nxt);
;             if constexpr (SP2) {
;             PG8_LDB(B0, 0, 0); PG8_LDB(B1, 0, 1); PG8_SCHED; PG8_LDA(At, 0, 0); PG8_STAGE(PG8_SA(1, 1), a1 + hstep, voffA);
;             PG8_WAIT_V(8); PG8_WAIT_L(0); PG8_BAR; PG8_MMA(0, 0, At, B0); PG8_MMA(0, 1, At, B1); PG8_BAR; PG8_SCHED;
;             PG8_LDA(At, 0, 1); PG8_STAGE(PG8_SB(0, 0), b2, voffB); PG8_STAGE(PG8_SB(0, 1), b2 + hstepB, voffB); PG8_STAGE(PG8_SA(0, 0), a2, voffA);
;             PG8_WAIT_V(8); PG8_WAIT_L(0); PG8_BAR; PG8_MMA(1, 0, At, B0); PG8_MMA(1, 1, At, B1); PG8_BAR; PG8_SCHED;
;             PG8_LDB(B0, 1, 0); PG8_LDB(B1, 1, 1); PG8_SCHED; PG8_LDA(At, 1, 0); PG8_STAGE(PG8_SA(0, 1), a2 + hstep, voffA);
;             PG8_WAIT_V(8); PG8_WAIT_L(0); PG8_BAR; PG8_MMA(0, 0, At, B0); PG8_MMA(0, 1, At, B1); PG8_BAR; PG8_SCHED;
;             PG8_LDA(At, 1, 1); PG8_STAGE(PG8_SB(1, 0), b3, voffB); PG8_STAGE(PG8_SB(1, 1), b3 + hstepB, voffB); PG8_STAGE(PG8_SA(1, 0), a3, voffA);
;             PG8_WAIT_V(8); PG8_WAIT_L(0); PG8_BAR; PG8_MMA(1, 0, At, B0); PG8_MMA(1, 1, At, B1); PG8_BAR; PG8_SCHED;
.LBB0_1595:
	ds_read_b128 v[130:133], v196
	ds_read_b128 v[134:137], v196 offset:1024
	ds_read_b128 v[138:141], v196 offset:2048
	ds_read_b128 v[142:145], v196 offset:3072
	ds_read_b128 v[166:169], v197
	ds_read_b128 v[170:173], v197 offset:1024
	ds_read_b128 v[174:177], v197 offset:2048
	ds_read_b128 v[178:181], v197 offset:3072
	s_add_u32 s20, s16, 0x100
	s_addc_u32 s21, s17, 0
	s_cmpk_eq_i32 s25, 0x54
	s_cselect_b32 s47, s3, s21
	s_cselect_b32 s46, s2, s20
	s_cselect_b32 s23, s19, s24
	s_cselect_b32 s22, s18, s9
	v_lshl_add_u64 v[190:191], s[16:17], 0, v[158:159]
	s_add_i32 m0, s31, 0xc000
	ds_read_b128 v[182:185], v198
	ds_read_b128 v[186:189], v198 offset:1024
	ds_read_b128 v[202:205], v198 offset:2048
	ds_read_b128 v[206:209], v198 offset:3072
	ds_read_b128 v[210:213], v198 offset:4096
	ds_read_b128 v[214:217], v198 offset:5120
	ds_read_b128 v[218:221], v198 offset:6144
	ds_read_b128 v[222:225], v198 offset:7168
	global_load_lds_dwordx4 v[190:191], off
	v_lshl_add_u64 v[190:191], s[16:17], 0, v[160:161]
	s_add_i32 m0, s31, 0xe000
	s_nop 0
	global_load_lds_dwordx4 v[190:191], off
	s_waitcnt vmcnt(8)
	s_waitcnt lgkmcnt(0)
	s_barrier
	s_waitcnt lgkmcnt(0)
	v_mfma_f32_16x16x32_bf16 v[126:129], v[130:133], v[182:185], v[126:129]
	v_mfma_f32_16x16x32_bf16 v[122:125], v[138:141], v[182:185], v[122:125]
	v_mfma_f32_16x16x32_bf16 v[110:113], v[130:133], v[202:205], v[110:113]
	v_mfma_f32_16x16x32_bf16 v[106:109], v[138:141], v[202:205], v[106:109]
	v_mfma_f32_16x16x32_bf16 v[94:97], v[130:133], v[210:213], v[94:97]
	v_mfma_f32_16x16x32_bf16 v[90:93], v[138:141], v[210:213], v[90:93]
	v_mfma_f32_16x16x32_bf16 v[78:81], v[130:133], v[218:221], v[78:81]
	v_mfma_f32_16x16x32_bf16 v[74:77], v[138:141], v[218:221], v[74:77]
	v_mfma_f32_16x16x32_bf16 v[126:129], v[134:137], v[186:189], v[126:129]
	v_mfma_f32_16x16x32_bf16 v[122:125], v[142:145], v[186:189], v[122:125]
	v_mfma_f32_16x16x32_bf16 v[110:113], v[134:137], v[206:209], v[110:113]
	v_mfma_f32_16x16x32_bf16 v[106:109], v[142:145], v[206:209], v[106:109]
	v_mfma_f32_16x16x32_bf16 v[94:97], v[134:137], v[214:217], v[94:97]
	v_mfma_f32_16x16x32_bf16 v[90:93], v[142:145], v[214:217], v[90:93]
	v_mfma_f32_16x16x32_bf16 v[78:81], v[134:137], v[222:225], v[78:81]
	v_mfma_f32_16x16x32_bf16 v[74:77], v[142:145], v[222:225], v[74:77]
	v_mfma_f32_16x16x32_bf16 v[118:121], v[166:169], v[182:185], v[118:121]
	v_mfma_f32_16x16x32_bf16 v[114:117], v[174:177], v[182:185], v[114:117]
	v_mfma_f32_16x16x32_bf16 v[102:105], v[166:169], v[202:205], v[102:105]
	v_mfma_f32_16x16x32_bf16 v[98:101], v[174:177], v[202:205], v[98:101]
	v_mfma_f32_16x16x32_bf16 v[86:89], v[166:169], v[210:213], v[86:89]
	v_mfma_f32_16x16x32_bf16 v[82:85], v[174:177], v[210:213], v[82:85]
	v_mfma_f32_16x16x32_bf16 v[70:73], v[166:169], v[218:221], v[70:73]
	v_mfma_f32_16x16x32_bf16 v[66:69], v[174:177], v[218:221], v[66:69]
	v_mfma_f32_16x16x32_bf16 v[118:121], v[170:173], v[186:189], v[118:121]
	v_mfma_f32_16x16x32_bf16 v[114:117], v[178:181], v[186:189], v[114:117]
	v_mfma_f32_16x16x32_bf16 v[102:105], v[170:173], v[206:209], v[102:105]
	v_mfma_f32_16x16x32_bf16 v[98:101], v[178:181], v[206:209], v[98:101]
	v_mfma_f32_16x16x32_bf16 v[86:89], v[170:173], v[214:217], v[86:89]
	v_mfma_f32_16x16x32_bf16 v[82:85], v[178:181], v[214:217], v[82:85]
	v_mfma_f32_16x16x32_bf16 v[70:73], v[170:173], v[222:225], v[70:73]
	v_mfma_f32_16x16x32_bf16 v[66:69], v[178:181], v[222:225], v[66:69]
	s_barrier
	s_add_i32 s16, s52, s30
	s_mov_b32 m0, s16
	ds_read_b128 v[182:185], v198 offset:16384
	ds_read_b128 v[186:189], v198 offset:17408
	ds_read_b128 v[202:205], v198 offset:18432
	ds_read_b128 v[206:209], v198 offset:19456
	ds_read_b128 v[210:213], v198 offset:20480
	ds_read_b128 v[214:217], v198 offset:21504
	ds_read_b128 v[218:221], v198 offset:22528
	ds_read_b128 v[222:225], v198 offset:23552
	global_load_lds_dwordx4 v148, s[22:23]
	s_add_i32 m0, s16, 0x2000
	s_add_u32 s16, s22, 0x58000
	v_lshl_add_u64 v[226:227], s[22:23], 0, v[152:153]
	s_addc_u32 s17, s23, 0
	s_add_i32 s56, s53, s30
	global_load_lds_dwordx4 v152, s[22:23]
	s_mov_b32 m0, s56
	s_nop 0
	global_load_lds_dwordx4 v148, s[16:17]
	s_add_i32 m0, s56, 0x2000
	s_nop 0
	global_load_lds_dwordx4 v152, s[16:17]
	s_mov_b32 m0, s31
	s_nop 0
	global_load_lds_dwordx4 v146, s[46:47]
	s_mov_b32 m0, s33
	s_nop 0
	global_load_lds_dwordx4 v150, s[46:47]
	s_waitcnt vmcnt(8)
	s_waitcnt lgkmcnt(0)
	s_barrier
	s_waitcnt lgkmcnt(0)
	v_mfma_f32_16x16x32_bf16 v[62:65], v[130:133], v[182:185], v[62:65]
	v_mfma_f32_16x16x32_bf16 v[58:61], v[138:141], v[182:185], v[58:61]
	v_mfma_f32_16x16x32_bf16 v[46:49], v[130:133], v[202:205], v[46:49]
	v_mfma_f32_16x16x32_bf16 v[42:45], v[138:141], v[202:205], v[42:45]
	v_mfma_f32_16x16x32_bf16 v[30:33], v[130:133], v[210:213], v[30:33]
	v_mfma_f32_16x16x32_bf16 v[26:29], v[138:141], v[210:213], v[26:29]
	v_mfma_f32_16x16x32_bf16 v[14:17], v[130:133], v[218:221], v[14:17]
	v_mfma_f32_16x16x32_bf16 v[10:13], v[138:141], v[218:221], v[10:13]
	v_mfma_f32_16x16x32_bf16 v[62:65], v[134:137], v[186:189], v[62:65]
	v_mfma_f32_16x16x32_bf16 v[58:61], v[142:145], v[186:189], v[58:61]
	v_mfma_f32_16x16x32_bf16 v[46:49], v[134:137], v[206:209], v[46:49]
	v_mfma_f32_16x16x32_bf16 v[42:45], v[142:145], v[206:209], v[42:45]
	v_mfma_f32_16x16x32_bf16 v[30:33], v[134:137], v[214:217], v[30:33]
	v_mfma_f32_16x16x32_bf16 v[26:29], v[142:145], v[214:217], v[26:29]
	v_mfma_f32_16x16x32_bf16 v[14:17], v[134:137], v[222:225], v[14:17]
	v_mfma_f32_16x16x32_bf16 v[10:13], v[142:145], v[222:225], v[10:13]
	v_mfma_f32_16x16x32_bf16 v[54:57], v[166:169], v[182:185], v[54:57]
	v_mfma_f32_16x16x32_bf16 v[50:53], v[174:177], v[182:185], v[50:53]
	v_mfma_f32_16x16x32_bf16 v[38:41], v[166:169], v[202:205], v[38:41]
	v_mfma_f32_16x16x32_bf16 v[34:37], v[174:177], v[202:205], v[34:37]
	v_mfma_f32_16x16x32_bf16 v[22:25], v[166:169], v[210:213], v[22:25]
	v_mfma_f32_16x16x32_bf16 v[18:21], v[174:177], v[210:213], v[18:21]
	v_mfma_f32_16x16x32_bf16 v[6:9], v[166:169], v[218:221], v[6:9]
	v_mfma_f32_16x16x32_bf16 v[2:5], v[174:177], v[218:221], v[2:5]
	v_mfma_f32_16x16x32_bf16 v[54:57], v[170:173], v[186:189], v[54:57]
	v_mfma_f32_16x16x32_bf16 v[50:53], v[178:181], v[186:189], v[50:53]
	v_mfma_f32_16x16x32_bf16 v[38:41], v[170:173], v[206:209], v[38:41]
	v_mfma_f32_16x16x32_bf16 v[34:37], v[178:181], v[206:209], v[34:37]
	v_mfma_f32_16x16x32_bf16 v[22:25], v[170:173], v[214:217], v[22:25]
	v_mfma_f32_16x16x32_bf16 v[18:21], v[178:181], v[214:217], v[18:21]
	v_mfma_f32_16x16x32_bf16 v[6:9], v[170:173], v[222:225], v[6:9]
	v_mfma_f32_16x16x32_bf16 v[2:5], v[178:181], v[222:225], v[2:5]
	s_barrier
; #define PG8_STAGE(bufoff, gbase, voff) do { _Pragma("unroll") for (int _i = 0; _i < 2; ++_i) \
;         __builtin_amdgcn_global_load_lds((const unsigned*)((const char*)(gbase) + (voff)[_i]), (LAS unsigned*)(lds + (bufoff) + ldsw + _i * 8192), 16, 0, 0); } while (0)
; #define PG8_LDA(dst, b, h) do { _Pragma("unroll") for (int m = 0; m < 4; ++m) _Pragma("unroll") for (int k = 0; k < 2; ++k) dst[m][k] = *(const LAS bf16x8*)(lds + PG8_SA(b, h) + aoff + m * 2048 + k * 1024); } while (0)
; #define PG8_LDB(dst, b, h) do { _Pragma("unroll") for (int n = 0; n < 2; ++n) _Pragma("unroll") for (int k = 0; k < 2; ++k) dst[n][k] = *(const LAS bf16x8*)(lds + PG8_SB(b, h) + boff + n * 2048 + k * 1024); } while (0)
; template <class Epi, class Sched, bool ALIGN_EPI = false, bool SP2 = false>
; __device__ __forceinline__ void gemm_phase(LAS unsigned char* lds, const Gemm g, const Sched& S, const Epi& E) {
;     ...
;         for (int t = 0; t < nt; t += 2) {
;             const bool last = (t == nt - 2);
;             const char* a1 = cA + (size_t)(t + 1) * kstep;
;             const char* a2 = last ? nA : cA + (size_t)(t + 2) * kstep; const char* b2 = last ? nB : cB + (size_t)(t + 2) * kstep;
;             const char* a3 = a2 + kstep; const char* b3 = b2 + kstep;
;             if (last && has_next) S.a_ready(nxt);
;             if constexpr (SP2) {
;             PG8_LDB(B0, 0, 0); PG8_LDB(B1, 0, 1); PG8_SCHED; PG8_LDA(At, 0, 0); PG8_STAGE(PG8_SA(1, 1), a1 + hstep, voffA);
;             PG8_WAIT_V(8); PG8_WAIT_L(0); PG8_BAR; PG8_MMA(0, 0, At, B0); PG8_MMA(0, 1, At, B1); PG8_BAR; PG8_SCHED;
;             PG8_LDA(At, 0, 1); PG8_STAGE(PG8_SB(0, 0), b2, voffB); PG8_STAGE(PG8_SB(0, 1), b2 + hstepB, voffB); PG8_STAGE(PG8_SA(0, 0), a2, voffA);
;             PG8_WAIT_V(8); PG8_WAIT_L(0); PG8_BAR; PG8_MMA(1, 0, At, B0); PG8_MMA(1, 1, At, B1); PG8_BAR; PG8_SCHED;
;             PG8_LDB(B0, 1, 0); PG8_LDB(B1, 1, 1); PG8_SCHED; PG8_LDA(At, 1, 0); PG8_STAGE(PG8_SA(0, 1), a2 + hstep, voffA);
;             PG8_WAIT_V(8); PG8_WAIT_L(0); PG8_BAR; PG8_MMA(0, 0, At, B0); PG8_MMA(0, 1, At, B1); PG8_BAR; PG8_SCHED;
;             PG8_LDA(At, 1, 1); PG8_STAGE(PG8_SB(1, 0), b3, voffB); PG8_STAGE(PG8_SB(1, 1), b3 + hstepB, voffB); PG8_STAGE(PG8_SA(1, 0), a3, voffA);
;             PG8_WAIT_V(8); PG8_WAIT_L(0); PG8_BAR; PG8_MMA(1, 0, At, B0); PG8_MMA(1, 1, At, B1); PG8_BAR; PG8_SCHED;
	s_add_i32 s56, 0, 0x18000
	s_add_i32 s57, 0, 0x1c000
	v_add_u32_e32 v142, s56, v1
	v_add_u32_e32 v154, s57, v1
	ds_read_b128 v[130:133], v142
	ds_read_b128 v[134:137], v142 offset:1024
	ds_read_b128 v[138:141], v142 offset:2048
	ds_read_b128 v[142:145], v142 offset:3072
	ds_read_b128 v[166:169], v154
	ds_read_b128 v[170:173], v154 offset:1024
	ds_read_b128 v[174:177], v154 offset:2048
	ds_read_b128 v[178:181], v154 offset:3072
	s_add_u32 s16, s46, 0x160000
	s_addc_u32 s17, s47, 0
	s_mov_b32 m0, s34
	ds_read_b128 v[182:185], v198 offset:32768
	ds_read_b128 v[186:189], v198 offset:33792
	ds_read_b128 v[202:205], v198 offset:34816
	ds_read_b128 v[206:209], v198 offset:35840
	ds_read_b128 v[210:213], v198 offset:36864
	ds_read_b128 v[214:217], v198 offset:37888
	ds_read_b128 v[218:221], v198 offset:38912
	ds_read_b128 v[222:225], v198 offset:39936
	global_load_lds_dwordx4 v146, s[16:17]
	s_mov_b32 m0, s35
	s_nop 0
	global_load_lds_dwordx4 v150, s[16:17]
	s_waitcnt vmcnt(8)
	s_waitcnt lgkmcnt(0)
	s_barrier
	s_waitcnt lgkmcnt(0)
	v_mfma_f32_16x16x32_bf16 v[126:129], v[130:133], v[182:185], v[126:129]
	v_mfma_f32_16x16x32_bf16 v[122:125], v[138:141], v[182:185], v[122:125]
	v_mfma_f32_16x16x32_bf16 v[110:113], v[130:133], v[202:205], v[110:113]
	v_mfma_f32_16x16x32_bf16 v[106:109], v[138:141], v[202:205], v[106:109]
	v_mfma_f32_16x16x32_bf16 v[94:97], v[130:133], v[210:213], v[94:97]
	v_mfma_f32_16x16x32_bf16 v[90:93], v[138:141], v[210:213], v[90:93]
	v_mfma_f32_16x16x32_bf16 v[78:81], v[130:133], v[218:221], v[78:81]
	v_mfma_f32_16x16x32_bf16 v[74:77], v[138:141], v[218:221], v[74:77]
	v_mfma_f32_16x16x32_bf16 v[126:129], v[134:137], v[186:189], v[126:129]
	v_mfma_f32_16x16x32_bf16 v[122:125], v[142:145], v[186:189], v[122:125]
	v_mfma_f32_16x16x32_bf16 v[110:113], v[134:137], v[206:209], v[110:113]
	v_mfma_f32_16x16x32_bf16 v[106:109], v[142:145], v[206:209], v[106:109]
	v_mfma_f32_16x16x32_bf16 v[94:97], v[134:137], v[214:217], v[94:97]
	v_mfma_f32_16x16x32_bf16 v[90:93], v[142:145], v[214:217], v[90:93]
	v_mfma_f32_16x16x32_bf16 v[78:81], v[134:137], v[222:225], v[78:81]
	v_mfma_f32_16x16x32_bf16 v[74:77], v[142:145], v[222:225], v[74:77]
	v_mfma_f32_16x16x32_bf16 v[118:121], v[166:169], v[182:185], v[118:121]
	v_mfma_f32_16x16x32_bf16 v[114:117], v[174:177], v[182:185], v[114:117]
	v_mfma_f32_16x16x32_bf16 v[102:105], v[166:169], v[202:205], v[102:105]
	v_mfma_f32_16x16x32_bf16 v[98:101], v[174:177], v[202:205], v[98:101]
	v_mfma_f32_16x16x32_bf16 v[86:89], v[166:169], v[210:213], v[86:89]
	v_mfma_f32_16x16x32_bf16 v[82:85], v[174:177], v[210:213], v[82:85]
	v_mfma_f32_16x16x32_bf16 v[70:73], v[166:169], v[218:221], v[70:73]
	v_mfma_f32_16x16x32_bf16 v[66:69], v[174:177], v[218:221], v[66:69]
	v_mfma_f32_16x16x32_bf16 v[118:121], v[170:173], v[186:189], v[118:121]
	v_mfma_f32_16x16x32_bf16 v[114:117], v[178:181], v[186:189], v[114:117]
	v_mfma_f32_16x16x32_bf16 v[102:105], v[170:173], v[206:209], v[102:105]
	v_mfma_f32_16x16x32_bf16 v[98:101], v[178:181], v[206:209], v[98:101]
	v_mfma_f32_16x16x32_bf16 v[86:89], v[170:173], v[214:217], v[86:89]
	v_mfma_f32_16x16x32_bf16 v[82:85], v[178:181], v[214:217], v[82:85]
	v_mfma_f32_16x16x32_bf16 v[70:73], v[170:173], v[222:225], v[70:73]
	v_mfma_f32_16x16x32_bf16 v[66:69], v[178:181], v[222:225], v[66:69]
	s_barrier
	s_add_u32 s98, s22, 0x80
	s_addc_u32 s99, s23, 0
	s_add_u32 s100, s46, 0x80
	s_addc_u32 s101, s47, 0
	s_add_i32 s16, s56, s30
	s_mov_b32 m0, s16
	ds_read_b128 v[182:185], v198 offset:49152
	ds_read_b128 v[186:189], v198 offset:50176
	ds_read_b128 v[202:205], v198 offset:51200
	ds_read_b128 v[206:209], v198 offset:52224
	ds_read_b128 v[210:213], v198 offset:53248
	ds_read_b128 v[214:217], v198 offset:54272
	ds_read_b128 v[218:221], v198 offset:55296
	ds_read_b128 v[222:225], v198 offset:56320
	global_load_lds_dwordx4 v148, s[98:99]
	s_add_i32 m0, s16, 0x2000
	s_add_u32 s16, s22, 0x58080
	v_lshl_add_u64 v[190:191], v[226:227], 0, s[12:13]
	s_addc_u32 s17, s23, 0
	s_add_i32 s22, s57, s30
	global_load_lds_dwordx4 v[190:191], off
	s_mov_b32 m0, s22
	s_nop 0
	global_load_lds_dwordx4 v148, s[16:17]
	s_add_i32 m0, s22, 0x2000
	s_nop 0
	global_load_lds_dwordx4 v152, s[16:17]
	s_mov_b32 m0, s49
	s_nop 0
	global_load_lds_dwordx4 v146, s[100:101]
	s_mov_b32 m0, s50
	s_nop 0
	global_load_lds_dwordx4 v150, s[100:101]
	s_waitcnt vmcnt(8)
	s_waitcnt lgkmcnt(0)
	s_barrier
	s_waitcnt lgkmcnt(0)
	v_mfma_f32_16x16x32_bf16 v[62:65], v[130:133], v[182:185], v[62:65]
	v_mfma_f32_16x16x32_bf16 v[58:61], v[138:141], v[182:185], v[58:61]
	v_mfma_f32_16x16x32_bf16 v[46:49], v[130:133], v[202:205], v[46:49]
	v_mfma_f32_16x16x32_bf16 v[42:45], v[138:141], v[202:205], v[42:45]
	v_mfma_f32_16x16x32_bf16 v[30:33], v[130:133], v[210:213], v[30:33]
	v_mfma_f32_16x16x32_bf16 v[26:29], v[138:141], v[210:213], v[26:29]
	v_mfma_f32_16x16x32_bf16 v[14:17], v[130:133], v[218:221], v[14:17]
	v_mfma_f32_16x16x32_bf16 v[10:13], v[138:141], v[218:221], v[10:13]
	v_mfma_f32_16x16x32_bf16 v[62:65], v[134:137], v[186:189], v[62:65]
	v_mfma_f32_16x16x32_bf16 v[58:61], v[142:145], v[186:189], v[58:61]
	v_mfma_f32_16x16x32_bf16 v[46:49], v[134:137], v[206:209], v[46:49]
	v_mfma_f32_16x16x32_bf16 v[42:45], v[142:145], v[206:209], v[42:45]
	v_mfma_f32_16x16x32_bf16 v[30:33], v[134:137], v[214:217], v[30:33]
	v_mfma_f32_16x16x32_bf16 v[26:29], v[142:145], v[214:217], v[26:29]
	v_mfma_f32_16x16x32_bf16 v[14:17], v[134:137], v[222:225], v[14:17]
	v_mfma_f32_16x16x32_bf16 v[10:13], v[142:145], v[222:225], v[10:13]
	v_mfma_f32_16x16x32_bf16 v[54:57], v[166:169], v[182:185], v[54:57]
	v_mfma_f32_16x16x32_bf16 v[50:53], v[174:177], v[182:185], v[50:53]
	v_mfma_f32_16x16x32_bf16 v[38:41], v[166:169], v[202:205], v[38:41]
	v_mfma_f32_16x16x32_bf16 v[34:37], v[174:177], v[202:205], v[34:37]
	v_mfma_f32_16x16x32_bf16 v[22:25], v[166:169], v[210:213], v[22:25]
	v_mfma_f32_16x16x32_bf16 v[18:21], v[174:177], v[210:213], v[18:21]
	v_mfma_f32_16x16x32_bf16 v[6:9], v[166:169], v[218:221], v[6:9]
	v_mfma_f32_16x16x32_bf16 v[2:5], v[174:177], v[218:221], v[2:5]
	v_mfma_f32_16x16x32_bf16 v[54:57], v[170:173], v[186:189], v[54:57]
	v_mfma_f32_16x16x32_bf16 v[50:53], v[178:181], v[186:189], v[50:53]
	v_mfma_f32_16x16x32_bf16 v[38:41], v[170:173], v[206:209], v[38:41]
	v_mfma_f32_16x16x32_bf16 v[34:37], v[178:181], v[206:209], v[34:37]
	v_mfma_f32_16x16x32_bf16 v[22:25], v[170:173], v[214:217], v[22:25]
	v_mfma_f32_16x16x32_bf16 v[18:21], v[178:181], v[214:217], v[18:21]
	v_mfma_f32_16x16x32_bf16 v[6:9], v[170:173], v[222:225], v[6:9]
	v_mfma_f32_16x16x32_bf16 v[2:5], v[178:181], v[222:225], v[2:5]
	s_barrier
; #define LAS __attribute__((address_space(3)))
; #define ERN_LOADX(q) do { _Pragma("unroll") for (int m = 0; m < 4; ++m) xb[(q) & 1][m] = *(const f32x4*)((const char*)xi + 4u * ERN_EOFF(q, m)); } while (0)
; #define ERN_LOADX(g) do { _Pragma("unroll") for (int bj_ = 0; bj_ < 2; ++bj_) _Pragma("unroll") for (int rh_ = 0; rh_ < 2; ++rh_) xb[(g) & 1][bj_][rh_] = *(const f32x4*)((const char*)xi + 4u * ERN_EOFF(g, bj_, rh_)); } while (0)
; #define PG8_BAR __builtin_amdgcn_s_barrier()
;     __device__ __forceinline__ void operator()(const f32x4 (&acc)[2][2][4][2], const Unit& u, int wr, int wc, int fr, int fq) const {
;         const int s = u.pm >> 5, lane = fq * 16 + fr, rr = lane >> 3, pc = lane & 7;
;         const float* __restrict__ xi = xin + (size_t)u.pm * BM * DM; float* __restrict__ xo = xout + (size_t)u.pm * BM * DM; bf16_t* __restrict__ ho = Hn + (size_t)u.pm * BM * DM;
;         LAS unsigned char* st = lds_epi + (wr * 4 + wc) * 2304;
;         LAS float* sst = (LAS float*)(lds_epi + 18432 + (wr * 4 + wc) * 512);
;         const int colr = u.pn * BM + wc * 64 + 4 * pc;
;         const unsigned eb = (unsigned)((wr * 64 + rr) * DM + colr);
;         f32x4 gv[2], gsn[2];
; #pragma unroll
;         for (int bj = 0; bj < 2; ++bj) { gv[bj] = *(const f32x4*)(gate + (size_t)s * MODW + colr + bj * 32) * (0.5f * GS2);
;             if (!PLAIN) gsn[bj] = *(const f32x4*)(gnext + colr + bj * 32) * (*(const f32x4*)(scnext + (size_t)s * MODW + colr + bj * 32) + 1.0f); else gsn[bj] = gv[bj]; }
;         const unsigned wr_off = (unsigned)(fr * 144 + 16 * fq), rd_off = (unsigned)(rr * 144 + pc * 16);
;         const bool odd = (rr & 1) != 0;
;         f32x4 xb[2][2][2];
;     ...
;         ERN_LOADX(0);
; #pragma unroll
;         for (int g = 0; g < 8; ++g) { const int ai = g >> 2, m = g & 3;
;             if (g + 1 < 8) ERN_LOADX(g + 1);
; template <class Epi, class Sched, bool ALIGN_EPI = false, bool SP2 = false>
; __device__ __forceinline__ void gemm_phase(LAS unsigned char* lds, const Gemm g, const Sched& S, const Epi& E) {
;     ...
;         if constexpr (ALIGN_EPI) { if (wr == 0) PG8_BAR; }
;         if constexpr (!Epi::AFTER_DRAIN) { E(acc, cur, wr, wc, fr, fq); S.done(cur); }
	s_add_i32 s25, s25, 2
	s_add_u32 s9, s9, 0x100
	s_addc_u32 s24, s24, 0
	s_cmpk_gt_u32 s25, 0x55
	s_mov_b64 s[16:17], s[20:21]
	s_cbranch_scc0 .LBB0_1595
	s_setprio 0
	s_ashr_i32 s16, s8, 5
	s_ashr_i32 s9, s8, 31
	v_lshl_or_b32 v130, s0, 8, v192
	s_mul_i32 s20, s16, 0x12000
	s_mul_hi_i32 s0, s16, 0x12000
	s_add_u32 s16, s37, s20
	v_ashrrev_i32_e32 v131, 31, v130
	s_addc_u32 s17, s48, s0
	v_lshlrev_b64 v[132:133], 2, v[130:131]
	v_lshl_add_u64 v[134:135], s[16:17], 0, v[132:133]
	s_add_u32 s16, s26, s20
	s_addc_u32 s17, s27, s0
	v_lshl_add_u64 v[136:137], s[4:5], 0, v[132:133]
	v_lshl_add_u64 v[132:133], s[16:17], 0, v[132:133]
	s_lshl_b64 s[16:17], s[8:9], 21
	s_add_u32 s22, s90, s16
	v_add_u32_e32 v202, v130, v193
	s_addc_u32 s23, s91, s17
	v_lshlrev_b32_e32 v205, 2, v202
	global_load_dwordx4 v[170:173], v[136:137], off
	global_load_dwordx4 v[166:169], v[134:135], off
	global_load_dwordx4 v[186:189], v[134:135], off offset:128
	global_load_dwordx4 v[206:209], v[132:133], off
	global_load_dwordx4 v[210:213], v[132:133], off offset:128
	global_load_dwordx4 v[214:217], v205, s[22:23]
	v_add_u32_e32 v130, 0x10000, v205
	global_load_dwordx4 v[218:221], v130, s[22:23]
	global_load_dwordx4 v[222:225], v[136:137], off offset:128
	global_load_dwordx4 v[226:229], v205, s[22:23] offset:128
	v_add_u32_e32 v204, 0x10080, v205
	global_load_dwordx4 v[230:233], v204, s[22:23]
	v_add_u32_e32 v130, 0x20000, v205
	v_add_u32_e32 v154, 0x30000, v205
	v_add_u32_e32 v184, 0x20080, v205
	v_add_u32_e32 v182, 0x30080, v205
	global_load_dwordx4 v[142:145], v130, s[22:23]
	global_load_dwordx4 v[138:141], v154, s[22:23]
	global_load_dwordx4 v[134:137], v184, s[22:23]
	s_nop 0
	global_load_dwordx4 v[130:133], v182, s[22:23]
	s_and_b64 vcc, exec, s[14:15]
	s_cbranch_vccz .Lalign_1598
	s_barrier
; #define LAS __attribute__((address_space(3)))
; #define ERN_EOFF(q, m) (eb + (unsigned)((((q) & 1) * HALF + (m) * 16) * DM + ERN_COL((q) >> 1)))
;     __device__ __forceinline__ void operator()(const f32x4 (&acc)[2][2][4][2], const Unit& u, int wr, int wc, int fr, int fq) const {
;     ...
;         for (int g = 0; g < 8; ++g) { const int ai = g >> 2, m = g & 3;
;             if (g + 1 < 8) ERN_LOADX(g + 1);
;             float sq0 = 0.f, sq1 = 0.f; u32x2 hw[2][2];
; #pragma unroll
;             for (int bj = 0; bj < 2; ++bj) {
;                 *(LAS f32x4*)(st + wr_off) = acc[ai][bj][m][0]; *(LAS f32x4*)(st + wr_off + 64) = acc[ai][bj][m][1];
;                 const f32x4 a0 = *(const LAS f32x4*)(st + rd_off), a1 = *(const LAS f32x4*)(st + rd_off + 8 * 144);
;                 { const f32x4 xv = xb[g & 1][bj][0] + gv[bj] * a0; __builtin_nontemporal_store(xv, (f32x4*)((char*)xo + 4u * ERN_EOFF(g, bj, 0)));
;                   sq0 += (xv.x * xv.x + xv.y * xv.y) + (xv.z * xv.z + xv.w * xv.w);
;                   const f32x4 hv = xv * gsn[bj]; hw[bj][0].x = cvt_pk_bf16(hv.x, hv.y); hw[bj][0].y = cvt_pk_bf16(hv.z, hv.w); }
;                 { const f32x4 xv = xb[g & 1][bj][1] + gv[bj] * a1; __builtin_nontemporal_store(xv, (f32x4*)((char*)xo + 4u * ERN_EOFF(g, bj, 1)));
;                   sq1 += (xv.x * xv.x + xv.y * xv.y) + (xv.z * xv.z + xv.w * xv.w);
;                   const f32x4 hv = xv * gsn[bj]; hw[bj][1].x = cvt_pk_bf16(hv.x, hv.y); hw[bj][1].y = cvt_pk_bf16(hv.z, hv.w); }
;             }
;             if (!NOH && !PLAIN) {
; #pragma unroll
;                 for (int rh = 0; rh < 2; ++rh) { u32x2 rv; rv.x = __shfl_xor(hw[1][rh].x, 8); rv.y = __shfl_xor(hw[1][rh].y, 8);
;                     const unsigned e0 = ERN_EOFF(g, 0, rh);
;                     const unsigned ee = odd ? (e0 - DM + 32) : e0, eo2 = odd ? e0 : (e0 + DM + 32);
;                     *(u32x2*)((char*)ho + 2u * ee) = odd ? rv : hw[0][rh];
;                     *(u32x2*)((char*)ho + 2u * eo2) = odd ? hw[0][rh] : rv; }
;             }
;             if (!PLAIN) { sq0 += __shfl_xor(sq0, 1); sq0 += __shfl_xor(sq0, 2); sq0 += __shfl_xor(sq0, 4);
;             sq1 += __shfl_xor(sq1, 1); sq1 += __shfl_xor(sq1, 2); sq1 += __shfl_xor(sq1, 4); }
;             if (!PLAIN && pc == 0) { sst[g * 16 + rr] = sq0; sst[g * 16 + 8 + rr] = sq1; }
.Lalign_1598:
	ds_write_b128 v200, v[126:129]
	ds_write_b128 v200, v[122:125] offset:64
	v_and_b32_e32 v127, 64, v199
	ds_read_b128 v[122:125], v201
	ds_read_b128 v[234:237], v201 offset:1152
	v_xor_b32_e32 v126, 8, v199
	v_add_u32_e32 v183, 64, v127
	v_cmp_lt_i32_e32 vcc, v126, v183
	v_add_u32_e32 v185, 0x4000, v202
	v_lshlrev_b32_e32 v238, 2, v185
	v_cndmask_b32_e32 v126, v199, v126, vcc
	v_lshlrev_b32_e32 v203, 2, v126
	s_lshl_b64 s[16:17], s[8:9], 20
	s_add_u32 s20, s93, s16
	s_addc_u32 s21, s92, s17
	s_waitcnt vmcnt(0)
	v_pk_mul_f32 v[180:181], v[166:167], 0.5 op_sel_hi:[1,0]
	v_pk_mul_f32 v[176:177], v[168:169], 0.5 op_sel_hi:[1,0]
	v_pk_add_f32 v[126:127], v[208:209], 1.0 op_sel_hi:[1,0]
	v_pk_add_f32 v[128:129], v[206:207], 1.0 op_sel_hi:[1,0]
	v_pk_mul_f32 v[174:175], v[172:173], v[126:127]
	v_pk_mul_f32 v[178:179], v[170:171], v[128:129]
	s_waitcnt lgkmcnt(1)
	v_pk_fma_f32 v[126:127], v[180:181], v[122:123], v[214:215]
	s_waitcnt lgkmcnt(0)
	v_pk_fma_f32 v[122:123], v[180:181], v[234:235], v[218:219]
	v_pk_mul_f32 v[168:169], v[186:187], 0.5 op_sel_hi:[1,0]
	v_pk_fma_f32 v[128:129], v[176:177], v[124:125], v[216:217]
	v_pk_fma_f32 v[124:125], v[176:177], v[236:237], v[220:221]
	v_pk_mul_f32 v[186:187], v[178:179], v[122:123]
	v_pk_mul_f32 v[166:167], v[188:189], 0.5 op_sel_hi:[1,0]
	global_store_dwordx4 v205, v[126:129], s[22:23] nt
	v_pk_mul_f32 v[170:171], v[174:175], v[128:129]
	v_pk_mul_f32 v[172:173], v[178:179], v[126:127]
	v_pk_mul_f32 v[206:207], v[174:175], v[124:125]
	v_cvt_pk_bf16_f32 v188, v172, v173
	v_cvt_pk_bf16_f32 v189, v170, v171
	global_store_dwordx4 v238, v[122:125], s[22:23] nt
	v_cvt_pk_bf16_f32 v186, v186, v187
	v_cvt_pk_bf16_f32 v187, v206, v207
	ds_write_b128 v200, v[118:121]
	ds_write_b128 v200, v[114:117] offset:64
	ds_read_b128 v[114:117], v201
	ds_read_b128 v[206:209], v201 offset:1152
	v_pk_add_f32 v[190:191], v[212:213], 1.0 op_sel_hi:[1,0]
	v_pk_add_f32 v[118:119], v[210:211], 1.0 op_sel_hi:[1,0]
	v_pk_mul_f32 v[170:171], v[224:225], v[190:191]
	v_pk_mul_f32 v[172:173], v[222:223], v[118:119]
	s_waitcnt lgkmcnt(1)
	v_pk_fma_f32 v[120:121], v[166:167], v[116:117], v[228:229]
	v_pk_fma_f32 v[118:119], v[168:169], v[114:115], v[226:227]
	s_waitcnt lgkmcnt(0)
	v_pk_fma_f32 v[114:115], v[168:169], v[206:207], v[230:231]
	v_pk_mul_f32 v[190:191], v[170:171], v[120:121]
	v_pk_mul_f32 v[206:207], v[172:173], v[118:119]
	global_store_dwordx4 v205, v[118:121], s[22:23] offset:128 nt
	v_cvt_pk_bf16_f32 v206, v206, v207
	v_cvt_pk_bf16_f32 v191, v190, v191
	ds_bpermute_b32 v190, v203, v206
	ds_bpermute_b32 v191, v203, v191
	v_pk_fma_f32 v[116:117], v[166:167], v[208:209], v[232:233]
	v_pk_mul_f32 v[206:207], v[172:173], v[114:115]
	global_store_dwordx4 v204, v[114:117], s[22:23] nt
	v_cvt_pk_bf16_f32 v204, v206, v207
	v_lshlrev_b32_e32 v207, 1, v202
	v_pk_mul_f32 v[208:209], v[170:171], v[116:117]
	s_nop 0
	v_cvt_pk_bf16_f32 v206, v208, v209
	s_waitcnt lgkmcnt(0)
	v_add_u32_e32 v250, 0xfffff040, v207
	v_cndmask_b32_e64 v250, v207, v250, s[40:41]
	v_cndmask_b32_e64 v248, v188, v190, s[40:41]
	v_cndmask_b32_e64 v249, v189, v191, s[40:41]
	global_store_dwordx2 v250, v[248:249], s[20:21]
	v_cndmask_b32_e64 v246, v190, v188, s[40:41]
	v_cndmask_b32_e64 v247, v191, v189, s[40:41]
	s_waitcnt lgkmcnt(1)
	v_add_u32_e32 v190, 0x1040, v207
	v_cndmask_b32_e64 v190, v207, v190, s[38:39]
	global_store_dwordx2 v190, v[246:247], s[20:21]
	ds_bpermute_b32 v188, v203, v204
	ds_bpermute_b32 v189, v203, v206
	v_lshlrev_b32_e32 v206, 1, v185
	s_waitcnt lgkmcnt(0)
	v_add_u32_e32 v250, 0xfffff040, v206
	v_cndmask_b32_e64 v250, v206, v250, s[40:41]
	v_cndmask_b32_e64 v248, v186, v188, s[40:41]
	v_cndmask_b32_e64 v249, v187, v189, s[40:41]
	global_store_dwordx2 v250, v[248:249], s[20:21]
	v_cndmask_b32_e64 v246, v188, v186, s[40:41]
	v_cndmask_b32_e64 v247, v189, v187, s[40:41]
	v_mul_f32_e32 v119, v119, v119
	v_mul_f32_e32 v127, v127, v127
	v_mul_f32_e32 v129, v129, v129
	v_fmac_f32_e32 v119, v118, v118
	v_mul_f32_e32 v118, v121, v121
	v_fmac_f32_e32 v129, v128, v128
	v_fmac_f32_e32 v118, v120, v120
	v_mul_f32_e32 v115, v115, v115
	v_fmac_f32_e32 v127, v126, v126
	v_add_f32_e32 v118, v119, v118
	v_fmac_f32_e32 v115, v114, v114
	v_mul_f32_e32 v114, v117, v117
	v_add_f32_e32 v117, v127, v129
	v_add_f32_e32 v117, v117, v118
	v_xor_b32_e32 v118, 1, v199
	v_cmp_lt_i32_e32 vcc, v118, v183
	v_mul_f32_e32 v123, v123, v123
	v_mul_f32_e32 v125, v125, v125
	v_cndmask_b32_e32 v118, v199, v118, vcc
	v_lshlrev_b32_e32 v190, 2, v118
	ds_bpermute_b32 v118, v190, v117
	v_fmac_f32_e32 v114, v116, v116
	v_fmac_f32_e32 v125, v124, v124
	v_fmac_f32_e32 v123, v122, v122
	v_add_f32_e32 v114, v115, v114
	s_waitcnt lgkmcnt(0)
	v_add_f32_e32 v116, v117, v118
	v_xor_b32_e32 v117, 2, v199
	v_cmp_lt_i32_e32 vcc, v117, v183
	v_add_f32_e32 v115, v123, v125
	v_add_f32_e32 v115, v115, v114
	v_cndmask_b32_e32 v117, v199, v117, vcc
	v_lshlrev_b32_e32 v191, 2, v117
	ds_bpermute_b32 v117, v191, v116
	ds_bpermute_b32 v118, v190, v115
	s_waitcnt lgkmcnt(1)
	v_add_f32_e32 v114, v116, v117
	s_waitcnt lgkmcnt(0)
	v_add_f32_e32 v117, v115, v118
	ds_bpermute_b32 v118, v191, v117
	v_xor_b32_e32 v116, 4, v199
	v_cmp_lt_i32_e32 vcc, v116, v183
	s_nop 1
	v_cndmask_b32_e32 v115, v199, v116, vcc
	v_lshlrev_b32_e32 v204, 2, v115
	s_waitcnt lgkmcnt(0)
	v_add_f32_e32 v116, v117, v118
	ds_bpermute_b32 v115, v204, v114
	ds_bpermute_b32 v117, v204, v116
	v_add_u32_e32 v118, 0x1040, v206
	v_cndmask_b32_e64 v118, v206, v118, s[38:39]
	global_store_dwordx2 v118, v[246:247], s[20:21]
	s_and_saveexec_b64 s[16:17], s[42:43]
	s_cbranch_execz .LBB0_1608
	s_waitcnt lgkmcnt(1)
	v_add_f32_e32 v114, v114, v115
	s_waitcnt lgkmcnt(0)
	v_add_f32_e32 v115, v116, v117
	ds_write2_b32 v194, v114, v115 offset1:8

; #define PG8_STAGE(bufoff, gbase, voff) do { _Pragma("unroll") for (int _i = 0; _i < 2; ++_i) \
;         __builtin_amdgcn_global_load_lds((const unsigned*)((const char*)(gbase) + (voff)[_i]), (LAS unsigned*)(lds + (bufoff) + ldsw + _i * 8192), 16, 0, 0); } while (0)
; #define PG8_LDA(dst, b, h) do { _Pragma("unroll") for (int m = 0; m < 4; ++m) _Pragma("unroll") for (int k = 0; k < 2; ++k) dst[m][k] = *(const LAS bf16x8*)(lds + PG8_SA(b, h) + aoff + m * 2048 + k * 1024); } while (0)
; #define PG8_LDB(dst, b, h) do { _Pragma("unroll") for (int n = 0; n < 2; ++n) _Pragma("unroll") for (int k = 0; k < 2; ++k) dst[n][k] = *(const LAS bf16x8*)(lds + PG8_SB(b, h) + boff + n * 2048 + k * 1024); } while (0)
; template <class Epi, class Sched, bool ALIGN_EPI = false, bool SP2 = false>
; __device__ __forceinline__ void gemm_phase(LAS unsigned char* lds, const Gemm g, const Sched& S, const Epi& E) {
;     ...
;         for (int t = 0; t < nt; t += 2) {
;             const bool last = (t == nt - 2);
;             const char* a1 = cA + (size_t)(t + 1) * kstep;
;             const char* a2 = last ? nA : cA + (size_t)(t + 2) * kstep; const char* b2 = last ? nB : cB + (size_t)(t + 2) * kstep;
;             const char* a3 = a2 + kstep; const char* b3 = b2 + kstep;
;             if (last && has_next) S.a_ready(nxt);
;             if constexpr (SP2) {
;             PG8_LDB(B0, 0, 0); PG8_LDB(B1, 0, 1); PG8_SCHED; PG8_LDA(At, 0, 0); PG8_STAGE(PG8_SA(1, 1), a1 + hstep, voffA);
;             PG8_WAIT_V(8); PG8_WAIT_L(0); PG8_BAR; PG8_MMA(0, 0, At, B0); PG8_MMA(0, 1, At, B1); PG8_BAR; PG8_SCHED;
;             PG8_LDA(At, 0, 1); PG8_STAGE(PG8_SB(0, 0), b2, voffB); PG8_STAGE(PG8_SB(0, 1), b2 + hstepB, voffB); PG8_STAGE(PG8_SA(0, 0), a2, voffA);
;             PG8_WAIT_V(8); PG8_WAIT_L(0); PG8_BAR; PG8_MMA(1, 0, At, B0); PG8_MMA(1, 1, At, B1); PG8_BAR; PG8_SCHED;
;             PG8_LDB(B0, 1, 0); PG8_LDB(B1, 1, 1); PG8_SCHED; PG8_LDA(At, 1, 0); PG8_STAGE(PG8_SA(0, 1), a2 + hstep, voffA);
;             PG8_WAIT_V(8); PG8_WAIT_L(0); PG8_BAR; PG8_MMA(0, 0, At, B0); PG8_MMA(0, 1, At, B1); PG8_BAR; PG8_SCHED;
;             PG8_LDA(At, 1, 1); PG8_STAGE(PG8_SB(1, 0), b3, voffB); PG8_STAGE(PG8_SB(1, 1), b3 + hstepB, voffB); PG8_STAGE(PG8_SA(1, 0), a3, voffA);
;             PG8_WAIT_V(8); PG8_WAIT_L(0); PG8_BAR; PG8_MMA(1, 0, At, B0); PG8_MMA(1, 1, At, B1); PG8_BAR; PG8_SCHED;
.LBB0_1926:
	ds_read_b128 v[130:133], v196
	ds_read_b128 v[134:137], v196 offset:1024
	ds_read_b128 v[138:141], v196 offset:2048
	ds_read_b128 v[142:145], v196 offset:3072
	ds_read_b128 v[166:169], v197
	ds_read_b128 v[170:173], v197 offset:1024
	ds_read_b128 v[174:177], v197 offset:2048
	ds_read_b128 v[178:181], v197 offset:3072
	s_add_u32 s20, s18, 0x100
	s_addc_u32 s21, s19, 0
	s_cmpk_eq_i32 s25, 0x54
	s_cselect_b32 s47, s17, s21
	s_cselect_b32 s46, s16, s20
	s_cselect_b32 s23, s3, s24
	s_cselect_b32 s22, s2, s5
	v_lshl_add_u64 v[190:191], s[18:19], 0, v[160:161]
	s_add_i32 m0, s27, 0xc000
	ds_read_b128 v[182:185], v198
	ds_read_b128 v[186:189], v198 offset:1024
	ds_read_b128 v[202:205], v198 offset:2048
	ds_read_b128 v[206:209], v198 offset:3072
	ds_read_b128 v[210:213], v198 offset:4096
	ds_read_b128 v[214:217], v198 offset:5120
	ds_read_b128 v[218:221], v198 offset:6144
	ds_read_b128 v[222:225], v198 offset:7168
	global_load_lds_dwordx4 v[190:191], off
	v_lshl_add_u64 v[190:191], s[18:19], 0, v[158:159]
	s_add_i32 m0, s27, 0xe000
	s_nop 0
	global_load_lds_dwordx4 v[190:191], off
	s_waitcnt vmcnt(8)
	s_waitcnt lgkmcnt(0)
	s_barrier
	s_waitcnt lgkmcnt(0)
	v_mfma_f32_16x16x32_bf16 v[126:129], v[130:133], v[182:185], v[126:129]
	v_mfma_f32_16x16x32_bf16 v[122:125], v[138:141], v[182:185], v[122:125]
	v_mfma_f32_16x16x32_bf16 v[110:113], v[130:133], v[202:205], v[110:113]
	v_mfma_f32_16x16x32_bf16 v[106:109], v[138:141], v[202:205], v[106:109]
	v_mfma_f32_16x16x32_bf16 v[94:97], v[130:133], v[210:213], v[94:97]
	v_mfma_f32_16x16x32_bf16 v[90:93], v[138:141], v[210:213], v[90:93]
	v_mfma_f32_16x16x32_bf16 v[78:81], v[130:133], v[218:221], v[78:81]
	v_mfma_f32_16x16x32_bf16 v[74:77], v[138:141], v[218:221], v[74:77]
	v_mfma_f32_16x16x32_bf16 v[126:129], v[134:137], v[186:189], v[126:129]
	v_mfma_f32_16x16x32_bf16 v[122:125], v[142:145], v[186:189], v[122:125]
	v_mfma_f32_16x16x32_bf16 v[110:113], v[134:137], v[206:209], v[110:113]
	v_mfma_f32_16x16x32_bf16 v[106:109], v[142:145], v[206:209], v[106:109]
	v_mfma_f32_16x16x32_bf16 v[94:97], v[134:137], v[214:217], v[94:97]
	v_mfma_f32_16x16x32_bf16 v[90:93], v[142:145], v[214:217], v[90:93]
	v_mfma_f32_16x16x32_bf16 v[78:81], v[134:137], v[222:225], v[78:81]
	v_mfma_f32_16x16x32_bf16 v[74:77], v[142:145], v[222:225], v[74:77]
	v_mfma_f32_16x16x32_bf16 v[118:121], v[166:169], v[182:185], v[118:121]
	v_mfma_f32_16x16x32_bf16 v[114:117], v[174:177], v[182:185], v[114:117]
	v_mfma_f32_16x16x32_bf16 v[102:105], v[166:169], v[202:205], v[102:105]
	v_mfma_f32_16x16x32_bf16 v[98:101], v[174:177], v[202:205], v[98:101]
	v_mfma_f32_16x16x32_bf16 v[86:89], v[166:169], v[210:213], v[86:89]
	v_mfma_f32_16x16x32_bf16 v[82:85], v[174:177], v[210:213], v[82:85]
	v_mfma_f32_16x16x32_bf16 v[70:73], v[166:169], v[218:221], v[70:73]
	v_mfma_f32_16x16x32_bf16 v[66:69], v[174:177], v[218:221], v[66:69]
	v_mfma_f32_16x16x32_bf16 v[118:121], v[170:173], v[186:189], v[118:121]
	v_mfma_f32_16x16x32_bf16 v[114:117], v[178:181], v[186:189], v[114:117]
	v_mfma_f32_16x16x32_bf16 v[102:105], v[170:173], v[206:209], v[102:105]
	v_mfma_f32_16x16x32_bf16 v[98:101], v[178:181], v[206:209], v[98:101]
	v_mfma_f32_16x16x32_bf16 v[86:89], v[170:173], v[214:217], v[86:89]
	v_mfma_f32_16x16x32_bf16 v[82:85], v[178:181], v[214:217], v[82:85]
	v_mfma_f32_16x16x32_bf16 v[70:73], v[170:173], v[222:225], v[70:73]
	v_mfma_f32_16x16x32_bf16 v[66:69], v[178:181], v[222:225], v[66:69]
	s_barrier
	s_add_i32 s18, s50, s26
	s_mov_b32 m0, s18
	ds_read_b128 v[182:185], v198 offset:16384
	ds_read_b128 v[186:189], v198 offset:17408
	ds_read_b128 v[202:205], v198 offset:18432
	ds_read_b128 v[206:209], v198 offset:19456
	ds_read_b128 v[210:213], v198 offset:20480
	ds_read_b128 v[214:217], v198 offset:21504
	ds_read_b128 v[218:221], v198 offset:22528
	ds_read_b128 v[222:225], v198 offset:23552
	global_load_lds_dwordx4 v148, s[22:23]
	s_add_i32 m0, s18, 0x2000
	s_add_u32 s18, s22, 0x58000
	v_lshl_add_u64 v[226:227], s[22:23], 0, v[152:153]
	s_addc_u32 s19, s23, 0
	s_add_i32 s54, s51, s26
	global_load_lds_dwordx4 v152, s[22:23]
	s_mov_b32 m0, s54
	s_nop 0
	global_load_lds_dwordx4 v148, s[18:19]
	s_add_i32 m0, s54, 0x2000
	s_nop 0
	global_load_lds_dwordx4 v152, s[18:19]
	s_mov_b32 m0, s27
	s_nop 0
	global_load_lds_dwordx4 v146, s[46:47]
	s_mov_b32 m0, s28
	s_nop 0
	global_load_lds_dwordx4 v150, s[46:47]
	s_waitcnt vmcnt(8)
	s_waitcnt lgkmcnt(0)
	s_barrier
	s_waitcnt lgkmcnt(0)
	v_mfma_f32_16x16x32_bf16 v[62:65], v[130:133], v[182:185], v[62:65]
	v_mfma_f32_16x16x32_bf16 v[58:61], v[138:141], v[182:185], v[58:61]
	v_mfma_f32_16x16x32_bf16 v[46:49], v[130:133], v[202:205], v[46:49]
	v_mfma_f32_16x16x32_bf16 v[42:45], v[138:141], v[202:205], v[42:45]
	v_mfma_f32_16x16x32_bf16 v[30:33], v[130:133], v[210:213], v[30:33]
	v_mfma_f32_16x16x32_bf16 v[26:29], v[138:141], v[210:213], v[26:29]
	v_mfma_f32_16x16x32_bf16 v[14:17], v[130:133], v[218:221], v[14:17]
	v_mfma_f32_16x16x32_bf16 v[10:13], v[138:141], v[218:221], v[10:13]
	v_mfma_f32_16x16x32_bf16 v[62:65], v[134:137], v[186:189], v[62:65]
	v_mfma_f32_16x16x32_bf16 v[58:61], v[142:145], v[186:189], v[58:61]
	v_mfma_f32_16x16x32_bf16 v[46:49], v[134:137], v[206:209], v[46:49]
	v_mfma_f32_16x16x32_bf16 v[42:45], v[142:145], v[206:209], v[42:45]
	v_mfma_f32_16x16x32_bf16 v[30:33], v[134:137], v[214:217], v[30:33]
	v_mfma_f32_16x16x32_bf16 v[26:29], v[142:145], v[214:217], v[26:29]
	v_mfma_f32_16x16x32_bf16 v[14:17], v[134:137], v[222:225], v[14:17]
	v_mfma_f32_16x16x32_bf16 v[10:13], v[142:145], v[222:225], v[10:13]
	v_mfma_f32_16x16x32_bf16 v[54:57], v[166:169], v[182:185], v[54:57]
	v_mfma_f32_16x16x32_bf16 v[50:53], v[174:177], v[182:185], v[50:53]
	v_mfma_f32_16x16x32_bf16 v[38:41], v[166:169], v[202:205], v[38:41]
	v_mfma_f32_16x16x32_bf16 v[34:37], v[174:177], v[202:205], v[34:37]
	v_mfma_f32_16x16x32_bf16 v[22:25], v[166:169], v[210:213], v[22:25]
	v_mfma_f32_16x16x32_bf16 v[18:21], v[174:177], v[210:213], v[18:21]
	v_mfma_f32_16x16x32_bf16 v[6:9], v[166:169], v[218:221], v[6:9]
	v_mfma_f32_16x16x32_bf16 v[2:5], v[174:177], v[218:221], v[2:5]
	v_mfma_f32_16x16x32_bf16 v[54:57], v[170:173], v[186:189], v[54:57]
	v_mfma_f32_16x16x32_bf16 v[50:53], v[178:181], v[186:189], v[50:53]
	v_mfma_f32_16x16x32_bf16 v[38:41], v[170:173], v[206:209], v[38:41]
	v_mfma_f32_16x16x32_bf16 v[34:37], v[178:181], v[206:209], v[34:37]
	v_mfma_f32_16x16x32_bf16 v[22:25], v[170:173], v[214:217], v[22:25]
	v_mfma_f32_16x16x32_bf16 v[18:21], v[178:181], v[214:217], v[18:21]
	v_mfma_f32_16x16x32_bf16 v[6:9], v[170:173], v[222:225], v[6:9]
	v_mfma_f32_16x16x32_bf16 v[2:5], v[178:181], v[222:225], v[2:5]
	s_barrier
; #define PG8_STAGE(bufoff, gbase, voff) do { _Pragma("unroll") for (int _i = 0; _i < 2; ++_i) \
;         __builtin_amdgcn_global_load_lds((const unsigned*)((const char*)(gbase) + (voff)[_i]), (LAS unsigned*)(lds + (bufoff) + ldsw + _i * 8192), 16, 0, 0); } while (0)
; #define PG8_LDA(dst, b, h) do { _Pragma("unroll") for (int m = 0; m < 4; ++m) _Pragma("unroll") for (int k = 0; k < 2; ++k) dst[m][k] = *(const LAS bf16x8*)(lds + PG8_SA(b, h) + aoff + m * 2048 + k * 1024); } while (0)
; #define PG8_LDB(dst, b, h) do { _Pragma("unroll") for (int n = 0; n < 2; ++n) _Pragma("unroll") for (int k = 0; k < 2; ++k) dst[n][k] = *(const LAS bf16x8*)(lds + PG8_SB(b, h) + boff + n * 2048 + k * 1024); } while (0)
; template <class Epi, class Sched, bool ALIGN_EPI = false, bool SP2 = false>
; __device__ __forceinline__ void gemm_phase(LAS unsigned char* lds, const Gemm g, const Sched& S, const Epi& E) {
;     ...
;         for (int t = 0; t < nt; t += 2) {
;             const bool last = (t == nt - 2);
;             const char* a1 = cA + (size_t)(t + 1) * kstep;
;             const char* a2 = last ? nA : cA + (size_t)(t + 2) * kstep; const char* b2 = last ? nB : cB + (size_t)(t + 2) * kstep;
;             const char* a3 = a2 + kstep; const char* b3 = b2 + kstep;
;             if (last && has_next) S.a_ready(nxt);
;             if constexpr (SP2) {
;             PG8_LDB(B0, 0, 0); PG8_LDB(B1, 0, 1); PG8_SCHED; PG8_LDA(At, 0, 0); PG8_STAGE(PG8_SA(1, 1), a1 + hstep, voffA);
;             PG8_WAIT_V(8); PG8_WAIT_L(0); PG8_BAR; PG8_MMA(0, 0, At, B0); PG8_MMA(0, 1, At, B1); PG8_BAR; PG8_SCHED;
;             PG8_LDA(At, 0, 1); PG8_STAGE(PG8_SB(0, 0), b2, voffB); PG8_STAGE(PG8_SB(0, 1), b2 + hstepB, voffB); PG8_STAGE(PG8_SA(0, 0), a2, voffA);
;             PG8_WAIT_V(8); PG8_WAIT_L(0); PG8_BAR; PG8_MMA(1, 0, At, B0); PG8_MMA(1, 1, At, B1); PG8_BAR; PG8_SCHED;
;             PG8_LDB(B0, 1, 0); PG8_LDB(B1, 1, 1); PG8_SCHED; PG8_LDA(At, 1, 0); PG8_STAGE(PG8_SA(0, 1), a2 + hstep, voffA);
;             PG8_WAIT_V(8); PG8_WAIT_L(0); PG8_BAR; PG8_MMA(0, 0, At, B0); PG8_MMA(0, 1, At, B1); PG8_BAR; PG8_SCHED;
;             PG8_LDA(At, 1, 1); PG8_STAGE(PG8_SB(1, 0), b3, voffB); PG8_STAGE(PG8_SB(1, 1), b3 + hstepB, voffB); PG8_STAGE(PG8_SA(1, 0), a3, voffA);
;             PG8_WAIT_V(8); PG8_WAIT_L(0); PG8_BAR; PG8_MMA(1, 0, At, B0); PG8_MMA(1, 1, At, B1); PG8_BAR; PG8_SCHED;
	s_add_i32 s54, 0, 0x18000
	s_add_i32 s55, 0, 0x1c000
	v_add_u32_e32 v142, s54, v1
	v_add_u32_e32 v154, s55, v1
	ds_read_b128 v[130:133], v142
	ds_read_b128 v[134:137], v142 offset:1024
	ds_read_b128 v[138:141], v142 offset:2048
	ds_read_b128 v[142:145], v142 offset:3072
	ds_read_b128 v[166:169], v154
	ds_read_b128 v[170:173], v154 offset:1024
	ds_read_b128 v[174:177], v154 offset:2048
	ds_read_b128 v[178:181], v154 offset:3072
	s_add_u32 s18, s46, 0x160000
	s_addc_u32 s19, s47, 0
	s_mov_b32 m0, s29
	ds_read_b128 v[182:185], v198 offset:32768
	ds_read_b128 v[186:189], v198 offset:33792
	ds_read_b128 v[202:205], v198 offset:34816
	ds_read_b128 v[206:209], v198 offset:35840
	ds_read_b128 v[210:213], v198 offset:36864
	ds_read_b128 v[214:217], v198 offset:37888
	ds_read_b128 v[218:221], v198 offset:38912
	ds_read_b128 v[222:225], v198 offset:39936
	global_load_lds_dwordx4 v146, s[18:19]
	s_mov_b32 m0, s30
	s_nop 0
	global_load_lds_dwordx4 v150, s[18:19]
	s_waitcnt vmcnt(8)
	s_waitcnt lgkmcnt(0)
	s_barrier
	s_waitcnt lgkmcnt(0)
	v_mfma_f32_16x16x32_bf16 v[126:129], v[130:133], v[182:185], v[126:129]
	v_mfma_f32_16x16x32_bf16 v[122:125], v[138:141], v[182:185], v[122:125]
	v_mfma_f32_16x16x32_bf16 v[110:113], v[130:133], v[202:205], v[110:113]
	v_mfma_f32_16x16x32_bf16 v[106:109], v[138:141], v[202:205], v[106:109]
	v_mfma_f32_16x16x32_bf16 v[94:97], v[130:133], v[210:213], v[94:97]
	v_mfma_f32_16x16x32_bf16 v[90:93], v[138:141], v[210:213], v[90:93]
	v_mfma_f32_16x16x32_bf16 v[78:81], v[130:133], v[218:221], v[78:81]
	v_mfma_f32_16x16x32_bf16 v[74:77], v[138:141], v[218:221], v[74:77]
	v_mfma_f32_16x16x32_bf16 v[126:129], v[134:137], v[186:189], v[126:129]
	v_mfma_f32_16x16x32_bf16 v[122:125], v[142:145], v[186:189], v[122:125]
	v_mfma_f32_16x16x32_bf16 v[110:113], v[134:137], v[206:209], v[110:113]
	v_mfma_f32_16x16x32_bf16 v[106:109], v[142:145], v[206:209], v[106:109]
	v_mfma_f32_16x16x32_bf16 v[94:97], v[134:137], v[214:217], v[94:97]
	v_mfma_f32_16x16x32_bf16 v[90:93], v[142:145], v[214:217], v[90:93]
	v_mfma_f32_16x16x32_bf16 v[78:81], v[134:137], v[222:225], v[78:81]
	v_mfma_f32_16x16x32_bf16 v[74:77], v[142:145], v[222:225], v[74:77]
	v_mfma_f32_16x16x32_bf16 v[118:121], v[166:169], v[182:185], v[118:121]
	v_mfma_f32_16x16x32_bf16 v[114:117], v[174:177], v[182:185], v[114:117]
	v_mfma_f32_16x16x32_bf16 v[102:105], v[166:169], v[202:205], v[102:105]
	v_mfma_f32_16x16x32_bf16 v[98:101], v[174:177], v[202:205], v[98:101]
	v_mfma_f32_16x16x32_bf16 v[86:89], v[166:169], v[210:213], v[86:89]
	v_mfma_f32_16x16x32_bf16 v[82:85], v[174:177], v[210:213], v[82:85]
	v_mfma_f32_16x16x32_bf16 v[70:73], v[166:169], v[218:221], v[70:73]
	v_mfma_f32_16x16x32_bf16 v[66:69], v[174:177], v[218:221], v[66:69]
	v_mfma_f32_16x16x32_bf16 v[118:121], v[170:173], v[186:189], v[118:121]
	v_mfma_f32_16x16x32_bf16 v[114:117], v[178:181], v[186:189], v[114:117]
	v_mfma_f32_16x16x32_bf16 v[102:105], v[170:173], v[206:209], v[102:105]
	v_mfma_f32_16x16x32_bf16 v[98:101], v[178:181], v[206:209], v[98:101]
	v_mfma_f32_16x16x32_bf16 v[86:89], v[170:173], v[214:217], v[86:89]
	v_mfma_f32_16x16x32_bf16 v[82:85], v[178:181], v[214:217], v[82:85]
	v_mfma_f32_16x16x32_bf16 v[70:73], v[170:173], v[222:225], v[70:73]
	v_mfma_f32_16x16x32_bf16 v[66:69], v[178:181], v[222:225], v[66:69]
	s_barrier
	s_add_u32 s98, s22, 0x80
	s_addc_u32 s99, s23, 0
	s_add_u32 s100, s46, 0x80
	s_addc_u32 s101, s47, 0
	s_add_i32 s18, s54, s26
	s_mov_b32 m0, s18
	ds_read_b128 v[182:185], v198 offset:49152
	ds_read_b128 v[186:189], v198 offset:50176
	ds_read_b128 v[202:205], v198 offset:51200
	ds_read_b128 v[206:209], v198 offset:52224
	ds_read_b128 v[210:213], v198 offset:53248
	ds_read_b128 v[214:217], v198 offset:54272
	ds_read_b128 v[218:221], v198 offset:55296
	ds_read_b128 v[222:225], v198 offset:56320
	global_load_lds_dwordx4 v148, s[98:99]
	s_add_i32 m0, s18, 0x2000
	s_add_u32 s18, s22, 0x58080
	v_lshl_add_u64 v[190:191], v[226:227], 0, s[12:13]
	s_addc_u32 s19, s23, 0
	s_add_i32 s22, s55, s26
	global_load_lds_dwordx4 v[190:191], off
	s_mov_b32 m0, s22
	s_nop 0
	global_load_lds_dwordx4 v148, s[18:19]
	s_add_i32 m0, s22, 0x2000
	s_nop 0
	global_load_lds_dwordx4 v152, s[18:19]
	s_mov_b32 m0, s37
	s_nop 0
	global_load_lds_dwordx4 v146, s[100:101]
	s_mov_b32 m0, s48
	s_nop 0
	global_load_lds_dwordx4 v150, s[100:101]
	s_waitcnt vmcnt(8)
	s_waitcnt lgkmcnt(0)
	s_barrier
	s_waitcnt lgkmcnt(0)
	v_mfma_f32_16x16x32_bf16 v[62:65], v[130:133], v[182:185], v[62:65]
	v_mfma_f32_16x16x32_bf16 v[58:61], v[138:141], v[182:185], v[58:61]
	v_mfma_f32_16x16x32_bf16 v[46:49], v[130:133], v[202:205], v[46:49]
	v_mfma_f32_16x16x32_bf16 v[42:45], v[138:141], v[202:205], v[42:45]
	v_mfma_f32_16x16x32_bf16 v[30:33], v[130:133], v[210:213], v[30:33]
	v_mfma_f32_16x16x32_bf16 v[26:29], v[138:141], v[210:213], v[26:29]
	v_mfma_f32_16x16x32_bf16 v[14:17], v[130:133], v[218:221], v[14:17]
	v_mfma_f32_16x16x32_bf16 v[10:13], v[138:141], v[218:221], v[10:13]
	v_mfma_f32_16x16x32_bf16 v[62:65], v[134:137], v[186:189], v[62:65]
	v_mfma_f32_16x16x32_bf16 v[58:61], v[142:145], v[186:189], v[58:61]
	v_mfma_f32_16x16x32_bf16 v[46:49], v[134:137], v[206:209], v[46:49]
	v_mfma_f32_16x16x32_bf16 v[42:45], v[142:145], v[206:209], v[42:45]
	v_mfma_f32_16x16x32_bf16 v[30:33], v[134:137], v[214:217], v[30:33]
	v_mfma_f32_16x16x32_bf16 v[26:29], v[142:145], v[214:217], v[26:29]
	v_mfma_f32_16x16x32_bf16 v[14:17], v[134:137], v[222:225], v[14:17]
	v_mfma_f32_16x16x32_bf16 v[10:13], v[142:145], v[222:225], v[10:13]
	v_mfma_f32_16x16x32_bf16 v[54:57], v[166:169], v[182:185], v[54:57]
	v_mfma_f32_16x16x32_bf16 v[50:53], v[174:177], v[182:185], v[50:53]
	v_mfma_f32_16x16x32_bf16 v[38:41], v[166:169], v[202:205], v[38:41]
	v_mfma_f32_16x16x32_bf16 v[34:37], v[174:177], v[202:205], v[34:37]
	v_mfma_f32_16x16x32_bf16 v[22:25], v[166:169], v[210:213], v[22:25]
	v_mfma_f32_16x16x32_bf16 v[18:21], v[174:177], v[210:213], v[18:21]
	v_mfma_f32_16x16x32_bf16 v[6:9], v[166:169], v[218:221], v[6:9]
	v_mfma_f32_16x16x32_bf16 v[2:5], v[174:177], v[218:221], v[2:5]
	v_mfma_f32_16x16x32_bf16 v[54:57], v[170:173], v[186:189], v[54:57]
	v_mfma_f32_16x16x32_bf16 v[50:53], v[178:181], v[186:189], v[50:53]
	v_mfma_f32_16x16x32_bf16 v[38:41], v[170:173], v[206:209], v[38:41]
	v_mfma_f32_16x16x32_bf16 v[34:37], v[178:181], v[206:209], v[34:37]
	v_mfma_f32_16x16x32_bf16 v[22:25], v[170:173], v[214:217], v[22:25]
	v_mfma_f32_16x16x32_bf16 v[18:21], v[178:181], v[214:217], v[18:21]
	v_mfma_f32_16x16x32_bf16 v[6:9], v[170:173], v[222:225], v[6:9]
	v_mfma_f32_16x16x32_bf16 v[2:5], v[178:181], v[222:225], v[2:5]
	s_barrier
; #define LAS __attribute__((address_space(3)))
; #define ERN_LOADX(q) do { _Pragma("unroll") for (int m = 0; m < 4; ++m) xb[(q) & 1][m] = *(const f32x4*)((const char*)xi + 4u * ERN_EOFF(q, m)); } while (0)
; #define ERN_LOADX(g) do { _Pragma("unroll") for (int bj_ = 0; bj_ < 2; ++bj_) _Pragma("unroll") for (int rh_ = 0; rh_ < 2; ++rh_) xb[(g) & 1][bj_][rh_] = *(const f32x4*)((const char*)xi + 4u * ERN_EOFF(g, bj_, rh_)); } while (0)
; #define PG8_BAR __builtin_amdgcn_s_barrier()
;     __device__ __forceinline__ void operator()(const f32x4 (&acc)[2][2][4][2], const Unit& u, int wr, int wc, int fr, int fq) const {
;         const int s = u.pm >> 5, lane = fq * 16 + fr, rr = lane >> 3, pc = lane & 7;
;         const float* __restrict__ xi = xin + (size_t)u.pm * BM * DM; float* __restrict__ xo = xout + (size_t)u.pm * BM * DM; bf16_t* __restrict__ ho = Hn + (size_t)u.pm * BM * DM;
;         LAS unsigned char* st = lds_epi + (wr * 4 + wc) * 2304;
;         LAS float* sst = (LAS float*)(lds_epi + 18432 + (wr * 4 + wc) * 512);
;         const int colr = u.pn * BM + wc * 64 + 4 * pc;
;         const unsigned eb = (unsigned)((wr * 64 + rr) * DM + colr);
;         f32x4 gv[2], gsn[2];
; #pragma unroll
;         for (int bj = 0; bj < 2; ++bj) { gv[bj] = *(const f32x4*)(gate + (size_t)s * MODW + colr + bj * 32) * (0.5f * GS2);
;             if (!PLAIN) gsn[bj] = *(const f32x4*)(gnext + colr + bj * 32) * (*(const f32x4*)(scnext + (size_t)s * MODW + colr + bj * 32) + 1.0f); else gsn[bj] = gv[bj]; }
;         const unsigned wr_off = (unsigned)(fr * 144 + 16 * fq), rd_off = (unsigned)(rr * 144 + pc * 16);
;         const bool odd = (rr & 1) != 0;
;         f32x4 xb[2][2][2];
;     ...
;         ERN_LOADX(0);
; #pragma unroll
;         for (int g = 0; g < 8; ++g) { const int ai = g >> 2, m = g & 3;
;             if (g + 1 < 8) ERN_LOADX(g + 1);
; template <class Epi, class Sched, bool ALIGN_EPI = false, bool SP2 = false>
; __device__ __forceinline__ void gemm_phase(LAS unsigned char* lds, const Gemm g, const Sched& S, const Epi& E) {
;     ...
;         if constexpr (ALIGN_EPI) { if (wr == 0) PG8_BAR; }
;         if constexpr (!Epi::AFTER_DRAIN) { E(acc, cur, wr, wc, fr, fq); S.done(cur); }
	s_add_i32 s25, s25, 2
	s_add_u32 s5, s5, 0x100
	s_addc_u32 s24, s24, 0
	s_cmpk_lt_u32 s25, 0x56
	s_mov_b64 s[18:19], s[20:21]
	s_cbranch_scc1 .LBB0_1926
	s_setprio 0
	s_ashr_i32 s18, s4, 5
	s_ashr_i32 s5, s4, 31
	v_lshl_or_b32 v130, s0, 8, v192
	s_mul_i32 s20, s18, 0x12000
	s_mul_hi_i32 s0, s18, 0x12000
	s_add_u32 s18, s33, s20
	v_ashrrev_i32_e32 v131, 31, v130
	s_addc_u32 s19, s34, s0
	v_lshlrev_b64 v[132:133], 2, v[130:131]
	v_lshl_add_u64 v[134:135], s[18:19], 0, v[132:133]
	s_add_u32 s18, s35, s20
	s_addc_u32 s19, s36, s0
	v_lshl_add_u64 v[136:137], s[10:11], 0, v[132:133]
	v_lshl_add_u64 v[132:133], s[18:19], 0, v[132:133]
	s_lshl_b64 s[18:19], s[4:5], 21
	s_add_u32 s20, s90, s18
	v_add_u32_e32 v202, v130, v193
	s_addc_u32 s21, s91, s19
	v_lshlrev_b32_e32 v205, 2, v202
	global_load_dwordx4 v[170:173], v[136:137], off
	global_load_dwordx4 v[166:169], v[134:135], off
	global_load_dwordx4 v[186:189], v[134:135], off offset:128
	global_load_dwordx4 v[206:209], v[132:133], off
	global_load_dwordx4 v[210:213], v[132:133], off offset:128
	global_load_dwordx4 v[214:217], v205, s[20:21]
	v_add_u32_e32 v130, 0x10000, v205
	global_load_dwordx4 v[218:221], v130, s[20:21]
	global_load_dwordx4 v[222:225], v[136:137], off offset:128
	global_load_dwordx4 v[226:229], v205, s[20:21] offset:128
	v_add_u32_e32 v204, 0x10080, v205
	global_load_dwordx4 v[230:233], v204, s[20:21]
	v_add_u32_e32 v130, 0x20000, v205
	v_add_u32_e32 v154, 0x30000, v205
	v_add_u32_e32 v184, 0x20080, v205
	v_add_u32_e32 v182, 0x30080, v205
	global_load_dwordx4 v[142:145], v130, s[20:21]
	global_load_dwordx4 v[138:141], v154, s[20:21]
	global_load_dwordx4 v[134:137], v184, s[20:21]
	s_nop 0
	global_load_dwordx4 v[130:133], v182, s[20:21]
	s_andn2_b64 vcc, exec, s[14:15]
	s_cbranch_vccnz .Lalign_1929
	s_barrier
; #define LAS __attribute__((address_space(3)))
; #define ERN_EOFF(q, m) (eb + (unsigned)((((q) & 1) * HALF + (m) * 16) * DM + ERN_COL((q) >> 1)))
;     __device__ __forceinline__ void operator()(const f32x4 (&acc)[2][2][4][2], const Unit& u, int wr, int wc, int fr, int fq) const {
;     ...
;         for (int g = 0; g < 8; ++g) { const int ai = g >> 2, m = g & 3;
;             if (g + 1 < 8) ERN_LOADX(g + 1);
;             float sq0 = 0.f, sq1 = 0.f; u32x2 hw[2][2];
; #pragma unroll
;             for (int bj = 0; bj < 2; ++bj) {
;                 *(LAS f32x4*)(st + wr_off) = acc[ai][bj][m][0]; *(LAS f32x4*)(st + wr_off + 64) = acc[ai][bj][m][1];
;                 const f32x4 a0 = *(const LAS f32x4*)(st + rd_off), a1 = *(const LAS f32x4*)(st + rd_off + 8 * 144);
;                 { const f32x4 xv = xb[g & 1][bj][0] + gv[bj] * a0; __builtin_nontemporal_store(xv, (f32x4*)((char*)xo + 4u * ERN_EOFF(g, bj, 0)));
;                   sq0 += (xv.x * xv.x + xv.y * xv.y) + (xv.z * xv.z + xv.w * xv.w);
;                   const f32x4 hv = xv * gsn[bj]; hw[bj][0].x = cvt_pk_bf16(hv.x, hv.y); hw[bj][0].y = cvt_pk_bf16(hv.z, hv.w); }
;                 { const f32x4 xv = xb[g & 1][bj][1] + gv[bj] * a1; __builtin_nontemporal_store(xv, (f32x4*)((char*)xo + 4u * ERN_EOFF(g, bj, 1)));
;                   sq1 += (xv.x * xv.x + xv.y * xv.y) + (xv.z * xv.z + xv.w * xv.w);
;                   const f32x4 hv = xv * gsn[bj]; hw[bj][1].x = cvt_pk_bf16(hv.x, hv.y); hw[bj][1].y = cvt_pk_bf16(hv.z, hv.w); }
;             }
;             if (!NOH && !PLAIN) {
; #pragma unroll
;                 for (int rh = 0; rh < 2; ++rh) { u32x2 rv; rv.x = __shfl_xor(hw[1][rh].x, 8); rv.y = __shfl_xor(hw[1][rh].y, 8);
;                     const unsigned e0 = ERN_EOFF(g, 0, rh);
;                     const unsigned ee = odd ? (e0 - DM + 32) : e0, eo2 = odd ? e0 : (e0 + DM + 32);
;                     *(u32x2*)((char*)ho + 2u * ee) = odd ? rv : hw[0][rh];
;                     *(u32x2*)((char*)ho + 2u * eo2) = odd ? hw[0][rh] : rv; }
;             }
;             if (!PLAIN) { sq0 += __shfl_xor(sq0, 1); sq0 += __shfl_xor(sq0, 2); sq0 += __shfl_xor(sq0, 4);
;             sq1 += __shfl_xor(sq1, 1); sq1 += __shfl_xor(sq1, 2); sq1 += __shfl_xor(sq1, 4); }
;             if (!PLAIN && pc == 0) { sst[g * 16 + rr] = sq0; sst[g * 16 + 8 + rr] = sq1; }
.Lalign_1929:
	ds_write_b128 v200, v[126:129]
	ds_write_b128 v200, v[122:125] offset:64
	v_and_b32_e32 v127, 64, v199
	ds_read_b128 v[122:125], v201
	ds_read_b128 v[234:237], v201 offset:1152
	v_xor_b32_e32 v126, 8, v199
	v_add_u32_e32 v183, 64, v127
	v_cmp_lt_i32_e32 vcc, v126, v183
	v_add_u32_e32 v185, 0x4000, v202
	v_lshlrev_b32_e32 v238, 2, v185
	v_cndmask_b32_e32 v126, v199, v126, vcc
	v_lshlrev_b32_e32 v203, 2, v126
	s_lshl_b64 s[18:19], s[4:5], 20
	s_add_u32 s18, s93, s18
	s_addc_u32 s19, s92, s19
	s_waitcnt vmcnt(0)
	v_pk_mul_f32 v[180:181], v[166:167], 0.5 op_sel_hi:[1,0]
	v_pk_mul_f32 v[176:177], v[168:169], 0.5 op_sel_hi:[1,0]
	v_pk_add_f32 v[126:127], v[208:209], 1.0 op_sel_hi:[1,0]
	v_pk_add_f32 v[128:129], v[206:207], 1.0 op_sel_hi:[1,0]
	v_pk_mul_f32 v[174:175], v[172:173], v[126:127]
	v_pk_mul_f32 v[178:179], v[170:171], v[128:129]
	s_waitcnt lgkmcnt(1)
	v_pk_fma_f32 v[126:127], v[180:181], v[122:123], v[214:215]
	s_waitcnt lgkmcnt(0)
	v_pk_fma_f32 v[122:123], v[180:181], v[234:235], v[218:219]
	v_pk_mul_f32 v[168:169], v[186:187], 0.5 op_sel_hi:[1,0]
	v_pk_fma_f32 v[128:129], v[176:177], v[124:125], v[216:217]
	v_pk_fma_f32 v[124:125], v[176:177], v[236:237], v[220:221]
	v_pk_mul_f32 v[186:187], v[178:179], v[122:123]
	v_pk_mul_f32 v[166:167], v[188:189], 0.5 op_sel_hi:[1,0]
	global_store_dwordx4 v205, v[126:129], s[20:21] nt
	v_pk_mul_f32 v[170:171], v[174:175], v[128:129]
	v_pk_mul_f32 v[172:173], v[178:179], v[126:127]
	v_pk_mul_f32 v[206:207], v[174:175], v[124:125]
	v_cvt_pk_bf16_f32 v188, v172, v173
	v_cvt_pk_bf16_f32 v189, v170, v171
	global_store_dwordx4 v238, v[122:125], s[20:21] nt
	v_cvt_pk_bf16_f32 v186, v186, v187
	v_cvt_pk_bf16_f32 v187, v206, v207
	ds_write_b128 v200, v[118:121]
	ds_write_b128 v200, v[114:117] offset:64
	ds_read_b128 v[114:117], v201
	ds_read_b128 v[206:209], v201 offset:1152
	v_pk_add_f32 v[190:191], v[212:213], 1.0 op_sel_hi:[1,0]
	v_pk_add_f32 v[118:119], v[210:211], 1.0 op_sel_hi:[1,0]
	v_pk_mul_f32 v[170:171], v[224:225], v[190:191]
	v_pk_mul_f32 v[172:173], v[222:223], v[118:119]
	s_waitcnt lgkmcnt(1)
	v_pk_fma_f32 v[120:121], v[166:167], v[116:117], v[228:229]
	v_pk_fma_f32 v[118:119], v[168:169], v[114:115], v[226:227]
	s_waitcnt lgkmcnt(0)
	v_pk_fma_f32 v[114:115], v[168:169], v[206:207], v[230:231]
	v_pk_mul_f32 v[190:191], v[170:171], v[120:121]
	v_pk_mul_f32 v[206:207], v[172:173], v[118:119]
	global_store_dwordx4 v205, v[118:121], s[20:21] offset:128 nt
	v_cvt_pk_bf16_f32 v206, v206, v207
	v_cvt_pk_bf16_f32 v191, v190, v191
	ds_bpermute_b32 v190, v203, v206
	ds_bpermute_b32 v191, v203, v191
	v_pk_fma_f32 v[116:117], v[166:167], v[208:209], v[232:233]
	v_pk_mul_f32 v[206:207], v[172:173], v[114:115]
	global_store_dwordx4 v204, v[114:117], s[20:21] nt
	v_cvt_pk_bf16_f32 v204, v206, v207
	v_lshlrev_b32_e32 v207, 1, v202
	v_pk_mul_f32 v[208:209], v[170:171], v[116:117]
	s_nop 0
	v_cvt_pk_bf16_f32 v206, v208, v209
	s_waitcnt lgkmcnt(0)
	v_add_u32_e32 v250, 0xfffff040, v207
	v_cndmask_b32_e64 v250, v207, v250, s[40:41]
	v_cndmask_b32_e64 v248, v188, v190, s[40:41]
	v_cndmask_b32_e64 v249, v189, v191, s[40:41]
	global_store_dwordx2 v250, v[248:249], s[18:19]
	v_cndmask_b32_e64 v246, v190, v188, s[40:41]
	v_cndmask_b32_e64 v247, v191, v189, s[40:41]
	s_waitcnt lgkmcnt(1)
	v_add_u32_e32 v190, 0x1040, v207
	v_cndmask_b32_e64 v190, v207, v190, s[38:39]
	global_store_dwordx2 v190, v[246:247], s[18:19]
	ds_bpermute_b32 v188, v203, v204
	ds_bpermute_b32 v189, v203, v206
	v_lshlrev_b32_e32 v206, 1, v185
	s_waitcnt lgkmcnt(0)
	v_add_u32_e32 v250, 0xfffff040, v206
	v_cndmask_b32_e64 v250, v206, v250, s[40:41]
	v_cndmask_b32_e64 v248, v186, v188, s[40:41]
	v_cndmask_b32_e64 v249, v187, v189, s[40:41]
	global_store_dwordx2 v250, v[248:249], s[18:19]
	v_cndmask_b32_e64 v246, v188, v186, s[40:41]
	v_cndmask_b32_e64 v247, v189, v187, s[40:41]
	v_mul_f32_e32 v119, v119, v119
	v_mul_f32_e32 v127, v127, v127
	v_mul_f32_e32 v129, v129, v129
	v_fmac_f32_e32 v119, v118, v118
	v_mul_f32_e32 v118, v121, v121
	v_fmac_f32_e32 v129, v128, v128
	v_fmac_f32_e32 v118, v120, v120
	v_mul_f32_e32 v115, v115, v115
	v_fmac_f32_e32 v127, v126, v126
	v_add_f32_e32 v118, v119, v118
	v_fmac_f32_e32 v115, v114, v114
	v_mul_f32_e32 v114, v117, v117
	v_add_f32_e32 v117, v127, v129
	v_add_f32_e32 v117, v117, v118
	v_xor_b32_e32 v118, 1, v199
	v_cmp_lt_i32_e32 vcc, v118, v183
	v_mul_f32_e32 v123, v123, v123
	v_mul_f32_e32 v125, v125, v125
	v_cndmask_b32_e32 v118, v199, v118, vcc
	v_lshlrev_b32_e32 v190, 2, v118
	ds_bpermute_b32 v118, v190, v117
	v_fmac_f32_e32 v114, v116, v116
	v_fmac_f32_e32 v125, v124, v124
	v_fmac_f32_e32 v123, v122, v122
	v_add_f32_e32 v114, v115, v114
	s_waitcnt lgkmcnt(0)
	v_add_f32_e32 v116, v117, v118
	v_xor_b32_e32 v117, 2, v199
	v_cmp_lt_i32_e32 vcc, v117, v183
	v_add_f32_e32 v115, v123, v125
	v_add_f32_e32 v115, v115, v114
	v_cndmask_b32_e32 v117, v199, v117, vcc
	v_lshlrev_b32_e32 v191, 2, v117
	ds_bpermute_b32 v117, v191, v116
	ds_bpermute_b32 v118, v190, v115
	s_waitcnt lgkmcnt(1)
	v_add_f32_e32 v114, v116, v117
	s_waitcnt lgkmcnt(0)
	v_add_f32_e32 v117, v115, v118
	ds_bpermute_b32 v118, v191, v117
	v_xor_b32_e32 v116, 4, v199
	v_cmp_lt_i32_e32 vcc, v116, v183
	s_nop 1
	v_cndmask_b32_e32 v115, v199, v116, vcc
	v_lshlrev_b32_e32 v204, 2, v115
	s_waitcnt lgkmcnt(0)
	v_add_f32_e32 v116, v117, v118
	ds_bpermute_b32 v115, v204, v114
	ds_bpermute_b32 v117, v204, v116
	v_add_u32_e32 v118, 0x1040, v206
	v_cndmask_b32_e64 v118, v206, v118, s[38:39]
	global_store_dwordx2 v118, v[246:247], s[18:19]
	s_and_saveexec_b64 s[22:23], s[42:43]
	s_cbranch_execz .LBB0_1939
	s_waitcnt lgkmcnt(1)
	v_add_f32_e32 v114, v114, v115
	s_waitcnt lgkmcnt(0)
	v_add_f32_e32 v115, v116, v117
	ds_write2_b32 v194, v114, v115 offset1:8

; #define PG8_STAGE(bufoff, gbase, voff) do { _Pragma("unroll") for (int _i = 0; _i < 2; ++_i) \
;         __builtin_amdgcn_global_load_lds((const unsigned*)((const char*)(gbase) + (voff)[_i]), (LAS unsigned*)(lds + (bufoff) + ldsw + _i * 8192), 16, 0, 0); } while (0)
; #define PG8_LDA(dst, b, h) do { _Pragma("unroll") for (int m = 0; m < 4; ++m) _Pragma("unroll") for (int k = 0; k < 2; ++k) dst[m][k] = *(const LAS bf16x8*)(lds + PG8_SA(b, h) + aoff + m * 2048 + k * 1024); } while (0)
; #define PG8_LDB(dst, b, h) do { _Pragma("unroll") for (int n = 0; n < 2; ++n) _Pragma("unroll") for (int k = 0; k < 2; ++k) dst[n][k] = *(const LAS bf16x8*)(lds + PG8_SB(b, h) + boff + n * 2048 + k * 1024); } while (0)
; template <class Epi, class Sched, bool ALIGN_EPI = false, bool SP2 = false>
; __device__ __forceinline__ void gemm_phase(LAS unsigned char* lds, const Gemm g, const Sched& S, const Epi& E) {
;     ...
;         for (int t = 0; t < nt; t += 2) {
;             const bool last = (t == nt - 2);
;             const char* a1 = cA + (size_t)(t + 1) * kstep;
;             const char* a2 = last ? nA : cA + (size_t)(t + 2) * kstep; const char* b2 = last ? nB : cB + (size_t)(t + 2) * kstep;
;             const char* a3 = a2 + kstep; const char* b3 = b2 + kstep;
;             if (last && has_next) S.a_ready(nxt);
;             if constexpr (SP2) {
;             PG8_LDB(B0, 0, 0); PG8_LDB(B1, 0, 1); PG8_SCHED; PG8_LDA(At, 0, 0); PG8_STAGE(PG8_SA(1, 1), a1 + hstep, voffA);
;             PG8_WAIT_V(8); PG8_WAIT_L(0); PG8_BAR; PG8_MMA(0, 0, At, B0); PG8_MMA(0, 1, At, B1); PG8_BAR; PG8_SCHED;
;             PG8_LDA(At, 0, 1); PG8_STAGE(PG8_SB(0, 0), b2, voffB); PG8_STAGE(PG8_SB(0, 1), b2 + hstepB, voffB); PG8_STAGE(PG8_SA(0, 0), a2, voffA);
;             PG8_WAIT_V(8); PG8_WAIT_L(0); PG8_BAR; PG8_MMA(1, 0, At, B0); PG8_MMA(1, 1, At, B1); PG8_BAR; PG8_SCHED;
;             PG8_LDB(B0, 1, 0); PG8_LDB(B1, 1, 1); PG8_SCHED; PG8_LDA(At, 1, 0); PG8_STAGE(PG8_SA(0, 1), a2 + hstep, voffA);
;             PG8_WAIT_V(8); PG8_WAIT_L(0); PG8_BAR; PG8_MMA(0, 0, At, B0); PG8_MMA(0, 1, At, B1); PG8_BAR; PG8_SCHED;
;             PG8_LDA(At, 1, 1); PG8_STAGE(PG8_SB(1, 0), b3, voffB); PG8_STAGE(PG8_SB(1, 1), b3 + hstepB, voffB); PG8_STAGE(PG8_SA(1, 0), a3, voffA);
;             PG8_WAIT_V(8); PG8_WAIT_L(0); PG8_BAR; PG8_MMA(1, 0, At, B0); PG8_MMA(1, 1, At, B1); PG8_BAR; PG8_SCHED;
.LBB0_2766:
	ds_read_b128 v[50:53], v196
	ds_read_b128 v[54:57], v196 offset:1024
	ds_read_b128 v[138:141], v196 offset:2048
	ds_read_b128 v[142:145], v196 offset:3072
	ds_read_b128 v[146:149], v197
	ds_read_b128 v[150:153], v197 offset:1024
	ds_read_b128 v[174:177], v197 offset:2048
	ds_read_b128 v[178:181], v197 offset:3072
	s_add_u32 s24, s22, 0xfff80080
	s_addc_u32 s25, s23, -1
	s_cmp_eq_u32 s55, 28
	s_cselect_b32 s35, s3, s25
	s_cselect_b32 s34, s15, s24
	s_cselect_b32 s25, s13, s54
	s_cselect_b32 s24, s21, s53
	s_add_i32 m0, s28, 0xc000
	ds_read_b128 v[182:185], v198
	ds_read_b128 v[186:189], v198 offset:1024
	ds_read_b128 v[202:205], v198 offset:2048
	ds_read_b128 v[206:209], v198 offset:3072
	ds_read_b128 v[210:213], v198 offset:4096
	ds_read_b128 v[214:217], v198 offset:5120
	ds_read_b128 v[218:221], v198 offset:6144
	ds_read_b128 v[222:225], v198 offset:7168
	global_load_lds_dwordx4 v168, s[22:23]
	s_add_i32 m0, s28, 0xe000
	s_nop 0
	global_load_lds_dwordx4 v166, s[22:23]
	s_waitcnt vmcnt(8)
	s_waitcnt lgkmcnt(0)
	s_barrier
	s_waitcnt lgkmcnt(0)
	v_mfma_f32_16x16x32_bf16 v[134:137], v[50:53], v[182:185], v[134:137]
	v_mfma_f32_16x16x32_bf16 v[130:133], v[138:141], v[182:185], v[130:133]
	v_mfma_f32_16x16x32_bf16 v[118:121], v[50:53], v[202:205], v[118:121]
	v_mfma_f32_16x16x32_bf16 v[114:117], v[138:141], v[202:205], v[114:117]
	v_mfma_f32_16x16x32_bf16 v[102:105], v[50:53], v[210:213], v[102:105]
	v_mfma_f32_16x16x32_bf16 v[98:101], v[138:141], v[210:213], v[98:101]
	v_mfma_f32_16x16x32_bf16 v[86:89], v[50:53], v[218:221], v[86:89]
	v_mfma_f32_16x16x32_bf16 v[82:85], v[138:141], v[218:221], v[82:85]
	v_mfma_f32_16x16x32_bf16 v[134:137], v[54:57], v[186:189], v[134:137]
	v_mfma_f32_16x16x32_bf16 v[130:133], v[142:145], v[186:189], v[130:133]
	v_mfma_f32_16x16x32_bf16 v[118:121], v[54:57], v[206:209], v[118:121]
	v_mfma_f32_16x16x32_bf16 v[114:117], v[142:145], v[206:209], v[114:117]
	v_mfma_f32_16x16x32_bf16 v[102:105], v[54:57], v[214:217], v[102:105]
	v_mfma_f32_16x16x32_bf16 v[98:101], v[142:145], v[214:217], v[98:101]
	v_mfma_f32_16x16x32_bf16 v[86:89], v[54:57], v[222:225], v[86:89]
	v_mfma_f32_16x16x32_bf16 v[82:85], v[142:145], v[222:225], v[82:85]
	v_mfma_f32_16x16x32_bf16 v[126:129], v[146:149], v[182:185], v[126:129]
	v_mfma_f32_16x16x32_bf16 v[122:125], v[174:177], v[182:185], v[122:125]
	v_mfma_f32_16x16x32_bf16 v[110:113], v[146:149], v[202:205], v[110:113]
	v_mfma_f32_16x16x32_bf16 v[106:109], v[174:177], v[202:205], v[106:109]
	v_mfma_f32_16x16x32_bf16 v[94:97], v[146:149], v[210:213], v[94:97]
	v_mfma_f32_16x16x32_bf16 v[90:93], v[174:177], v[210:213], v[90:93]
	v_mfma_f32_16x16x32_bf16 v[78:81], v[146:149], v[218:221], v[78:81]
	v_mfma_f32_16x16x32_bf16 v[74:77], v[174:177], v[218:221], v[74:77]
	v_mfma_f32_16x16x32_bf16 v[126:129], v[150:153], v[186:189], v[126:129]
	v_mfma_f32_16x16x32_bf16 v[122:125], v[178:181], v[186:189], v[122:125]
	v_mfma_f32_16x16x32_bf16 v[110:113], v[150:153], v[206:209], v[110:113]
	v_mfma_f32_16x16x32_bf16 v[106:109], v[178:181], v[206:209], v[106:109]
	v_mfma_f32_16x16x32_bf16 v[94:97], v[150:153], v[214:217], v[94:97]
	v_mfma_f32_16x16x32_bf16 v[90:93], v[178:181], v[214:217], v[90:93]
	v_mfma_f32_16x16x32_bf16 v[78:81], v[150:153], v[222:225], v[78:81]
	v_mfma_f32_16x16x32_bf16 v[74:77], v[178:181], v[222:225], v[74:77]
	s_barrier
	s_add_i32 s56, s51, s27
	s_mov_b32 m0, s56
	ds_read_b128 v[182:185], v198 offset:16384
	ds_read_b128 v[186:189], v198 offset:17408
	ds_read_b128 v[202:205], v198 offset:18432
	ds_read_b128 v[206:209], v198 offset:19456
	ds_read_b128 v[210:213], v198 offset:20480
	ds_read_b128 v[214:217], v198 offset:21504
	ds_read_b128 v[218:221], v198 offset:22528
	ds_read_b128 v[222:225], v198 offset:23552
	global_load_lds_dwordx4 v156, s[24:25]
	s_add_i32 m0, s56, 0x2000
	s_add_u32 s56, s24, 0x20000
	v_lshl_add_u64 v[226:227], s[24:25], 0, v[160:161]
	s_addc_u32 s57, s25, 0
	s_add_i32 s58, s52, s27
	global_load_lds_dwordx4 v160, s[24:25]
	s_mov_b32 m0, s58
	v_lshl_add_u64 v[230:231], s[34:35], 0, v[158:159]
	global_load_lds_dwordx4 v156, s[56:57]
	s_add_i32 m0, s58, 0x2000
	s_nop 0
	global_load_lds_dwordx4 v160, s[56:57]
	v_lshl_add_u64 v[228:229], s[34:35], 0, v[154:155]
	s_mov_b32 m0, s28
	s_nop 0
	global_load_lds_dwordx4 v154, s[34:35]
	s_mov_b32 m0, s29
	s_nop 0
	global_load_lds_dwordx4 v158, s[34:35]
	s_waitcnt vmcnt(8)
	s_waitcnt lgkmcnt(0)
	s_barrier
	s_waitcnt lgkmcnt(0)
	v_mfma_f32_16x16x32_bf16 v[70:73], v[50:53], v[182:185], v[70:73]
	v_mfma_f32_16x16x32_bf16 v[66:69], v[138:141], v[182:185], v[66:69]
	v_mfma_f32_16x16x32_bf16 v[46:49], v[50:53], v[202:205], v[46:49]
	v_mfma_f32_16x16x32_bf16 v[42:45], v[138:141], v[202:205], v[42:45]
	v_mfma_f32_16x16x32_bf16 v[30:33], v[50:53], v[210:213], v[30:33]
	v_mfma_f32_16x16x32_bf16 v[26:29], v[138:141], v[210:213], v[26:29]
	v_mfma_f32_16x16x32_bf16 v[14:17], v[50:53], v[218:221], v[14:17]
	v_mfma_f32_16x16x32_bf16 v[10:13], v[138:141], v[218:221], v[10:13]
	v_mfma_f32_16x16x32_bf16 v[70:73], v[54:57], v[186:189], v[70:73]
	v_mfma_f32_16x16x32_bf16 v[66:69], v[142:145], v[186:189], v[66:69]
	v_mfma_f32_16x16x32_bf16 v[46:49], v[54:57], v[206:209], v[46:49]
	v_mfma_f32_16x16x32_bf16 v[42:45], v[142:145], v[206:209], v[42:45]
	v_mfma_f32_16x16x32_bf16 v[30:33], v[54:57], v[214:217], v[30:33]
	v_mfma_f32_16x16x32_bf16 v[26:29], v[142:145], v[214:217], v[26:29]
	v_mfma_f32_16x16x32_bf16 v[14:17], v[54:57], v[222:225], v[14:17]
	v_mfma_f32_16x16x32_bf16 v[10:13], v[142:145], v[222:225], v[10:13]
	v_mfma_f32_16x16x32_bf16 v[38:41], v[146:149], v[202:205], v[38:41]
	v_mfma_f32_16x16x32_bf16 v[34:37], v[174:177], v[202:205], v[34:37]
	v_mfma_f32_16x16x32_bf16 v[22:25], v[146:149], v[210:213], v[22:25]
	v_mfma_f32_16x16x32_bf16 v[18:21], v[174:177], v[210:213], v[18:21]
	v_mfma_f32_16x16x32_bf16 v[6:9], v[146:149], v[218:221], v[6:9]
	v_mfma_f32_16x16x32_bf16 v[2:5], v[174:177], v[218:221], v[2:5]
	v_mfma_f32_16x16x32_bf16 v[50:53], v[146:149], v[182:185], v[62:65]
	v_mfma_f32_16x16x32_bf16 v[54:57], v[174:177], v[182:185], v[58:61]
	v_mfma_f32_16x16x32_bf16 v[38:41], v[150:153], v[206:209], v[38:41]
	v_mfma_f32_16x16x32_bf16 v[34:37], v[178:181], v[206:209], v[34:37]
	v_mfma_f32_16x16x32_bf16 v[22:25], v[150:153], v[214:217], v[22:25]
	v_mfma_f32_16x16x32_bf16 v[18:21], v[178:181], v[214:217], v[18:21]
	v_mfma_f32_16x16x32_bf16 v[6:9], v[150:153], v[222:225], v[6:9]
	v_mfma_f32_16x16x32_bf16 v[2:5], v[178:181], v[222:225], v[2:5]
	v_mfma_f32_16x16x32_bf16 v[50:53], v[150:153], v[186:189], v[50:53]
	v_mfma_f32_16x16x32_bf16 v[54:57], v[178:181], v[186:189], v[54:57]
	s_barrier
; #define PG8_STAGE(bufoff, gbase, voff) do { _Pragma("unroll") for (int _i = 0; _i < 2; ++_i) \
;         __builtin_amdgcn_global_load_lds((const unsigned*)((const char*)(gbase) + (voff)[_i]), (LAS unsigned*)(lds + (bufoff) + ldsw + _i * 8192), 16, 0, 0); } while (0)
; #define PG8_LDA(dst, b, h) do { _Pragma("unroll") for (int m = 0; m < 4; ++m) _Pragma("unroll") for (int k = 0; k < 2; ++k) dst[m][k] = *(const LAS bf16x8*)(lds + PG8_SA(b, h) + aoff + m * 2048 + k * 1024); } while (0)
; #define PG8_LDB(dst, b, h) do { _Pragma("unroll") for (int n = 0; n < 2; ++n) _Pragma("unroll") for (int k = 0; k < 2; ++k) dst[n][k] = *(const LAS bf16x8*)(lds + PG8_SB(b, h) + boff + n * 2048 + k * 1024); } while (0)
; template <class Epi, class Sched, bool ALIGN_EPI = false, bool SP2 = false>
; __device__ __forceinline__ void gemm_phase(LAS unsigned char* lds, const Gemm g, const Sched& S, const Epi& E) {
;     ...
;         for (int t = 0; t < nt; t += 2) {
;             const bool last = (t == nt - 2);
;             const char* a1 = cA + (size_t)(t + 1) * kstep;
;             const char* a2 = last ? nA : cA + (size_t)(t + 2) * kstep; const char* b2 = last ? nB : cB + (size_t)(t + 2) * kstep;
;             const char* a3 = a2 + kstep; const char* b3 = b2 + kstep;
;             if (last && has_next) S.a_ready(nxt);
;             if constexpr (SP2) {
;             PG8_LDB(B0, 0, 0); PG8_LDB(B1, 0, 1); PG8_SCHED; PG8_LDA(At, 0, 0); PG8_STAGE(PG8_SA(1, 1), a1 + hstep, voffA);
;             PG8_WAIT_V(8); PG8_WAIT_L(0); PG8_BAR; PG8_MMA(0, 0, At, B0); PG8_MMA(0, 1, At, B1); PG8_BAR; PG8_SCHED;
;             PG8_LDA(At, 0, 1); PG8_STAGE(PG8_SB(0, 0), b2, voffB); PG8_STAGE(PG8_SB(0, 1), b2 + hstepB, voffB); PG8_STAGE(PG8_SA(0, 0), a2, voffA);
;             PG8_WAIT_V(8); PG8_WAIT_L(0); PG8_BAR; PG8_MMA(1, 0, At, B0); PG8_MMA(1, 1, At, B1); PG8_BAR; PG8_SCHED;
;             PG8_LDB(B0, 1, 0); PG8_LDB(B1, 1, 1); PG8_SCHED; PG8_LDA(At, 1, 0); PG8_STAGE(PG8_SA(0, 1), a2 + hstep, voffA);
;             PG8_WAIT_V(8); PG8_WAIT_L(0); PG8_BAR; PG8_MMA(0, 0, At, B0); PG8_MMA(0, 1, At, B1); PG8_BAR; PG8_SCHED;
;             PG8_LDA(At, 1, 1); PG8_STAGE(PG8_SB(1, 0), b3, voffB); PG8_STAGE(PG8_SB(1, 1), b3 + hstepB, voffB); PG8_STAGE(PG8_SA(1, 0), a3, voffA);
;             PG8_WAIT_V(8); PG8_WAIT_L(0); PG8_BAR; PG8_MMA(1, 0, At, B0); PG8_MMA(1, 1, At, B1); PG8_BAR; PG8_SCHED;
	s_add_i32 s56, 0, 0x18000
	s_add_i32 s57, 0, 0x1c000
	v_add_u32_e32 v142, s56, v1
	v_add_u32_e32 v162, s57, v1
	ds_read_b128 v[58:61], v142
	ds_read_b128 v[62:65], v142 offset:1024
	ds_read_b128 v[138:141], v142 offset:2048
	ds_read_b128 v[142:145], v142 offset:3072
	ds_read_b128 v[146:149], v162
	ds_read_b128 v[150:153], v162 offset:1024
	ds_read_b128 v[174:177], v162 offset:2048
	ds_read_b128 v[178:181], v162 offset:3072
	s_add_u32 s34, s34, 0x80000
	s_addc_u32 s35, s35, 0
	s_mov_b32 m0, s30
	ds_read_b128 v[182:185], v198 offset:32768
	ds_read_b128 v[186:189], v198 offset:33792
	ds_read_b128 v[202:205], v198 offset:34816
	ds_read_b128 v[206:209], v198 offset:35840
	ds_read_b128 v[210:213], v198 offset:36864
	ds_read_b128 v[214:217], v198 offset:37888
	ds_read_b128 v[218:221], v198 offset:38912
	ds_read_b128 v[222:225], v198 offset:39936
	global_load_lds_dwordx4 v154, s[34:35]
	s_mov_b32 m0, s31
	s_nop 0
	global_load_lds_dwordx4 v158, s[34:35]
	s_waitcnt vmcnt(8)
	s_waitcnt lgkmcnt(0)
	s_barrier
	s_waitcnt lgkmcnt(0)
	v_mfma_f32_16x16x32_bf16 v[134:137], v[58:61], v[182:185], v[134:137]
	v_mfma_f32_16x16x32_bf16 v[130:133], v[138:141], v[182:185], v[130:133]
	v_mfma_f32_16x16x32_bf16 v[118:121], v[58:61], v[202:205], v[118:121]
	v_mfma_f32_16x16x32_bf16 v[114:117], v[138:141], v[202:205], v[114:117]
	v_mfma_f32_16x16x32_bf16 v[102:105], v[58:61], v[210:213], v[102:105]
	v_mfma_f32_16x16x32_bf16 v[98:101], v[138:141], v[210:213], v[98:101]
	v_mfma_f32_16x16x32_bf16 v[86:89], v[58:61], v[218:221], v[86:89]
	v_mfma_f32_16x16x32_bf16 v[82:85], v[138:141], v[218:221], v[82:85]
	v_mfma_f32_16x16x32_bf16 v[134:137], v[62:65], v[186:189], v[134:137]
	v_mfma_f32_16x16x32_bf16 v[130:133], v[142:145], v[186:189], v[130:133]
	v_mfma_f32_16x16x32_bf16 v[118:121], v[62:65], v[206:209], v[118:121]
	v_mfma_f32_16x16x32_bf16 v[114:117], v[142:145], v[206:209], v[114:117]
	v_mfma_f32_16x16x32_bf16 v[102:105], v[62:65], v[214:217], v[102:105]
	v_mfma_f32_16x16x32_bf16 v[98:101], v[142:145], v[214:217], v[98:101]
	v_mfma_f32_16x16x32_bf16 v[86:89], v[62:65], v[222:225], v[86:89]
	v_mfma_f32_16x16x32_bf16 v[82:85], v[142:145], v[222:225], v[82:85]
	v_mfma_f32_16x16x32_bf16 v[126:129], v[146:149], v[182:185], v[126:129]
	v_mfma_f32_16x16x32_bf16 v[122:125], v[174:177], v[182:185], v[122:125]
	v_mfma_f32_16x16x32_bf16 v[110:113], v[146:149], v[202:205], v[110:113]
	v_mfma_f32_16x16x32_bf16 v[106:109], v[174:177], v[202:205], v[106:109]
	v_mfma_f32_16x16x32_bf16 v[94:97], v[146:149], v[210:213], v[94:97]
	v_mfma_f32_16x16x32_bf16 v[90:93], v[174:177], v[210:213], v[90:93]
	v_mfma_f32_16x16x32_bf16 v[78:81], v[146:149], v[218:221], v[78:81]
	v_mfma_f32_16x16x32_bf16 v[74:77], v[174:177], v[218:221], v[74:77]
	v_mfma_f32_16x16x32_bf16 v[126:129], v[150:153], v[186:189], v[126:129]
	v_mfma_f32_16x16x32_bf16 v[122:125], v[178:181], v[186:189], v[122:125]
	v_mfma_f32_16x16x32_bf16 v[110:113], v[150:153], v[206:209], v[110:113]
	v_mfma_f32_16x16x32_bf16 v[106:109], v[178:181], v[206:209], v[106:109]
	v_mfma_f32_16x16x32_bf16 v[94:97], v[150:153], v[214:217], v[94:97]
	v_mfma_f32_16x16x32_bf16 v[90:93], v[178:181], v[214:217], v[90:93]
	v_mfma_f32_16x16x32_bf16 v[78:81], v[150:153], v[222:225], v[78:81]
	v_mfma_f32_16x16x32_bf16 v[74:77], v[178:181], v[222:225], v[74:77]
	s_barrier
	s_add_u32 s98, s24, 0x80
	s_addc_u32 s99, s25, 0
	s_add_i32 s34, s56, s27
	s_mov_b32 m0, s34
	ds_read_b128 v[182:185], v198 offset:49152
	ds_read_b128 v[186:189], v198 offset:50176
	ds_read_b128 v[202:205], v198 offset:51200
	ds_read_b128 v[206:209], v198 offset:52224
	ds_read_b128 v[210:213], v198 offset:53248
	ds_read_b128 v[214:217], v198 offset:54272
	ds_read_b128 v[218:221], v198 offset:55296
	ds_read_b128 v[222:225], v198 offset:56320
	global_load_lds_dwordx4 v156, s[98:99]
	s_add_i32 m0, s34, 0x2000
	s_add_u32 s24, s24, 0x20080
	v_lshl_add_u64 v[190:191], v[226:227], 0, s[8:9]
	s_addc_u32 s25, s25, 0
	s_add_i32 s34, s57, s27
	global_load_lds_dwordx4 v[190:191], off
	s_mov_b32 m0, s34
	s_nop 0
	global_load_lds_dwordx4 v156, s[24:25]
	s_add_i32 m0, s34, 0x2000
	s_nop 0
	global_load_lds_dwordx4 v160, s[24:25]
	v_lshl_add_u64 v[190:191], v[228:229], 0, s[8:9]
	s_mov_b32 m0, s48
	s_nop 0
	global_load_lds_dwordx4 v[190:191], off
	v_lshl_add_u64 v[190:191], v[230:231], 0, s[8:9]
	s_mov_b32 m0, s49
	s_nop 0
	global_load_lds_dwordx4 v[190:191], off
	s_waitcnt vmcnt(8)
	s_waitcnt lgkmcnt(0)
	s_barrier
	s_waitcnt lgkmcnt(0)
	v_mfma_f32_16x16x32_bf16 v[70:73], v[58:61], v[182:185], v[70:73]
	v_mfma_f32_16x16x32_bf16 v[66:69], v[138:141], v[182:185], v[66:69]
	v_mfma_f32_16x16x32_bf16 v[46:49], v[58:61], v[202:205], v[46:49]
	v_mfma_f32_16x16x32_bf16 v[42:45], v[138:141], v[202:205], v[42:45]
	v_mfma_f32_16x16x32_bf16 v[30:33], v[58:61], v[210:213], v[30:33]
	v_mfma_f32_16x16x32_bf16 v[26:29], v[138:141], v[210:213], v[26:29]
	v_mfma_f32_16x16x32_bf16 v[14:17], v[58:61], v[218:221], v[14:17]
	v_mfma_f32_16x16x32_bf16 v[10:13], v[138:141], v[218:221], v[10:13]
	v_mfma_f32_16x16x32_bf16 v[70:73], v[62:65], v[186:189], v[70:73]
	v_mfma_f32_16x16x32_bf16 v[66:69], v[142:145], v[186:189], v[66:69]
	v_mfma_f32_16x16x32_bf16 v[46:49], v[62:65], v[206:209], v[46:49]
	v_mfma_f32_16x16x32_bf16 v[42:45], v[142:145], v[206:209], v[42:45]
	v_mfma_f32_16x16x32_bf16 v[30:33], v[62:65], v[214:217], v[30:33]
	v_mfma_f32_16x16x32_bf16 v[26:29], v[142:145], v[214:217], v[26:29]
	v_mfma_f32_16x16x32_bf16 v[14:17], v[62:65], v[222:225], v[14:17]
	v_mfma_f32_16x16x32_bf16 v[10:13], v[142:145], v[222:225], v[10:13]
	v_mfma_f32_16x16x32_bf16 v[50:53], v[146:149], v[182:185], v[50:53]
	v_mfma_f32_16x16x32_bf16 v[62:65], v[150:153], v[186:189], v[50:53]
	v_mfma_f32_16x16x32_bf16 v[50:53], v[174:177], v[182:185], v[54:57]
	v_mfma_f32_16x16x32_bf16 v[38:41], v[146:149], v[202:205], v[38:41]
	v_mfma_f32_16x16x32_bf16 v[34:37], v[174:177], v[202:205], v[34:37]
	v_mfma_f32_16x16x32_bf16 v[22:25], v[146:149], v[210:213], v[22:25]
	v_mfma_f32_16x16x32_bf16 v[18:21], v[174:177], v[210:213], v[18:21]
	v_mfma_f32_16x16x32_bf16 v[6:9], v[146:149], v[218:221], v[6:9]
	v_mfma_f32_16x16x32_bf16 v[2:5], v[174:177], v[218:221], v[2:5]
	v_mfma_f32_16x16x32_bf16 v[58:61], v[178:181], v[186:189], v[50:53]
	v_mfma_f32_16x16x32_bf16 v[38:41], v[150:153], v[206:209], v[38:41]
	v_mfma_f32_16x16x32_bf16 v[34:37], v[178:181], v[206:209], v[34:37]
	v_mfma_f32_16x16x32_bf16 v[22:25], v[150:153], v[214:217], v[22:25]
	v_mfma_f32_16x16x32_bf16 v[18:21], v[178:181], v[214:217], v[18:21]
	v_mfma_f32_16x16x32_bf16 v[6:9], v[150:153], v[222:225], v[6:9]
	v_mfma_f32_16x16x32_bf16 v[2:5], v[178:181], v[222:225], v[2:5]
	s_barrier
; #define LAS __attribute__((address_space(3)))
;     __device__ __forceinline__ void operator()(const f32x4 (&acc)[2][2][4][2], const Unit& u, int wr, int wc, int fr, int fq) const {
;         const int s = u.pm >> 5, lane = fq * 16 + fr, rr = lane >> 3, pc = lane & 7;
;         const float* __restrict__ xi = xin + (size_t)u.pm * BM * DM; float* __restrict__ xo = xout + (size_t)u.pm * BM * DM; bf16_t* __restrict__ ho = Hn + (size_t)u.pm * BM * DM;
;         LAS unsigned char* st = lds_epi + (wr * 4 + wc) * 2304;
;         LAS float* sst = (LAS float*)(lds_epi + 18432 + (wr * 4 + wc) * 512);
;         const int colr = u.pn * BM + wc * 64 + 4 * pc;
;         const unsigned eb = (unsigned)((wr * 64 + rr) * DM + colr);
;         f32x4 gv[2], gsn[2];
; #pragma unroll
;         for (int bj = 0; bj < 2; ++bj) { gv[bj] = *(const f32x4*)(gate + (size_t)s * MODW + colr + bj * 32) * (0.5f * GS2);
;             if (!PLAIN) gsn[bj] = *(const f32x4*)(gnext + colr + bj * 32) * (*(const f32x4*)(scnext + (size_t)s * MODW + colr + bj * 32) + 1.0f); else gsn[bj] = gv[bj]; }
;         const unsigned wr_off = (unsigned)(fr * 144 + 16 * fq), rd_off = (unsigned)(rr * 144 + pc * 16);
;         const bool odd = (rr & 1) != 0;
;         f32x4 xb[2][2][2];
;     ...
;         ERN_LOADX(0);
; #pragma unroll
;         for (int g = 0; g < 8; ++g) { const int ai = g >> 2, m = g & 3;
;             if (g + 1 < 8) ERN_LOADX(g + 1);
;             float sq0 = 0.f, sq1 = 0.f; u32x2 hw[2][2];
; #pragma unroll
;             for (int bj = 0; bj < 2; ++bj) {
;                 *(LAS f32x4*)(st + wr_off) = acc[ai][bj][m][0]; *(LAS f32x4*)(st + wr_off + 64) = acc[ai][bj][m][1];
;                 const f32x4 a0 = *(const LAS f32x4*)(st + rd_off), a1 = *(const LAS f32x4*)(st + rd_off + 8 * 144);
;                 { const f32x4 xv = xb[g & 1][bj][0] + gv[bj] * a0; __builtin_nontemporal_store(xv, (f32x4*)((char*)xo + 4u * ERN_EOFF(g, bj, 0)));
;                   sq0 += (xv.x * xv.x + xv.y * xv.y) + (xv.z * xv.z + xv.w * xv.w);
;                   const f32x4 hv = xv * gsn[bj]; hw[bj][0].x = cvt_pk_bf16(hv.x, hv.y); hw[bj][0].y = cvt_pk_bf16(hv.z, hv.w); }
;                 { const f32x4 xv = xb[g & 1][bj][1] + gv[bj] * a1; __builtin_nontemporal_store(xv, (f32x4*)((char*)xo + 4u * ERN_EOFF(g, bj, 1)));
;                   sq1 += (xv.x * xv.x + xv.y * xv.y) + (xv.z * xv.z + xv.w * xv.w);
	s_add_i32 s55, s55, 2
	s_add_u32 s53, s53, 0x100
	s_addc_u32 s54, s54, 0
	s_add_u32 s22, s22, 0x100
	s_addc_u32 s23, s23, 0
	s_cmp_lt_u32 s55, 30
	s_cbranch_scc1 .LBB0_2766
	s_setprio 0
	s_ashr_i32 s13, s2, 5
	s_ashr_i32 s3, s2, 31
	v_lshl_or_b32 v50, s20, 8, v192
	s_mul_hi_i32 s15, s13, 0x12000
	s_mul_i32 s13, s13, 0x12000
	s_add_u32 s20, s44, s13
	v_ashrrev_i32_e32 v51, 31, v50
	s_addc_u32 s21, s45, s15
	v_lshlrev_b64 v[52:53], 2, v[50:51]
	v_lshl_add_u64 v[138:139], s[20:21], 0, v[52:53]
	s_add_u32 s20, s46, s13
	s_addc_u32 s21, s47, s15
	v_lshl_add_u64 v[140:141], s[6:7], 0, v[52:53]
	v_lshl_add_u64 v[52:53], s[20:21], 0, v[52:53]
	s_lshl_b64 s[20:21], s[2:3], 21
	s_add_u32 s22, s90, s20
	v_add_u32_e32 v202, v50, v193
	s_addc_u32 s23, s91, s21
	v_lshlrev_b32_e32 v205, 2, v202
	global_load_dwordx4 v[54:57], v[138:139], off
	global_load_dwordx4 v[174:177], v[140:141], off
	global_load_dwordx4 v[178:181], v[52:53], off
	global_load_dwordx4 v[206:209], v[52:53], off offset:128
	global_load_dwordx4 v[186:189], v205, s[22:23]
	v_add_u32_e32 v50, 0x10000, v205
	global_load_dwordx4 v[210:213], v50, s[22:23]
	global_load_dwordx4 v[214:217], v[140:141], off offset:128
	s_nop 0
	global_load_dwordx4 v[50:53], v[138:139], off offset:128
	global_load_dwordx4 v[218:221], v205, s[22:23] offset:128
	v_add_u32_e32 v204, 0x10080, v205
	global_load_dwordx4 v[222:225], v204, s[22:23]
	v_add_u32_e32 v138, 0x20000, v205
	v_add_u32_e32 v162, 0x30000, v205
	v_add_u32_e32 v184, 0x20080, v205
	v_add_u32_e32 v182, 0x30080, v205
	global_load_dwordx4 v[150:153], v138, s[22:23]
	global_load_dwordx4 v[146:149], v162, s[22:23]
	global_load_dwordx4 v[142:145], v184, s[22:23]
	s_nop 0
	global_load_dwordx4 v[138:141], v182, s[22:23]
	s_andn2_b64 vcc, exec, s[10:11]
	s_cbranch_vccnz .Lalign_2769
	s_barrier
.Lalign_2769:
	ds_write_b128 v200, v[134:137]
	ds_write_b128 v200, v[130:133] offset:64
	v_and_b32_e32 v135, 64, v199
	ds_read_b128 v[130:133], v201
	ds_read_b128 v[226:229], v201 offset:1152
	v_xor_b32_e32 v134, 8, v199
	v_add_u32_e32 v183, 64, v135
	v_cmp_lt_i32_e32 vcc, v134, v183
	v_add_u32_e32 v185, 0x4000, v202
	v_lshlrev_b32_e32 v230, 2, v185
	v_cndmask_b32_e32 v134, v199, v134, vcc
	v_lshlrev_b32_e32 v203, 2, v134
	s_lshl_b64 s[20:21], s[2:3], 20
	s_add_u32 s20, s93, s20
	s_addc_u32 s21, s92, s21
	s_waitcnt vmcnt(0)
	v_pk_add_f32 v[134:135], v[180:181], 1.0 op_sel_hi:[1,0]
	v_pk_add_f32 v[136:137], v[178:179], 1.0 op_sel_hi:[1,0]
	v_pk_mul_f32 v[178:179], v[176:177], v[134:135]
	v_pk_mul_f32 v[180:181], v[174:175], v[136:137]
	s_waitcnt lgkmcnt(1)
	v_pk_fma_f32 v[134:135], v[54:55], v[130:131], v[186:187]
	s_waitcnt lgkmcnt(0)
	v_pk_fma_f32 v[130:131], v[54:55], v[226:227], v[210:211]
	v_pk_fma_f32 v[136:137], v[56:57], v[132:133], v[188:189]
	v_pk_fma_f32 v[132:133], v[56:57], v[228:229], v[212:213]
	v_pk_mul_f32 v[186:187], v[180:181], v[130:131]
	v_pk_add_f32 v[190:191], v[208:209], 1.0 op_sel_hi:[1,0]
	global_store_dwordx4 v205, v[134:137], s[22:23] nt
	v_pk_mul_f32 v[174:175], v[178:179], v[136:137]
	v_pk_mul_f32 v[176:177], v[180:181], v[134:135]
	v_pk_mul_f32 v[208:209], v[178:179], v[132:133]
	v_cvt_pk_bf16_f32 v188, v176, v177
	v_cvt_pk_bf16_f32 v189, v174, v175
	global_store_dwordx4 v230, v[130:133], s[22:23] nt
	v_cvt_pk_bf16_f32 v186, v186, v187
	v_cvt_pk_bf16_f32 v187, v208, v209
	ds_write_b128 v200, v[126:129]
	ds_write_b128 v200, v[122:125] offset:64
	ds_read_b128 v[122:125], v201
	v_pk_add_f32 v[126:127], v[206:207], 1.0 op_sel_hi:[1,0]
	ds_read_b128 v[206:209], v201 offset:1152
	v_pk_mul_f32 v[174:175], v[216:217], v[190:191]
	v_pk_mul_f32 v[176:177], v[214:215], v[126:127]
	s_waitcnt lgkmcnt(1)
	v_pk_fma_f32 v[128:129], v[52:53], v[124:125], v[220:221]
	v_pk_fma_f32 v[126:127], v[50:51], v[122:123], v[218:219]
	s_waitcnt lgkmcnt(0)
	v_pk_fma_f32 v[122:123], v[50:51], v[206:207], v[222:223]
	v_pk_mul_f32 v[190:191], v[174:175], v[128:129]
	v_pk_mul_f32 v[206:207], v[176:177], v[126:127]
	global_store_dwordx4 v205, v[126:129], s[22:23] offset:128 nt
	v_cvt_pk_bf16_f32 v206, v206, v207
	v_cvt_pk_bf16_f32 v191, v190, v191
	ds_bpermute_b32 v190, v203, v206
	ds_bpermute_b32 v191, v203, v191
	v_pk_fma_f32 v[124:125], v[52:53], v[208:209], v[224:225]
	v_pk_mul_f32 v[206:207], v[176:177], v[122:123]
	global_store_dwordx4 v204, v[122:125], s[22:23] nt
	v_cvt_pk_bf16_f32 v204, v206, v207
	v_lshlrev_b32_e32 v207, 1, v202
	v_pk_mul_f32 v[208:209], v[174:175], v[124:125]
	s_nop 0
	v_cvt_pk_bf16_f32 v206, v208, v209
	s_waitcnt lgkmcnt(0)
	v_add_u32_e32 v250, 0xfffff040, v207
	v_cndmask_b32_e64 v250, v207, v250, s[38:39]
	v_cndmask_b32_e64 v248, v188, v190, s[38:39]
	v_cndmask_b32_e64 v249, v189, v191, s[38:39]
	global_store_dwordx2 v250, v[248:249], s[20:21]
	v_cndmask_b32_e64 v246, v190, v188, s[38:39]
	v_cndmask_b32_e64 v247, v191, v189, s[38:39]
	s_waitcnt lgkmcnt(1)
	v_add_u32_e32 v190, 0x1040, v207
	v_cndmask_b32_e64 v190, v207, v190, s[36:37]
	global_store_dwordx2 v190, v[246:247], s[20:21]
	ds_bpermute_b32 v188, v203, v204
	ds_bpermute_b32 v189, v203, v206
	v_lshlrev_b32_e32 v206, 1, v185
	s_and_saveexec_b64 s[24:25], s[38:39]
	s_xor_b64 s[24:25], exec, s[24:25]
	s_mov_b64 s[58:59], s[70:71]
	s_cbranch_execz .LBB0_2775
	v_lshlrev_b32_e32 v206, 1, v185
	v_add_u32_e32 v185, 0xfffff040, v206
	s_waitcnt lgkmcnt(0)
	global_store_dwordx2 v185, v[188:189], s[20:21]

; #define PG8_STAGE(bufoff, gbase, voff) do { _Pragma("unroll") for (int _i = 0; _i < 2; ++_i) \
;         __builtin_amdgcn_global_load_lds((const unsigned*)((const char*)(gbase) + (voff)[_i]), (LAS unsigned*)(lds + (bufoff) + ldsw + _i * 8192), 16, 0, 0); } while (0)
; #define PG8_LDA(dst, b, h) do { _Pragma("unroll") for (int m = 0; m < 4; ++m) _Pragma("unroll") for (int k = 0; k < 2; ++k) dst[m][k] = *(const LAS bf16x8*)(lds + PG8_SA(b, h) + aoff + m * 2048 + k * 1024); } while (0)
; #define PG8_LDB(dst, b, h) do { _Pragma("unroll") for (int n = 0; n < 2; ++n) _Pragma("unroll") for (int k = 0; k < 2; ++k) dst[n][k] = *(const LAS bf16x8*)(lds + PG8_SB(b, h) + boff + n * 2048 + k * 1024); } while (0)
; template <class Epi, class Sched, bool ALIGN_EPI = false, bool SP2 = false>
; __device__ __forceinline__ void gemm_phase(LAS unsigned char* lds, const Gemm g, const Sched& S, const Epi& E) {
;     ...
;         for (int t = 0; t < nt; t += 2) {
;             const bool last = (t == nt - 2);
;             const char* a1 = cA + (size_t)(t + 1) * kstep;
;             const char* a2 = last ? nA : cA + (size_t)(t + 2) * kstep; const char* b2 = last ? nB : cB + (size_t)(t + 2) * kstep;
;             const char* a3 = a2 + kstep; const char* b3 = b2 + kstep;
;             if (last && has_next) S.a_ready(nxt);
;             if constexpr (SP2) {
;             PG8_LDB(B0, 0, 0); PG8_LDB(B1, 0, 1); PG8_SCHED; PG8_LDA(At, 0, 0); PG8_STAGE(PG8_SA(1, 1), a1 + hstep, voffA);
;             PG8_WAIT_V(8); PG8_WAIT_L(0); PG8_BAR; PG8_MMA(0, 0, At, B0); PG8_MMA(0, 1, At, B1); PG8_BAR; PG8_SCHED;
;             PG8_LDA(At, 0, 1); PG8_STAGE(PG8_SB(0, 0), b2, voffB); PG8_STAGE(PG8_SB(0, 1), b2 + hstepB, voffB); PG8_STAGE(PG8_SA(0, 0), a2, voffA);
;             PG8_WAIT_V(8); PG8_WAIT_L(0); PG8_BAR; PG8_MMA(1, 0, At, B0); PG8_MMA(1, 1, At, B1); PG8_BAR; PG8_SCHED;
;             PG8_LDB(B0, 1, 0); PG8_LDB(B1, 1, 1); PG8_SCHED; PG8_LDA(At, 1, 0); PG8_STAGE(PG8_SA(0, 1), a2 + hstep, voffA);
;             PG8_WAIT_V(8); PG8_WAIT_L(0); PG8_BAR; PG8_MMA(0, 0, At, B0); PG8_MMA(0, 1, At, B1); PG8_BAR; PG8_SCHED;
;             PG8_LDA(At, 1, 1); PG8_STAGE(PG8_SB(1, 0), b3, voffB); PG8_STAGE(PG8_SB(1, 1), b3 + hstepB, voffB); PG8_STAGE(PG8_SA(1, 0), a3, voffA);
;             PG8_WAIT_V(8); PG8_WAIT_L(0); PG8_BAR; PG8_MMA(1, 0, At, B0); PG8_MMA(1, 1, At, B1); PG8_BAR; PG8_SCHED;
.LBB0_3002:
	ds_read_b128 v[152:155], v147
	ds_read_b128 v[156:159], v147 offset:1024
	ds_read_b128 v[160:163], v147 offset:2048
	ds_read_b128 v[164:167], v147 offset:3072
	ds_read_b128 v[168:171], v148
	ds_read_b128 v[172:175], v148 offset:1024
	ds_read_b128 v[176:179], v148 offset:2048
	ds_read_b128 v[180:183], v148 offset:3072
	s_add_u32 s16, s14, 0x100
	s_addc_u32 s17, s15, 0
	s_cmpk_eq_i32 s40, 0x54
	s_cselect_b32 s21, s11, s17
	s_cselect_b32 s20, s10, s16
	s_cselect_b32 s19, s3, s39
	s_cselect_b32 s18, s2, s13
	v_lshl_add_u64 v[216:217], s[14:15], 0, v[138:139]
	s_add_i32 m0, s24, 0xc000
	ds_read_b128 v[184:187], v149
	ds_read_b128 v[188:191], v149 offset:1024
	ds_read_b128 v[192:195], v149 offset:2048
	ds_read_b128 v[196:199], v149 offset:3072
	ds_read_b128 v[200:203], v149 offset:4096
	ds_read_b128 v[204:207], v149 offset:5120
	ds_read_b128 v[208:211], v149 offset:6144
	ds_read_b128 v[212:215], v149 offset:7168
	global_load_lds_dwordx4 v[216:217], off
	v_lshl_add_u64 v[216:217], s[14:15], 0, v[136:137]
	s_add_i32 m0, s24, 0xe000
	s_nop 0
	global_load_lds_dwordx4 v[216:217], off
	s_waitcnt vmcnt(8)
	s_waitcnt lgkmcnt(0)
	s_barrier
	s_waitcnt lgkmcnt(0)
	v_mfma_f32_16x16x32_bf16 v[124:127], v[152:155], v[184:187], v[124:127]
	v_mfma_f32_16x16x32_bf16 v[120:123], v[160:163], v[184:187], v[120:123]
	v_mfma_f32_16x16x32_bf16 v[112:115], v[152:155], v[192:195], v[112:115]
	v_mfma_f32_16x16x32_bf16 v[104:107], v[160:163], v[192:195], v[104:107]
	v_mfma_f32_16x16x32_bf16 v[92:95], v[152:155], v[200:203], v[92:95]
	v_mfma_f32_16x16x32_bf16 v[88:91], v[160:163], v[200:203], v[88:91]
	v_mfma_f32_16x16x32_bf16 v[76:79], v[152:155], v[208:211], v[76:79]
	v_mfma_f32_16x16x32_bf16 v[72:75], v[160:163], v[208:211], v[72:75]
	v_mfma_f32_16x16x32_bf16 v[124:127], v[156:159], v[188:191], v[124:127]
	v_mfma_f32_16x16x32_bf16 v[120:123], v[164:167], v[188:191], v[120:123]
	v_mfma_f32_16x16x32_bf16 v[112:115], v[156:159], v[196:199], v[112:115]
	v_mfma_f32_16x16x32_bf16 v[104:107], v[164:167], v[196:199], v[104:107]
	v_mfma_f32_16x16x32_bf16 v[92:95], v[156:159], v[204:207], v[92:95]
	v_mfma_f32_16x16x32_bf16 v[88:91], v[164:167], v[204:207], v[88:91]
	v_mfma_f32_16x16x32_bf16 v[76:79], v[156:159], v[212:215], v[76:79]
	v_mfma_f32_16x16x32_bf16 v[72:75], v[164:167], v[212:215], v[72:75]
	v_mfma_f32_16x16x32_bf16 v[116:119], v[168:171], v[184:187], v[116:119]
	v_mfma_f32_16x16x32_bf16 v[108:111], v[176:179], v[184:187], v[108:111]
	v_mfma_f32_16x16x32_bf16 v[100:103], v[168:171], v[192:195], v[100:103]
	v_mfma_f32_16x16x32_bf16 v[96:99], v[176:179], v[192:195], v[96:99]
	v_mfma_f32_16x16x32_bf16 v[84:87], v[168:171], v[200:203], v[84:87]
	v_mfma_f32_16x16x32_bf16 v[80:83], v[176:179], v[200:203], v[80:83]
	v_mfma_f32_16x16x32_bf16 v[68:71], v[168:171], v[208:211], v[68:71]
	v_mfma_f32_16x16x32_bf16 v[64:67], v[176:179], v[208:211], v[64:67]
	v_mfma_f32_16x16x32_bf16 v[116:119], v[172:175], v[188:191], v[116:119]
	v_mfma_f32_16x16x32_bf16 v[108:111], v[180:183], v[188:191], v[108:111]
	v_mfma_f32_16x16x32_bf16 v[100:103], v[172:175], v[196:199], v[100:103]
	v_mfma_f32_16x16x32_bf16 v[96:99], v[180:183], v[196:199], v[96:99]
	v_mfma_f32_16x16x32_bf16 v[84:87], v[172:175], v[204:207], v[84:87]
	v_mfma_f32_16x16x32_bf16 v[80:83], v[180:183], v[204:207], v[80:83]
	v_mfma_f32_16x16x32_bf16 v[68:71], v[172:175], v[212:215], v[68:71]
	v_mfma_f32_16x16x32_bf16 v[64:67], v[180:183], v[212:215], v[64:67]
	s_barrier
	s_add_i32 s14, s34, s23
	s_mov_b32 m0, s14
	ds_read_b128 v[184:187], v149 offset:16384
	ds_read_b128 v[188:191], v149 offset:17408
	ds_read_b128 v[192:195], v149 offset:18432
	ds_read_b128 v[196:199], v149 offset:19456
	ds_read_b128 v[200:203], v149 offset:20480
	ds_read_b128 v[204:207], v149 offset:21504
	ds_read_b128 v[208:211], v149 offset:22528
	ds_read_b128 v[212:215], v149 offset:23552
	global_load_lds_dwordx4 v130, s[18:19]
	s_add_i32 m0, s14, 0x2000
	s_add_u32 s14, s18, 0x58000
	v_lshl_add_u64 v[218:219], s[18:19], 0, v[134:135]
	s_addc_u32 s15, s19, 0
	s_add_i32 s41, s35, s23
	global_load_lds_dwordx4 v134, s[18:19]
	s_mov_b32 m0, s41
	s_nop 0
	global_load_lds_dwordx4 v130, s[14:15]
	s_add_i32 m0, s41, 0x2000
	s_nop 0
	global_load_lds_dwordx4 v134, s[14:15]
	s_mov_b32 m0, s24
	s_nop 0
	global_load_lds_dwordx4 v128, s[20:21]
	s_mov_b32 m0, s25
	s_nop 0
	global_load_lds_dwordx4 v132, s[20:21]
	s_waitcnt vmcnt(8)
	s_waitcnt lgkmcnt(0)
	s_barrier
	s_waitcnt lgkmcnt(0)
	v_mfma_f32_16x16x32_bf16 v[60:63], v[152:155], v[184:187], v[60:63]
	v_mfma_f32_16x16x32_bf16 v[56:59], v[160:163], v[184:187], v[56:59]
	v_mfma_f32_16x16x32_bf16 v[44:47], v[152:155], v[192:195], v[44:47]
	v_mfma_f32_16x16x32_bf16 v[40:43], v[160:163], v[192:195], v[40:43]
	v_mfma_f32_16x16x32_bf16 v[28:31], v[152:155], v[200:203], v[28:31]
	v_mfma_f32_16x16x32_bf16 v[24:27], v[160:163], v[200:203], v[24:27]
	v_mfma_f32_16x16x32_bf16 v[12:15], v[152:155], v[208:211], v[12:15]
	v_mfma_f32_16x16x32_bf16 v[8:11], v[160:163], v[208:211], v[8:11]
	v_mfma_f32_16x16x32_bf16 v[60:63], v[156:159], v[188:191], v[60:63]
	v_mfma_f32_16x16x32_bf16 v[56:59], v[164:167], v[188:191], v[56:59]
	v_mfma_f32_16x16x32_bf16 v[44:47], v[156:159], v[196:199], v[44:47]
	v_mfma_f32_16x16x32_bf16 v[40:43], v[164:167], v[196:199], v[40:43]
	v_mfma_f32_16x16x32_bf16 v[28:31], v[156:159], v[204:207], v[28:31]
	v_mfma_f32_16x16x32_bf16 v[24:27], v[164:167], v[204:207], v[24:27]
	v_mfma_f32_16x16x32_bf16 v[12:15], v[156:159], v[212:215], v[12:15]
	v_mfma_f32_16x16x32_bf16 v[8:11], v[164:167], v[212:215], v[8:11]
	v_mfma_f32_16x16x32_bf16 v[52:55], v[168:171], v[184:187], v[52:55]
	v_mfma_f32_16x16x32_bf16 v[48:51], v[176:179], v[184:187], v[48:51]
	v_mfma_f32_16x16x32_bf16 v[36:39], v[168:171], v[192:195], v[36:39]
	v_mfma_f32_16x16x32_bf16 v[32:35], v[176:179], v[192:195], v[32:35]
	v_mfma_f32_16x16x32_bf16 v[20:23], v[168:171], v[200:203], v[20:23]
	v_mfma_f32_16x16x32_bf16 v[16:19], v[176:179], v[200:203], v[16:19]
	v_mfma_f32_16x16x32_bf16 v[4:7], v[168:171], v[208:211], v[4:7]
	v_mfma_f32_16x16x32_bf16 v[0:3], v[176:179], v[208:211], v[0:3]
	v_mfma_f32_16x16x32_bf16 v[52:55], v[172:175], v[188:191], v[52:55]
	v_mfma_f32_16x16x32_bf16 v[48:51], v[180:183], v[188:191], v[48:51]
	v_mfma_f32_16x16x32_bf16 v[36:39], v[172:175], v[196:199], v[36:39]
	v_mfma_f32_16x16x32_bf16 v[32:35], v[180:183], v[196:199], v[32:35]
	v_mfma_f32_16x16x32_bf16 v[20:23], v[172:175], v[204:207], v[20:23]
	v_mfma_f32_16x16x32_bf16 v[16:19], v[180:183], v[204:207], v[16:19]
	v_mfma_f32_16x16x32_bf16 v[4:7], v[172:175], v[212:215], v[4:7]
	v_mfma_f32_16x16x32_bf16 v[0:3], v[180:183], v[212:215], v[0:3]
	s_barrier
; #define PG8_STAGE(bufoff, gbase, voff) do { _Pragma("unroll") for (int _i = 0; _i < 2; ++_i) \
;         __builtin_amdgcn_global_load_lds((const unsigned*)((const char*)(gbase) + (voff)[_i]), (LAS unsigned*)(lds + (bufoff) + ldsw + _i * 8192), 16, 0, 0); } while (0)
; #define PG8_LDA(dst, b, h) do { _Pragma("unroll") for (int m = 0; m < 4; ++m) _Pragma("unroll") for (int k = 0; k < 2; ++k) dst[m][k] = *(const LAS bf16x8*)(lds + PG8_SA(b, h) + aoff + m * 2048 + k * 1024); } while (0)
; #define PG8_LDB(dst, b, h) do { _Pragma("unroll") for (int n = 0; n < 2; ++n) _Pragma("unroll") for (int k = 0; k < 2; ++k) dst[n][k] = *(const LAS bf16x8*)(lds + PG8_SB(b, h) + boff + n * 2048 + k * 1024); } while (0)
; template <class Epi, class Sched, bool ALIGN_EPI = false, bool SP2 = false>
; __device__ __forceinline__ void gemm_phase(LAS unsigned char* lds, const Gemm g, const Sched& S, const Epi& E) {
;     ...
;         for (int t = 0; t < nt; t += 2) {
;             const bool last = (t == nt - 2);
;             const char* a1 = cA + (size_t)(t + 1) * kstep;
;             const char* a2 = last ? nA : cA + (size_t)(t + 2) * kstep; const char* b2 = last ? nB : cB + (size_t)(t + 2) * kstep;
;             const char* a3 = a2 + kstep; const char* b3 = b2 + kstep;
;             if (last && has_next) S.a_ready(nxt);
;             if constexpr (SP2) {
;             PG8_LDB(B0, 0, 0); PG8_LDB(B1, 0, 1); PG8_SCHED; PG8_LDA(At, 0, 0); PG8_STAGE(PG8_SA(1, 1), a1 + hstep, voffA);
;             PG8_WAIT_V(8); PG8_WAIT_L(0); PG8_BAR; PG8_MMA(0, 0, At, B0); PG8_MMA(0, 1, At, B1); PG8_BAR; PG8_SCHED;
;             PG8_LDA(At, 0, 1); PG8_STAGE(PG8_SB(0, 0), b2, voffB); PG8_STAGE(PG8_SB(0, 1), b2 + hstepB, voffB); PG8_STAGE(PG8_SA(0, 0), a2, voffA);
;             PG8_WAIT_V(8); PG8_WAIT_L(0); PG8_BAR; PG8_MMA(1, 0, At, B0); PG8_MMA(1, 1, At, B1); PG8_BAR; PG8_SCHED;
;             PG8_LDB(B0, 1, 0); PG8_LDB(B1, 1, 1); PG8_SCHED; PG8_LDA(At, 1, 0); PG8_STAGE(PG8_SA(0, 1), a2 + hstep, voffA);
;             PG8_WAIT_V(8); PG8_WAIT_L(0); PG8_BAR; PG8_MMA(0, 0, At, B0); PG8_MMA(0, 1, At, B1); PG8_BAR; PG8_SCHED;
;             PG8_LDA(At, 1, 1); PG8_STAGE(PG8_SB(1, 0), b3, voffB); PG8_STAGE(PG8_SB(1, 1), b3 + hstepB, voffB); PG8_STAGE(PG8_SA(1, 0), a3, voffA);
;             PG8_WAIT_V(8); PG8_WAIT_L(0); PG8_BAR; PG8_MMA(1, 0, At, B0); PG8_MMA(1, 1, At, B1); PG8_BAR; PG8_SCHED;
	s_add_i32 s41, 0, 0x18000
	s_add_i32 s42, 0, 0x1c000
	v_add_u32_e32 v164, s41, v144
	v_add_u32_e32 v180, s42, v144
	ds_read_b128 v[152:155], v164
	ds_read_b128 v[156:159], v164 offset:1024
	ds_read_b128 v[160:163], v164 offset:2048
	ds_read_b128 v[164:167], v164 offset:3072
	ds_read_b128 v[168:171], v180
	ds_read_b128 v[172:175], v180 offset:1024
	ds_read_b128 v[176:179], v180 offset:2048
	ds_read_b128 v[180:183], v180 offset:3072
	s_add_u32 s14, s20, 0x160000
	s_addc_u32 s15, s21, 0
	s_mov_b32 m0, s26
	ds_read_b128 v[184:187], v149 offset:32768
	ds_read_b128 v[188:191], v149 offset:33792
	ds_read_b128 v[192:195], v149 offset:34816
	ds_read_b128 v[196:199], v149 offset:35840
	ds_read_b128 v[200:203], v149 offset:36864
	ds_read_b128 v[204:207], v149 offset:37888
	ds_read_b128 v[208:211], v149 offset:38912
	ds_read_b128 v[212:215], v149 offset:39936
	global_load_lds_dwordx4 v128, s[14:15]
	s_mov_b32 m0, s27
	s_nop 0
	global_load_lds_dwordx4 v132, s[14:15]
	s_waitcnt vmcnt(8)
	s_waitcnt lgkmcnt(0)
	s_barrier
	s_waitcnt lgkmcnt(0)
	v_mfma_f32_16x16x32_bf16 v[124:127], v[152:155], v[184:187], v[124:127]
	v_mfma_f32_16x16x32_bf16 v[120:123], v[160:163], v[184:187], v[120:123]
	v_mfma_f32_16x16x32_bf16 v[112:115], v[152:155], v[192:195], v[112:115]
	v_mfma_f32_16x16x32_bf16 v[104:107], v[160:163], v[192:195], v[104:107]
	v_mfma_f32_16x16x32_bf16 v[92:95], v[152:155], v[200:203], v[92:95]
	v_mfma_f32_16x16x32_bf16 v[88:91], v[160:163], v[200:203], v[88:91]
	v_mfma_f32_16x16x32_bf16 v[76:79], v[152:155], v[208:211], v[76:79]
	v_mfma_f32_16x16x32_bf16 v[72:75], v[160:163], v[208:211], v[72:75]
	v_mfma_f32_16x16x32_bf16 v[124:127], v[156:159], v[188:191], v[124:127]
	v_mfma_f32_16x16x32_bf16 v[120:123], v[164:167], v[188:191], v[120:123]
	v_mfma_f32_16x16x32_bf16 v[112:115], v[156:159], v[196:199], v[112:115]
	v_mfma_f32_16x16x32_bf16 v[104:107], v[164:167], v[196:199], v[104:107]
	v_mfma_f32_16x16x32_bf16 v[92:95], v[156:159], v[204:207], v[92:95]
	v_mfma_f32_16x16x32_bf16 v[88:91], v[164:167], v[204:207], v[88:91]
	v_mfma_f32_16x16x32_bf16 v[76:79], v[156:159], v[212:215], v[76:79]
	v_mfma_f32_16x16x32_bf16 v[72:75], v[164:167], v[212:215], v[72:75]
	v_mfma_f32_16x16x32_bf16 v[116:119], v[168:171], v[184:187], v[116:119]
	v_mfma_f32_16x16x32_bf16 v[108:111], v[176:179], v[184:187], v[108:111]
	v_mfma_f32_16x16x32_bf16 v[100:103], v[168:171], v[192:195], v[100:103]
	v_mfma_f32_16x16x32_bf16 v[96:99], v[176:179], v[192:195], v[96:99]
	v_mfma_f32_16x16x32_bf16 v[84:87], v[168:171], v[200:203], v[84:87]
	v_mfma_f32_16x16x32_bf16 v[80:83], v[176:179], v[200:203], v[80:83]
	v_mfma_f32_16x16x32_bf16 v[68:71], v[168:171], v[208:211], v[68:71]
	v_mfma_f32_16x16x32_bf16 v[64:67], v[176:179], v[208:211], v[64:67]
	v_mfma_f32_16x16x32_bf16 v[116:119], v[172:175], v[188:191], v[116:119]
	v_mfma_f32_16x16x32_bf16 v[108:111], v[180:183], v[188:191], v[108:111]
	v_mfma_f32_16x16x32_bf16 v[100:103], v[172:175], v[196:199], v[100:103]
	v_mfma_f32_16x16x32_bf16 v[96:99], v[180:183], v[196:199], v[96:99]
	v_mfma_f32_16x16x32_bf16 v[84:87], v[172:175], v[204:207], v[84:87]
	v_mfma_f32_16x16x32_bf16 v[80:83], v[180:183], v[204:207], v[80:83]
	v_mfma_f32_16x16x32_bf16 v[68:71], v[172:175], v[212:215], v[68:71]
	v_mfma_f32_16x16x32_bf16 v[64:67], v[180:183], v[212:215], v[64:67]
	s_barrier
	s_add_u32 s98, s18, 0x80
	s_addc_u32 s99, s19, 0
	s_add_u32 s100, s20, 0x80
	s_addc_u32 s101, s21, 0
	s_add_i32 s14, s41, s23
	s_mov_b32 m0, s14
	ds_read_b128 v[184:187], v149 offset:49152
	ds_read_b128 v[188:191], v149 offset:50176
	ds_read_b128 v[192:195], v149 offset:51200
	ds_read_b128 v[196:199], v149 offset:52224
	ds_read_b128 v[200:203], v149 offset:53248
	ds_read_b128 v[204:207], v149 offset:54272
	ds_read_b128 v[208:211], v149 offset:55296
	ds_read_b128 v[212:215], v149 offset:56320
	global_load_lds_dwordx4 v130, s[98:99]
	s_add_i32 m0, s14, 0x2000
	s_add_u32 s14, s18, 0x58080
	v_lshl_add_u64 v[216:217], v[218:219], 0, s[6:7]
	s_addc_u32 s15, s19, 0
	s_add_i32 s18, s42, s23
	global_load_lds_dwordx4 v[216:217], off
	s_mov_b32 m0, s18
	s_nop 0
	global_load_lds_dwordx4 v130, s[14:15]
	s_add_i32 m0, s18, 0x2000
	s_nop 0
	global_load_lds_dwordx4 v134, s[14:15]
	s_mov_b32 m0, s31
	s_nop 0
	global_load_lds_dwordx4 v128, s[100:101]
	s_mov_b32 m0, s33
	s_nop 0
	global_load_lds_dwordx4 v132, s[100:101]
	s_waitcnt vmcnt(8)
	s_waitcnt lgkmcnt(0)
	s_barrier
	s_waitcnt lgkmcnt(0)
	v_mfma_f32_16x16x32_bf16 v[60:63], v[152:155], v[184:187], v[60:63]
	v_mfma_f32_16x16x32_bf16 v[56:59], v[160:163], v[184:187], v[56:59]
	v_mfma_f32_16x16x32_bf16 v[44:47], v[152:155], v[192:195], v[44:47]
	v_mfma_f32_16x16x32_bf16 v[40:43], v[160:163], v[192:195], v[40:43]
	v_mfma_f32_16x16x32_bf16 v[28:31], v[152:155], v[200:203], v[28:31]
	v_mfma_f32_16x16x32_bf16 v[24:27], v[160:163], v[200:203], v[24:27]
	v_mfma_f32_16x16x32_bf16 v[12:15], v[152:155], v[208:211], v[12:15]
	v_mfma_f32_16x16x32_bf16 v[8:11], v[160:163], v[208:211], v[8:11]
	v_mfma_f32_16x16x32_bf16 v[60:63], v[156:159], v[188:191], v[60:63]
	v_mfma_f32_16x16x32_bf16 v[56:59], v[164:167], v[188:191], v[56:59]
	v_mfma_f32_16x16x32_bf16 v[44:47], v[156:159], v[196:199], v[44:47]
	v_mfma_f32_16x16x32_bf16 v[40:43], v[164:167], v[196:199], v[40:43]
	v_mfma_f32_16x16x32_bf16 v[28:31], v[156:159], v[204:207], v[28:31]
	v_mfma_f32_16x16x32_bf16 v[24:27], v[164:167], v[204:207], v[24:27]
	v_mfma_f32_16x16x32_bf16 v[12:15], v[156:159], v[212:215], v[12:15]
	v_mfma_f32_16x16x32_bf16 v[8:11], v[164:167], v[212:215], v[8:11]
	v_mfma_f32_16x16x32_bf16 v[52:55], v[168:171], v[184:187], v[52:55]
	v_mfma_f32_16x16x32_bf16 v[48:51], v[176:179], v[184:187], v[48:51]
	v_mfma_f32_16x16x32_bf16 v[36:39], v[168:171], v[192:195], v[36:39]
	v_mfma_f32_16x16x32_bf16 v[32:35], v[176:179], v[192:195], v[32:35]
	v_mfma_f32_16x16x32_bf16 v[20:23], v[168:171], v[200:203], v[20:23]
	v_mfma_f32_16x16x32_bf16 v[16:19], v[176:179], v[200:203], v[16:19]
	v_mfma_f32_16x16x32_bf16 v[4:7], v[168:171], v[208:211], v[4:7]
	v_mfma_f32_16x16x32_bf16 v[0:3], v[176:179], v[208:211], v[0:3]
	v_mfma_f32_16x16x32_bf16 v[52:55], v[172:175], v[188:191], v[52:55]
	v_mfma_f32_16x16x32_bf16 v[48:51], v[180:183], v[188:191], v[48:51]
	v_mfma_f32_16x16x32_bf16 v[36:39], v[172:175], v[196:199], v[36:39]
	v_mfma_f32_16x16x32_bf16 v[32:35], v[180:183], v[196:199], v[32:35]
	v_mfma_f32_16x16x32_bf16 v[20:23], v[172:175], v[204:207], v[20:23]
	v_mfma_f32_16x16x32_bf16 v[16:19], v[180:183], v[204:207], v[16:19]
	v_mfma_f32_16x16x32_bf16 v[4:7], v[172:175], v[212:215], v[4:7]
	v_mfma_f32_16x16x32_bf16 v[0:3], v[180:183], v[212:215], v[0:3]
	s_barrier
; #define LAS __attribute__((address_space(3)))
;     __device__ __forceinline__ void operator()(const f32x4 (&acc)[2][2][4][2], const Unit& u, int wr, int wc, int fr, int fq) const {
;         const int s = u.pm >> 5, lane = fq * 16 + fr, rr = lane >> 3, pc = lane & 7;
;         const float* __restrict__ xi = xin + (size_t)u.pm * BM * DM; float* __restrict__ xo = xout + (size_t)u.pm * BM * DM; bf16_t* __restrict__ ho = Hn + (size_t)u.pm * BM * DM;
;         LAS unsigned char* st = lds_epi + (wr * 4 + wc) * 2304;
;         LAS float* sst = (LAS float*)(lds_epi + 18432 + (wr * 4 + wc) * 512);
;         const int colr = u.pn * BM + wc * 64 + 4 * pc;
;         const unsigned eb = (unsigned)((wr * 64 + rr) * DM + colr);
;         f32x4 gv[2], gsn[2];
; #pragma unroll
;         for (int bj = 0; bj < 2; ++bj) { gv[bj] = *(const f32x4*)(gate + (size_t)s * MODW + colr + bj * 32) * (0.5f * GS2);
;             if (!PLAIN) gsn[bj] = *(const f32x4*)(gnext + colr + bj * 32) * (*(const f32x4*)(scnext + (size_t)s * MODW + colr + bj * 32) + 1.0f); else gsn[bj] = gv[bj]; }
;         const unsigned wr_off = (unsigned)(fr * 144 + 16 * fq), rd_off = (unsigned)(rr * 144 + pc * 16);
;         const bool odd = (rr & 1) != 0;
;         f32x4 xb[2][2][2];
;     ...
;         ERN_LOADX(0);
; #pragma unroll
;         for (int g = 0; g < 8; ++g) { const int ai = g >> 2, m = g & 3;
;             if (g + 1 < 8) ERN_LOADX(g + 1);
;             float sq0 = 0.f, sq1 = 0.f; u32x2 hw[2][2];
; #pragma unroll
;             for (int bj = 0; bj < 2; ++bj) {
;                 *(LAS f32x4*)(st + wr_off) = acc[ai][bj][m][0]; *(LAS f32x4*)(st + wr_off + 64) = acc[ai][bj][m][1];
;                 const f32x4 a0 = *(const LAS f32x4*)(st + rd_off), a1 = *(const LAS f32x4*)(st + rd_off + 8 * 144);
;                 { const f32x4 xv = xb[g & 1][bj][0] + gv[bj] * a0; __builtin_nontemporal_store(xv, (f32x4*)((char*)xo + 4u * ERN_EOFF(g, bj, 0)));
;                   sq0 += (xv.x * xv.x + xv.y * xv.y) + (xv.z * xv.z + xv.w * xv.w);
;                   const f32x4 hv = xv * gsn[bj]; hw[bj][0].x = cvt_pk_bf16(hv.x, hv.y); hw[bj][0].y = cvt_pk_bf16(hv.z, hv.w); }
;                 { const f32x4 xv = xb[g & 1][bj][1] + gv[bj] * a1; __builtin_nontemporal_store(xv, (f32x4*)((char*)xo + 4u * ERN_EOFF(g, bj, 1)));
;                   sq1 += (xv.x * xv.x + xv.y * xv.y) + (xv.z * xv.z + xv.w * xv.w);
	s_add_i32 s40, s40, 2
	s_add_u32 s13, s13, 0x100
	s_addc_u32 s39, s39, 0
	s_cmpk_lt_u32 s40, 0x56
	s_mov_b64 s[14:15], s[16:17]
	s_cbranch_scc1 .LBB0_3002
	s_setprio 0
	s_ashr_i32 s14, s12, 5
	s_ashr_i32 s13, s12, 31
	s_mul_hi_i32 s15, s14, 0x12000
	s_mul_i32 s14, s14, 0x12000
	v_lshl_or_b32 v152, s38, 8, v145
	s_add_u32 s14, s29, s14
	s_addc_u32 s15, s30, s15
	v_ashrrev_i32_e32 v153, 31, v152
	s_lshl_b64 s[12:13], s[12:13], 21
	v_lshl_add_u64 v[166:167], v[152:153], 2, s[14:15]
	s_add_u32 s12, s90, s12
	global_load_dwordx4 v[154:157], v[166:167], off
	s_addc_u32 s13, s91, s13
	v_lshl_add_u32 v152, v152, 2, v146
	global_load_dwordx4 v[158:161], v152, s[12:13]
	v_add_u32_e32 v153, 0x10000, v152
	global_load_dwordx4 v[162:165], v153, s[12:13]
	s_nop 0
	global_load_dwordx4 v[166:169], v[166:167], off offset:128
	s_nop 0
	global_load_dwordx4 v[170:173], v152, s[12:13] offset:128
	v_add_u32_e32 v198, 0x10080, v152
	global_load_dwordx4 v[174:177], v198, s[12:13]
	v_add_u32_e32 v199, 0x20000, v152
	global_load_dwordx4 v[178:181], v199, s[12:13]
	v_add_u32_e32 v200, 0x30000, v152
	global_load_dwordx4 v[182:185], v200, s[12:13]
	v_add_u32_e32 v201, 0x20080, v152
	global_load_dwordx4 v[186:189], v201, s[12:13]
	v_add_u32_e32 v202, 0x30080, v152
	global_load_dwordx4 v[190:193], v202, s[12:13]
	s_andn2_b64 vcc, exec, s[8:9]
	s_cbranch_vccnz .Lalign_3005
	s_barrier
.Lalign_3005:
	ds_write_b128 v150, v[124:127]
	ds_write_b128 v150, v[120:123] offset:64
	ds_read_b128 v[124:127], v151
	ds_read_b128 v[194:197], v151 offset:1152
	v_add_u32_e32 v203, 0x40000, v152
	v_add_u32_e32 v204, 0x50000, v152
	s_mov_b64 s[14:15], -1
	s_and_b64 vcc, exec, s[0:1]
	s_waitcnt vmcnt(0)
	v_pk_mul_f32 v[120:121], v[156:157], 0.5 op_sel_hi:[1,0]
	v_pk_mul_f32 v[122:123], v[154:155], 0.5 op_sel_hi:[1,0]
	s_waitcnt lgkmcnt(1)
	v_pk_fma_f32 v[126:127], v[120:121], v[126:127], v[160:161]
	v_pk_fma_f32 v[124:125], v[122:123], v[124:125], v[158:159]
	s_waitcnt lgkmcnt(0)
	v_pk_fma_f32 v[156:157], v[120:121], v[196:197], v[164:165]
	v_pk_fma_f32 v[154:155], v[122:123], v[194:195], v[162:163]
	global_store_dwordx4 v152, v[124:127], s[12:13] nt
	v_pk_mul_f32 v[158:159], v[120:121], v[156:157]
	v_pk_mul_f32 v[160:161], v[122:123], v[154:155]
	v_pk_mul_f32 v[124:125], v[122:123], v[124:125]
	v_pk_mul_f32 v[126:127], v[120:121], v[126:127]
	v_cvt_pk_bf16_f32 v124, v124, v125
	s_nop 0
	v_cvt_pk_bf16_f32 v124, v126, v127
	global_store_dwordx4 v153, v[154:157], s[12:13] nt
	v_cvt_pk_bf16_f32 v124, v160, v161
	v_add_u32_e32 v153, 0x40080, v152
	v_cvt_pk_bf16_f32 v124, v158, v159
	ds_write_b128 v150, v[116:119]
	ds_write_b128 v150, v[108:111] offset:64
	ds_read_b128 v[116:119], v151
	ds_read_b128 v[124:127], v151 offset:1152
	v_pk_mul_f32 v[108:109], v[168:169], 0.5 op_sel_hi:[1,0]
	v_pk_mul_f32 v[110:111], v[166:167], 0.5 op_sel_hi:[1,0]
	v_add_u32_e32 v166, 0x50080, v152
	s_waitcnt lgkmcnt(1)
	v_pk_fma_f32 v[118:119], v[108:109], v[118:119], v[172:173]
	v_pk_fma_f32 v[116:117], v[110:111], v[116:117], v[170:171]
	s_waitcnt lgkmcnt(0)
	v_pk_fma_f32 v[126:127], v[108:109], v[126:127], v[176:177]
	v_pk_fma_f32 v[124:125], v[110:111], v[124:125], v[174:175]
	global_store_dwordx4 v152, v[116:119], s[12:13] offset:128 nt
	v_pk_mul_f32 v[154:155], v[108:109], v[126:127]
	v_pk_mul_f32 v[156:157], v[110:111], v[124:125]
	v_pk_mul_f32 v[116:117], v[110:111], v[116:117]
	v_pk_mul_f32 v[118:119], v[108:109], v[118:119]
	v_cvt_pk_bf16_f32 v116, v116, v117
	s_nop 0
	v_cvt_pk_bf16_f32 v116, v118, v119
	global_store_dwordx4 v198, v[124:127], s[12:13] nt
	v_cvt_pk_bf16_f32 v116, v156, v157
	s_nop 0
	v_cvt_pk_bf16_f32 v116, v154, v155
	global_load_dwordx4 v[116:119], v203, s[12:13]
	global_load_dwordx4 v[124:127], v204, s[12:13]
	ds_write_b128 v150, v[112:115]
	ds_write_b128 v150, v[104:107] offset:64
	ds_read_b128 v[104:107], v151
	ds_read_b128 v[112:115], v151 offset:1152
	global_load_dwordx4 v[154:157], v153, s[12:13]
	global_load_dwordx4 v[158:161], v166, s[12:13]
	s_waitcnt lgkmcnt(1)
	v_pk_fma_f32 v[106:107], v[120:121], v[106:107], v[180:181]
	v_pk_fma_f32 v[104:105], v[122:123], v[104:105], v[178:179]
	s_waitcnt lgkmcnt(0)
	v_pk_fma_f32 v[114:115], v[120:121], v[114:115], v[184:185]
	v_pk_fma_f32 v[112:113], v[122:123], v[112:113], v[182:183]
	global_store_dwordx4 v199, v[104:107], s[12:13] nt
	v_pk_mul_f32 v[162:163], v[120:121], v[114:115]
	v_pk_mul_f32 v[164:165], v[122:123], v[112:113]
	v_pk_mul_f32 v[104:105], v[122:123], v[104:105]
	v_pk_mul_f32 v[106:107], v[120:121], v[106:107]
	v_cvt_pk_bf16_f32 v104, v104, v105
	s_nop 0
	v_cvt_pk_bf16_f32 v104, v106, v107
	global_store_dwordx4 v200, v[112:115], s[12:13] nt
	v_cvt_pk_bf16_f32 v104, v164, v165
	v_add_u32_e32 v164, 0x60080, v152
	v_cvt_pk_bf16_f32 v104, v162, v163
	ds_write_b128 v150, v[100:103]
	ds_write_b128 v150, v[96:99] offset:64
	ds_read_b128 v[96:99], v151
	ds_read_b128 v[100:103], v151 offset:1152
	v_add_u32_e32 v162, 0x60000, v152
	v_add_u32_e32 v163, 0x70000, v152
	v_add_u32_e32 v165, 0x70080, v152
	s_waitcnt lgkmcnt(1)
	v_pk_fma_f32 v[98:99], v[108:109], v[98:99], v[188:189]
	v_pk_fma_f32 v[96:97], v[110:111], v[96:97], v[186:187]
	s_waitcnt lgkmcnt(0)
	v_pk_fma_f32 v[102:103], v[108:109], v[102:103], v[192:193]
	v_pk_fma_f32 v[100:101], v[110:111], v[100:101], v[190:191]
	global_store_dwordx4 v201, v[96:99], s[12:13] nt
	v_pk_mul_f32 v[104:105], v[108:109], v[102:103]
	v_pk_mul_f32 v[106:107], v[110:111], v[100:101]
	v_pk_mul_f32 v[96:97], v[110:111], v[96:97]
	v_pk_mul_f32 v[98:99], v[108:109], v[98:99]
	v_cvt_pk_bf16_f32 v96, v96, v97
	s_nop 0
	v_cvt_pk_bf16_f32 v96, v98, v99
	global_store_dwordx4 v202, v[100:103], s[12:13] nt
	v_cvt_pk_bf16_f32 v96, v106, v107
	s_nop 0
	v_cvt_pk_bf16_f32 v96, v104, v105
	global_load_dwordx4 v[96:99], v162, s[12:13]
	global_load_dwordx4 v[100:103], v163, s[12:13]
	global_load_dwordx4 v[104:107], v164, s[12:13]
	global_load_dwordx4 v[112:115], v165, s[12:13]
	ds_write_b128 v150, v[92:95]
	ds_write_b128 v150, v[88:91] offset:64
	ds_read_b128 v[88:91], v151
	ds_read_b128 v[92:95], v151 offset:1152
	s_waitcnt vmcnt(11) lgkmcnt(1)
; #define LAS __attribute__((address_space(3)))
; __device__ __forceinline__ unsigned cvt_pk_bf16(float lo, float hi) { unsigned r; asm volatile("v_cvt_pk_bf16_f32 %0, %1, %2" : "=v"(r) : "v"(lo), "v"(hi)); return r; }
; #define ERN_EOFF(q, m) (eb + (unsigned)((((q) & 1) * HALF + (m) * 16) * DM + ERN_COL((q) >> 1)))
; #define ERN_LOADX(q) do { _Pragma("unroll") for (int m = 0; m < 4; ++m) xb[(q) & 1][m] = *(const f32x4*)((const char*)xi + 4u * ERN_EOFF(q, m)); } while (0)
; #define ERN_LOADX(g) do { _Pragma("unroll") for (int bj_ = 0; bj_ < 2; ++bj_) _Pragma("unroll") for (int rh_ = 0; rh_ < 2; ++rh_) xb[(g) & 1][bj_][rh_] = *(const f32x4*)((const char*)xi + 4u * ERN_EOFF(g, bj_, rh_)); } while (0)
;     __device__ __forceinline__ void operator()(const f32x4 (&acc)[2][2][4][2], const Unit& u, int wr, int wc, int fr, int fq) const {
;     ...
;         for (int g = 0; g < 8; ++g) { const int ai = g >> 2, m = g & 3;
;             if (g + 1 < 8) ERN_LOADX(g + 1);
;             float sq0 = 0.f, sq1 = 0.f; u32x2 hw[2][2];
; #pragma unroll
;             for (int bj = 0; bj < 2; ++bj) {
;                 *(LAS f32x4*)(st + wr_off) = acc[ai][bj][m][0]; *(LAS f32x4*)(st + wr_off + 64) = acc[ai][bj][m][1];
;                 const f32x4 a0 = *(const LAS f32x4*)(st + rd_off), a1 = *(const LAS f32x4*)(st + rd_off + 8 * 144);
;                 { const f32x4 xv = xb[g & 1][bj][0] + gv[bj] * a0; __builtin_nontemporal_store(xv, (f32x4*)((char*)xo + 4u * ERN_EOFF(g, bj, 0)));
;                   sq0 += (xv.x * xv.x + xv.y * xv.y) + (xv.z * xv.z + xv.w * xv.w);
;                   const f32x4 hv = xv * gsn[bj]; hw[bj][0].x = cvt_pk_bf16(hv.x, hv.y); hw[bj][0].y = cvt_pk_bf16(hv.z, hv.w); }
;                 { const f32x4 xv = xb[g & 1][bj][1] + gv[bj] * a1; __builtin_nontemporal_store(xv, (f32x4*)((char*)xo + 4u * ERN_EOFF(g, bj, 1)));
;                   sq1 += (xv.x * xv.x + xv.y * xv.y) + (xv.z * xv.z + xv.w * xv.w);
;                   const f32x4 hv = xv * gsn[bj]; hw[bj][1].x = cvt_pk_bf16(hv.x, hv.y); hw[bj][1].y = cvt_pk_bf16(hv.z, hv.w); }
;             }
	v_pk_fma_f32 v[90:91], v[120:121], v[90:91], v[118:119]
	v_pk_fma_f32 v[88:89], v[122:123], v[88:89], v[116:117]
	s_waitcnt vmcnt(10) lgkmcnt(0)
	v_pk_fma_f32 v[94:95], v[120:121], v[94:95], v[126:127]
	v_pk_fma_f32 v[92:93], v[122:123], v[92:93], v[124:125]
	global_store_dwordx4 v203, v[88:91], s[12:13] nt
	v_pk_mul_f32 v[116:117], v[120:121], v[94:95]
	v_pk_mul_f32 v[118:119], v[122:123], v[92:93]
	v_pk_mul_f32 v[88:89], v[122:123], v[88:89]
	v_pk_mul_f32 v[90:91], v[120:121], v[90:91]
	v_cvt_pk_bf16_f32 v88, v88, v89
	s_nop 0
	v_cvt_pk_bf16_f32 v88, v90, v91
	global_store_dwordx4 v204, v[92:95], s[12:13] nt
	v_cvt_pk_bf16_f32 v88, v118, v119
	v_add_u32_e32 v118, 0x100080, v152
	v_cvt_pk_bf16_f32 v88, v116, v117
	ds_write_b128 v150, v[84:87]
	ds_write_b128 v150, v[80:83] offset:64
	ds_read_b128 v[80:83], v151
	ds_read_b128 v[84:87], v151 offset:1152
	v_add_u32_e32 v116, 0x100000, v152
	v_add_u32_e32 v117, 0x110000, v152
	v_add_u32_e32 v119, 0x110080, v152
	s_waitcnt vmcnt(11) lgkmcnt(1)
	v_pk_fma_f32 v[82:83], v[108:109], v[82:83], v[156:157]
	v_pk_fma_f32 v[80:81], v[110:111], v[80:81], v[154:155]
	s_waitcnt vmcnt(10) lgkmcnt(0)
	v_pk_fma_f32 v[86:87], v[108:109], v[86:87], v[160:161]
	v_pk_fma_f32 v[84:85], v[110:111], v[84:85], v[158:159]
	global_store_dwordx4 v153, v[80:83], s[12:13] nt
	v_pk_mul_f32 v[88:89], v[108:109], v[86:87]
	v_pk_mul_f32 v[90:91], v[110:111], v[84:85]
	v_pk_mul_f32 v[80:81], v[110:111], v[80:81]
	v_pk_mul_f32 v[82:83], v[108:109], v[82:83]
	v_cvt_pk_bf16_f32 v80, v80, v81
	s_nop 0
	v_cvt_pk_bf16_f32 v80, v82, v83
	global_store_dwordx4 v166, v[84:87], s[12:13] nt
	v_cvt_pk_bf16_f32 v80, v90, v91
	s_nop 0
	v_cvt_pk_bf16_f32 v80, v88, v89
	global_load_dwordx4 v[80:83], v116, s[12:13]
	global_load_dwordx4 v[84:87], v117, s[12:13]
	ds_write_b128 v150, v[76:79]
	ds_write_b128 v150, v[72:75] offset:64
	ds_read_b128 v[72:75], v151
	ds_read_b128 v[76:79], v151 offset:1152
	global_load_dwordx4 v[88:91], v118, s[12:13]
	global_load_dwordx4 v[92:95], v119, s[12:13]
	s_waitcnt vmcnt(11) lgkmcnt(1)
	v_pk_fma_f32 v[74:75], v[120:121], v[74:75], v[98:99]
	v_pk_fma_f32 v[72:73], v[122:123], v[72:73], v[96:97]
	s_waitcnt vmcnt(10) lgkmcnt(0)
	v_pk_fma_f32 v[78:79], v[120:121], v[78:79], v[102:103]
	v_pk_fma_f32 v[76:77], v[122:123], v[76:77], v[100:101]
	global_store_dwordx4 v162, v[72:75], s[12:13] nt
	v_pk_mul_f32 v[96:97], v[120:121], v[78:79]
	v_pk_mul_f32 v[98:99], v[122:123], v[76:77]
	v_pk_mul_f32 v[72:73], v[122:123], v[72:73]
	v_pk_mul_f32 v[74:75], v[120:121], v[74:75]
	v_cvt_pk_bf16_f32 v72, v72, v73
	s_nop 0
	v_cvt_pk_bf16_f32 v72, v74, v75
	global_store_dwordx4 v163, v[76:79], s[12:13] nt
	v_cvt_pk_bf16_f32 v72, v98, v99
	v_add_u32_e32 v98, 0x120080, v152
	v_cvt_pk_bf16_f32 v72, v96, v97
	ds_write_b128 v150, v[68:71]
	ds_write_b128 v150, v[64:67] offset:64
	ds_read_b128 v[64:67], v151
	ds_read_b128 v[68:71], v151 offset:1152
	v_add_u32_e32 v96, 0x120000, v152
	v_add_u32_e32 v97, 0x130000, v152
	v_add_u32_e32 v99, 0x130080, v152
	s_waitcnt vmcnt(11) lgkmcnt(1)
	v_pk_fma_f32 v[66:67], v[108:109], v[66:67], v[106:107]
	v_pk_fma_f32 v[64:65], v[110:111], v[64:65], v[104:105]
	s_waitcnt vmcnt(10) lgkmcnt(0)
	v_pk_fma_f32 v[70:71], v[108:109], v[70:71], v[114:115]
	v_pk_fma_f32 v[68:69], v[110:111], v[68:69], v[112:113]
	global_store_dwordx4 v164, v[64:67], s[12:13] nt
	v_pk_mul_f32 v[72:73], v[108:109], v[70:71]
	v_pk_mul_f32 v[74:75], v[110:111], v[68:69]
	v_pk_mul_f32 v[64:65], v[110:111], v[64:65]
	v_pk_mul_f32 v[66:67], v[108:109], v[66:67]
	v_cvt_pk_bf16_f32 v64, v64, v65
	s_nop 0
	v_cvt_pk_bf16_f32 v64, v66, v67
	global_store_dwordx4 v165, v[68:71], s[12:13] nt
	v_cvt_pk_bf16_f32 v64, v74, v75
	s_nop 0
	v_cvt_pk_bf16_f32 v64, v72, v73
	global_load_dwordx4 v[64:67], v96, s[12:13]
	global_load_dwordx4 v[68:71], v97, s[12:13]
	global_load_dwordx4 v[72:75], v98, s[12:13]
	global_load_dwordx4 v[76:79], v99, s[12:13]
	ds_write_b128 v150, v[60:63]
	ds_write_b128 v150, v[56:59] offset:64
	ds_read_b128 v[56:59], v151
	ds_read_b128 v[60:63], v151 offset:1152
	s_waitcnt vmcnt(11) lgkmcnt(1)
	v_pk_fma_f32 v[58:59], v[120:121], v[58:59], v[82:83]
	v_pk_fma_f32 v[56:57], v[122:123], v[56:57], v[80:81]
	s_waitcnt vmcnt(10) lgkmcnt(0)
	v_pk_fma_f32 v[62:63], v[120:121], v[62:63], v[86:87]
	v_pk_fma_f32 v[60:61], v[122:123], v[60:61], v[84:85]
	global_store_dwordx4 v116, v[56:59], s[12:13] nt
	v_pk_mul_f32 v[80:81], v[120:121], v[62:63]
	v_pk_mul_f32 v[82:83], v[122:123], v[60:61]
	v_pk_mul_f32 v[56:57], v[122:123], v[56:57]
	v_pk_mul_f32 v[58:59], v[120:121], v[58:59]
	v_cvt_pk_bf16_f32 v56, v56, v57
	s_nop 0
	v_cvt_pk_bf16_f32 v56, v58, v59
	global_store_dwordx4 v117, v[60:63], s[12:13] nt
	v_cvt_pk_bf16_f32 v56, v82, v83
	v_add_u32_e32 v82, 0x140080, v152
	v_cvt_pk_bf16_f32 v56, v80, v81
	ds_write_b128 v150, v[52:55]
	ds_write_b128 v150, v[48:51] offset:64
	ds_read_b128 v[48:51], v151
	ds_read_b128 v[52:55], v151 offset:1152
	v_add_u32_e32 v80, 0x140000, v152
	v_add_u32_e32 v81, 0x150000, v152
	v_add_u32_e32 v83, 0x150080, v152
	s_waitcnt vmcnt(11) lgkmcnt(1)
	v_pk_fma_f32 v[50:51], v[108:109], v[50:51], v[90:91]
	v_pk_fma_f32 v[48:49], v[110:111], v[48:49], v[88:89]
	s_waitcnt vmcnt(10) lgkmcnt(0)
; #define LAS __attribute__((address_space(3)))
; __device__ __forceinline__ unsigned cvt_pk_bf16(float lo, float hi) { unsigned r; asm volatile("v_cvt_pk_bf16_f32 %0, %1, %2" : "=v"(r) : "v"(lo), "v"(hi)); return r; }
; #define ERN_EOFF(q, m) (eb + (unsigned)((((q) & 1) * HALF + (m) * 16) * DM + ERN_COL((q) >> 1)))
; #define PG8_BAR __builtin_amdgcn_s_barrier()
;     __device__ __forceinline__ void operator()(const f32x4 (&acc)[2][2][4][2], const Unit& u, int wr, int wc, int fr, int fq) const {
;     ...
;         for (int g = 0; g < 8; ++g) { const int ai = g >> 2, m = g & 3;
;             if (g + 1 < 8) ERN_LOADX(g + 1);
;             float sq0 = 0.f, sq1 = 0.f; u32x2 hw[2][2];
; #pragma unroll
;             for (int bj = 0; bj < 2; ++bj) {
;                 *(LAS f32x4*)(st + wr_off) = acc[ai][bj][m][0]; *(LAS f32x4*)(st + wr_off + 64) = acc[ai][bj][m][1];
;                 const f32x4 a0 = *(const LAS f32x4*)(st + rd_off), a1 = *(const LAS f32x4*)(st + rd_off + 8 * 144);
;                 { const f32x4 xv = xb[g & 1][bj][0] + gv[bj] * a0; __builtin_nontemporal_store(xv, (f32x4*)((char*)xo + 4u * ERN_EOFF(g, bj, 0)));
;                   sq0 += (xv.x * xv.x + xv.y * xv.y) + (xv.z * xv.z + xv.w * xv.w);
;                   const f32x4 hv = xv * gsn[bj]; hw[bj][0].x = cvt_pk_bf16(hv.x, hv.y); hw[bj][0].y = cvt_pk_bf16(hv.z, hv.w); }
;                 { const f32x4 xv = xb[g & 1][bj][1] + gv[bj] * a1; __builtin_nontemporal_store(xv, (f32x4*)((char*)xo + 4u * ERN_EOFF(g, bj, 1)));
;                   sq1 += (xv.x * xv.x + xv.y * xv.y) + (xv.z * xv.z + xv.w * xv.w);
;                   const f32x4 hv = xv * gsn[bj]; hw[bj][1].x = cvt_pk_bf16(hv.x, hv.y); hw[bj][1].y = cvt_pk_bf16(hv.z, hv.w); }
;             }
; template <class Epi, class Sched, bool ALIGN_EPI = false, bool SP2 = false>
; __device__ __forceinline__ void gemm_phase(LAS unsigned char* lds, const Gemm g, const Sched& S, const Epi& E) {
;     ...
;         if (!has_next) break;
; #pragma unroll
;         for (int a = 0; a < 2; ++a)
; #pragma unroll
;             for (int b = 0; b < 2; ++b)
; #pragma unroll
;                 for (int m = 0; m < 4; ++m)
; #pragma unroll
;                     for (int n = 0; n < 2; ++n) acc[a][b][m][n] = (f32x4){0.f, 0.f, 0.f, 0.f};
;         cur = nxt; cA = nA; cB = nB; ++ui;
;         if constexpr (ALIGN_EPI) { if (wr == 1) PG8_BAR; }
	v_pk_fma_f32 v[54:55], v[108:109], v[54:55], v[94:95]
	v_pk_fma_f32 v[52:53], v[110:111], v[52:53], v[92:93]
	global_store_dwordx4 v118, v[48:51], s[12:13] nt
	v_pk_mul_f32 v[56:57], v[108:109], v[54:55]
	v_pk_mul_f32 v[58:59], v[110:111], v[52:53]
	v_pk_mul_f32 v[48:49], v[110:111], v[48:49]
	v_pk_mul_f32 v[50:51], v[108:109], v[50:51]
	v_cvt_pk_bf16_f32 v48, v48, v49
	s_nop 0
	v_cvt_pk_bf16_f32 v48, v50, v51
	global_store_dwordx4 v119, v[52:55], s[12:13] nt
	v_cvt_pk_bf16_f32 v48, v58, v59
	s_nop 0
	v_cvt_pk_bf16_f32 v48, v56, v57
	global_load_dwordx4 v[48:51], v80, s[12:13]
	global_load_dwordx4 v[52:55], v81, s[12:13]
	ds_write_b128 v150, v[44:47]
	ds_write_b128 v150, v[40:43] offset:64
	ds_read_b128 v[40:43], v151
	ds_read_b128 v[44:47], v151 offset:1152
	global_load_dwordx4 v[56:59], v82, s[12:13]
	global_load_dwordx4 v[60:63], v83, s[12:13]
	s_waitcnt vmcnt(11) lgkmcnt(1)
	v_pk_fma_f32 v[42:43], v[120:121], v[42:43], v[66:67]
	v_pk_fma_f32 v[40:41], v[122:123], v[40:41], v[64:65]
	s_waitcnt vmcnt(10) lgkmcnt(0)
	v_pk_fma_f32 v[46:47], v[120:121], v[46:47], v[70:71]
	v_pk_fma_f32 v[44:45], v[122:123], v[44:45], v[68:69]
	global_store_dwordx4 v96, v[40:43], s[12:13] nt
	v_pk_mul_f32 v[64:65], v[120:121], v[46:47]
	v_pk_mul_f32 v[66:67], v[122:123], v[44:45]
	v_pk_mul_f32 v[40:41], v[122:123], v[40:41]
	v_pk_mul_f32 v[42:43], v[120:121], v[42:43]
	v_cvt_pk_bf16_f32 v40, v40, v41
	s_nop 0
	v_cvt_pk_bf16_f32 v40, v42, v43
	global_store_dwordx4 v97, v[44:47], s[12:13] nt
	v_cvt_pk_bf16_f32 v40, v66, v67
	v_add_u32_e32 v66, 0x160080, v152
	v_cvt_pk_bf16_f32 v40, v64, v65
	ds_write_b128 v150, v[36:39]
	ds_write_b128 v150, v[32:35] offset:64
	ds_read_b128 v[32:35], v151
	ds_read_b128 v[36:39], v151 offset:1152
	v_add_u32_e32 v64, 0x160000, v152
	v_add_u32_e32 v65, 0x170000, v152
	v_add_u32_e32 v67, 0x170080, v152
	s_waitcnt vmcnt(11) lgkmcnt(1)
	v_pk_fma_f32 v[34:35], v[108:109], v[34:35], v[74:75]
	v_pk_fma_f32 v[32:33], v[110:111], v[32:33], v[72:73]
	s_waitcnt vmcnt(10) lgkmcnt(0)
	v_pk_fma_f32 v[38:39], v[108:109], v[38:39], v[78:79]
	v_pk_fma_f32 v[36:37], v[110:111], v[36:37], v[76:77]
	global_store_dwordx4 v98, v[32:35], s[12:13] nt
	v_pk_mul_f32 v[40:41], v[108:109], v[38:39]
	v_pk_mul_f32 v[42:43], v[110:111], v[36:37]
	v_pk_mul_f32 v[32:33], v[110:111], v[32:33]
	v_pk_mul_f32 v[34:35], v[108:109], v[34:35]
	v_cvt_pk_bf16_f32 v32, v32, v33
	s_nop 0
	v_cvt_pk_bf16_f32 v32, v34, v35
	global_store_dwordx4 v99, v[36:39], s[12:13] nt
	v_cvt_pk_bf16_f32 v32, v42, v43
	s_nop 0
	v_cvt_pk_bf16_f32 v32, v40, v41
	global_load_dwordx4 v[32:35], v64, s[12:13]
	global_load_dwordx4 v[36:39], v65, s[12:13]
	global_load_dwordx4 v[40:43], v66, s[12:13]
	global_load_dwordx4 v[44:47], v67, s[12:13]
	ds_write_b128 v150, v[28:31]
	ds_write_b128 v150, v[24:27] offset:64
	ds_read_b128 v[24:27], v151
	ds_read_b128 v[28:31], v151 offset:1152
	s_waitcnt vmcnt(11) lgkmcnt(1)
	v_pk_fma_f32 v[26:27], v[120:121], v[26:27], v[50:51]
	v_pk_fma_f32 v[24:25], v[122:123], v[24:25], v[48:49]
	s_waitcnt vmcnt(10) lgkmcnt(0)
	v_pk_fma_f32 v[30:31], v[120:121], v[30:31], v[54:55]
	v_pk_fma_f32 v[28:29], v[122:123], v[28:29], v[52:53]
	global_store_dwordx4 v80, v[24:27], s[12:13] nt
	v_pk_mul_f32 v[48:49], v[120:121], v[30:31]
	v_pk_mul_f32 v[50:51], v[122:123], v[28:29]
	v_pk_mul_f32 v[24:25], v[122:123], v[24:25]
	v_pk_mul_f32 v[26:27], v[120:121], v[26:27]
	v_cvt_pk_bf16_f32 v24, v24, v25
	s_nop 0
	v_cvt_pk_bf16_f32 v24, v26, v27
	global_store_dwordx4 v81, v[28:31], s[12:13] nt
	v_cvt_pk_bf16_f32 v24, v50, v51
	s_nop 0
	v_cvt_pk_bf16_f32 v24, v48, v49
	ds_write_b128 v150, v[20:23]
	ds_write_b128 v150, v[16:19] offset:64
	ds_read_b128 v[16:19], v151
	ds_read_b128 v[20:23], v151 offset:1152
	s_waitcnt vmcnt(11) lgkmcnt(1)
	v_pk_fma_f32 v[18:19], v[108:109], v[18:19], v[58:59]
	v_pk_fma_f32 v[16:17], v[110:111], v[16:17], v[56:57]
	s_waitcnt vmcnt(10) lgkmcnt(0)
	v_pk_fma_f32 v[22:23], v[108:109], v[22:23], v[62:63]
	v_pk_fma_f32 v[20:21], v[110:111], v[20:21], v[60:61]
	global_store_dwordx4 v82, v[16:19], s[12:13] nt
	v_pk_mul_f32 v[24:25], v[108:109], v[22:23]
	v_pk_mul_f32 v[26:27], v[110:111], v[20:21]
	v_pk_mul_f32 v[16:17], v[110:111], v[16:17]
	v_pk_mul_f32 v[18:19], v[108:109], v[18:19]
	v_cvt_pk_bf16_f32 v16, v16, v17
	s_nop 0
	v_cvt_pk_bf16_f32 v16, v18, v19
	global_store_dwordx4 v83, v[20:23], s[12:13] nt
	v_cvt_pk_bf16_f32 v16, v26, v27
	s_nop 0
	v_cvt_pk_bf16_f32 v16, v24, v25
	ds_write_b128 v150, v[12:15]
	ds_write_b128 v150, v[8:11] offset:64
	ds_read_b128 v[8:11], v151
	ds_read_b128 v[12:15], v151 offset:1152
	s_waitcnt vmcnt(7) lgkmcnt(1)
	v_pk_fma_f32 v[10:11], v[120:121], v[10:11], v[34:35]
	v_pk_fma_f32 v[8:9], v[122:123], v[8:9], v[32:33]
	s_waitcnt vmcnt(6) lgkmcnt(0)
	v_pk_fma_f32 v[14:15], v[120:121], v[14:15], v[38:39]
	v_pk_fma_f32 v[12:13], v[122:123], v[12:13], v[36:37]
	global_store_dwordx4 v64, v[8:11], s[12:13] nt
	v_pk_mul_f32 v[16:17], v[120:121], v[14:15]
	v_pk_mul_f32 v[18:19], v[122:123], v[12:13]
	v_pk_mul_f32 v[8:9], v[122:123], v[8:9]
	v_pk_mul_f32 v[10:11], v[120:121], v[10:11]
	v_cvt_pk_bf16_f32 v8, v8, v9
	s_nop 0
	v_cvt_pk_bf16_f32 v8, v10, v11
	global_store_dwordx4 v65, v[12:15], s[12:13] nt
	v_cvt_pk_bf16_f32 v8, v18, v19
	s_nop 0
	v_cvt_pk_bf16_f32 v8, v16, v17
	ds_write_b128 v150, v[4:7]
	ds_write_b128 v150, v[0:3] offset:64
	ds_read_b128 v[0:3], v151
	ds_read_b128 v[4:7], v151 offset:1152
	s_waitcnt vmcnt(7) lgkmcnt(1)
	v_pk_fma_f32 v[2:3], v[108:109], v[2:3], v[42:43]
	v_pk_fma_f32 v[0:1], v[110:111], v[0:1], v[40:41]
	s_waitcnt vmcnt(6) lgkmcnt(0)
	v_pk_fma_f32 v[6:7], v[108:109], v[6:7], v[46:47]
	v_pk_fma_f32 v[4:5], v[110:111], v[4:5], v[44:45]
	global_store_dwordx4 v66, v[0:3], s[12:13] nt
	v_pk_mul_f32 v[8:9], v[108:109], v[6:7]
	v_pk_mul_f32 v[10:11], v[110:111], v[4:5]
	v_pk_mul_f32 v[0:1], v[110:111], v[0:1]
	v_pk_mul_f32 v[2:3], v[108:109], v[2:3]
	v_cvt_pk_bf16_f32 v0, v0, v1
	s_nop 0
	v_cvt_pk_bf16_f32 v0, v2, v3
	global_store_dwordx4 v67, v[4:7], s[12:13] nt
	v_cvt_pk_bf16_f32 v0, v10, v11
	s_nop 0
	v_cvt_pk_bf16_f32 v0, v8, v9
	s_cbranch_vccz .LBB0_2990
	s_andn2_b64 vcc, exec, s[4:5]
	s_cbranch_vccnz .LBB0_2989
	s_barrier
	s_branch .LBB0_2989
